# v34 minus the duplicate s_waitcnt lgkmcnt(0) in front of each GEMM MFMA segment (48 removed)
# speedup vs baseline: 1.0067x; 1.0067x over previous
.LBB0_38:
	ds_read_b128 v[150:153], v147
	ds_read_b128 v[156:159], v147 offset:1024
	ds_read_b128 v[160:163], v147 offset:2048
	ds_read_b128 v[164:167], v147 offset:3072
	s_add_u32 s83, s88, 0xfffc0080
	s_addc_u32 s90, s89, -1
	s_cmp_eq_u32 s82, 12
	s_cselect_b32 s93, s13, s90
	s_cselect_b32 s92, s78, s83
	s_cselect_b32 s91, s11, s81
	s_cselect_b32 s90, s79, s80
	v_lshl_add_u64 v[200:201], s[88:89], 0, v[136:137]
	s_add_i32 m0, s9, 0xc000
	ds_read_b128 v[168:171], v148
	ds_read_b128 v[172:175], v148 offset:1024
	ds_read_b128 v[176:179], v148 offset:2048
	ds_read_b128 v[180:183], v148 offset:3072
	ds_read_b128 v[184:187], v148 offset:4096
	ds_read_b128 v[188:191], v148 offset:5120
	ds_read_b128 v[192:195], v148 offset:6144
	ds_read_b128 v[196:199], v148 offset:7168
	global_load_lds_dwordx4 v[200:201], off
	s_add_i32 m0, s9, 0xe000
	v_lshl_add_u64 v[200:201], s[88:89], 0, v[138:139]
	global_load_lds_dwordx4 v[200:201], off
	s_waitcnt lgkmcnt(8)
	s_barrier
	s_waitcnt lgkmcnt(0)
	v_mfma_f32_16x16x32_bf16 v[124:127], v[150:153], v[168:171], v[124:127]
	v_mfma_f32_16x16x32_bf16 v[120:123], v[160:163], v[168:171], v[120:123]
	v_mfma_f32_16x16x32_bf16 v[116:119], v[150:153], v[176:179], v[116:119]
	v_mfma_f32_16x16x32_bf16 v[112:115], v[160:163], v[176:179], v[112:115]
	v_mfma_f32_16x16x32_bf16 v[100:103], v[150:153], v[184:187], v[100:103]
	v_mfma_f32_16x16x32_bf16 v[96:99], v[160:163], v[184:187], v[96:99]
	v_mfma_f32_16x16x32_bf16 v[84:87], v[150:153], v[192:195], v[84:87]
	v_mfma_f32_16x16x32_bf16 v[80:83], v[160:163], v[192:195], v[80:83]
	v_mfma_f32_16x16x32_bf16 v[124:127], v[156:159], v[172:175], v[124:127]
	v_mfma_f32_16x16x32_bf16 v[120:123], v[164:167], v[172:175], v[120:123]
	v_mfma_f32_16x16x32_bf16 v[116:119], v[156:159], v[180:183], v[116:119]
	v_mfma_f32_16x16x32_bf16 v[112:115], v[164:167], v[180:183], v[112:115]
	v_mfma_f32_16x16x32_bf16 v[100:103], v[156:159], v[188:191], v[100:103]
	v_mfma_f32_16x16x32_bf16 v[96:99], v[164:167], v[188:191], v[96:99]
	v_mfma_f32_16x16x32_bf16 v[84:87], v[156:159], v[196:199], v[84:87]
	v_mfma_f32_16x16x32_bf16 v[80:83], v[164:167], v[196:199], v[80:83]
	s_barrier
	s_add_i32 s83, s74, s1
	v_lshl_add_u64 v[216:217], s[90:91], 0, v[132:133]
	s_mov_b32 m0, s83
	ds_read_b128 v[200:203], v149
	ds_read_b128 v[204:207], v149 offset:1024
	ds_read_b128 v[208:211], v149 offset:2048
	ds_read_b128 v[212:215], v149 offset:3072
	global_load_lds_dwordx4 v[216:217], off
	s_add_i32 m0, s83, 0x2000
	v_lshl_add_u64 v[218:219], s[90:91], 0, v[128:129]
	global_load_lds_dwordx4 v[218:219], off
	s_barrier
	s_waitcnt lgkmcnt(0)
	v_mfma_f32_16x16x32_bf16 v[108:111], v[200:203], v[168:171], v[108:111]
	v_mfma_f32_16x16x32_bf16 v[104:107], v[208:211], v[168:171], v[104:107]
	v_mfma_f32_16x16x32_bf16 v[92:95], v[200:203], v[176:179], v[92:95]
	v_mfma_f32_16x16x32_bf16 v[88:91], v[208:211], v[176:179], v[88:91]
	v_mfma_f32_16x16x32_bf16 v[76:79], v[200:203], v[184:187], v[76:79]
	v_mfma_f32_16x16x32_bf16 v[72:75], v[208:211], v[184:187], v[72:75]
	v_mfma_f32_16x16x32_bf16 v[68:71], v[200:203], v[192:195], v[68:71]
	v_mfma_f32_16x16x32_bf16 v[64:67], v[208:211], v[192:195], v[64:67]
	v_mfma_f32_16x16x32_bf16 v[108:111], v[204:207], v[172:175], v[108:111]
	v_mfma_f32_16x16x32_bf16 v[104:107], v[212:215], v[172:175], v[104:107]
	v_mfma_f32_16x16x32_bf16 v[92:95], v[204:207], v[180:183], v[92:95]
	v_mfma_f32_16x16x32_bf16 v[88:91], v[212:215], v[180:183], v[88:91]
	v_mfma_f32_16x16x32_bf16 v[76:79], v[204:207], v[188:191], v[76:79]
	v_mfma_f32_16x16x32_bf16 v[72:75], v[212:215], v[188:191], v[72:75]
	v_mfma_f32_16x16x32_bf16 v[68:71], v[204:207], v[196:199], v[68:71]
	v_mfma_f32_16x16x32_bf16 v[64:67], v[212:215], v[196:199], v[64:67]
	s_mov_b32 m0, s9
	v_lshl_add_u64 v[220:221], s[92:93], 0, v[134:135]
	s_barrier
	ds_read_b128 v[168:171], v148 offset:16384
	ds_read_b128 v[172:175], v148 offset:17408
	ds_read_b128 v[176:179], v148 offset:18432
	ds_read_b128 v[180:183], v148 offset:19456
	ds_read_b128 v[184:187], v148 offset:20480
	ds_read_b128 v[188:191], v148 offset:21504
	ds_read_b128 v[192:195], v148 offset:22528
	ds_read_b128 v[196:199], v148 offset:23552
	global_load_lds_dwordx4 v[220:221], off
	s_mov_b32 m0, s35
	v_lshl_add_u64 v[222:223], s[92:93], 0, v[130:131]
	global_load_lds_dwordx4 v[222:223], off
	s_barrier
	s_waitcnt lgkmcnt(0)
	v_mfma_f32_16x16x32_bf16 v[60:63], v[150:153], v[168:171], v[60:63]
	v_mfma_f32_16x16x32_bf16 v[56:59], v[160:163], v[168:171], v[56:59]
	v_mfma_f32_16x16x32_bf16 v[52:55], v[150:153], v[176:179], v[52:55]
	v_mfma_f32_16x16x32_bf16 v[48:51], v[160:163], v[176:179], v[48:51]
	v_mfma_f32_16x16x32_bf16 v[36:39], v[150:153], v[184:187], v[36:39]
	v_mfma_f32_16x16x32_bf16 v[32:35], v[160:163], v[184:187], v[32:35]
	v_mfma_f32_16x16x32_bf16 v[20:23], v[150:153], v[192:195], v[20:23]
	v_mfma_f32_16x16x32_bf16 v[16:19], v[160:163], v[192:195], v[16:19]
	v_mfma_f32_16x16x32_bf16 v[60:63], v[156:159], v[172:175], v[60:63]
	v_mfma_f32_16x16x32_bf16 v[56:59], v[164:167], v[172:175], v[56:59]
	v_mfma_f32_16x16x32_bf16 v[52:55], v[156:159], v[180:183], v[52:55]
	v_mfma_f32_16x16x32_bf16 v[48:51], v[164:167], v[180:183], v[48:51]
	v_mfma_f32_16x16x32_bf16 v[36:39], v[156:159], v[188:191], v[36:39]
	v_mfma_f32_16x16x32_bf16 v[32:35], v[164:167], v[188:191], v[32:35]
	v_mfma_f32_16x16x32_bf16 v[20:23], v[156:159], v[196:199], v[20:23]
	v_mfma_f32_16x16x32_bf16 v[16:19], v[164:167], v[196:199], v[16:19]
	s_barrier
	s_add_u32 s94, s90, 0x40000
	s_addc_u32 s95, s91, 0
	s_add_i32 s83, s75, s1
	s_mov_b32 m0, s83
	v_lshl_add_u64 v[150:151], s[94:95], 0, v[132:133]
	global_load_lds_dwordx4 v[150:151], off
	s_add_i32 m0, s83, 0x2000
	v_lshl_add_u64 v[150:151], s[94:95], 0, v[128:129]
	global_load_lds_dwordx4 v[150:151], off
	s_waitcnt vmcnt(6)
	s_barrier
	v_mfma_f32_16x16x32_bf16 v[44:47], v[200:203], v[168:171], v[44:47]
	v_mfma_f32_16x16x32_bf16 v[40:43], v[208:211], v[168:171], v[40:43]
	v_mfma_f32_16x16x32_bf16 v[28:31], v[200:203], v[176:179], v[28:31]
	v_mfma_f32_16x16x32_bf16 v[24:27], v[208:211], v[176:179], v[24:27]
	v_mfma_f32_16x16x32_bf16 v[12:15], v[200:203], v[184:187], v[12:15]
	v_mfma_f32_16x16x32_bf16 v[8:11], v[208:211], v[184:187], v[8:11]
	v_mfma_f32_16x16x32_bf16 v[4:7], v[200:203], v[192:195], v[4:7]
	v_mfma_f32_16x16x32_bf16 v[0:3], v[208:211], v[192:195], v[0:3]
	v_mfma_f32_16x16x32_bf16 v[44:47], v[204:207], v[172:175], v[44:47]
	v_mfma_f32_16x16x32_bf16 v[40:43], v[212:215], v[172:175], v[40:43]
	v_mfma_f32_16x16x32_bf16 v[28:31], v[204:207], v[180:183], v[28:31]
	v_mfma_f32_16x16x32_bf16 v[24:27], v[212:215], v[180:183], v[24:27]
	v_mfma_f32_16x16x32_bf16 v[12:15], v[204:207], v[188:191], v[12:15]
	v_mfma_f32_16x16x32_bf16 v[8:11], v[212:215], v[188:191], v[8:11]
	v_mfma_f32_16x16x32_bf16 v[4:7], v[204:207], v[196:199], v[4:7]
	v_mfma_f32_16x16x32_bf16 v[0:3], v[212:215], v[196:199], v[0:3]
	s_add_i32 s83, 0, 0x18000
	v_add_u32_e32 v164, s83, v145
	s_barrier
	ds_read_b128 v[150:153], v164
	ds_read_b128 v[156:159], v164 offset:1024
	ds_read_b128 v[160:163], v164 offset:2048
	ds_read_b128 v[164:167], v164 offset:3072
	s_add_u32 s92, s92, 0x40000
	s_addc_u32 s93, s93, 0
	s_mov_b32 m0, s68
	v_lshl_add_u64 v[200:201], s[92:93], 0, v[134:135]
	ds_read_b128 v[168:171], v148 offset:32768
	ds_read_b128 v[172:175], v148 offset:33792
	ds_read_b128 v[176:179], v148 offset:34816
	ds_read_b128 v[180:183], v148 offset:35840
	ds_read_b128 v[184:187], v148 offset:36864
	ds_read_b128 v[188:191], v148 offset:37888
	ds_read_b128 v[192:195], v148 offset:38912
	ds_read_b128 v[196:199], v148 offset:39936
	global_load_lds_dwordx4 v[200:201], off
	s_mov_b32 m0, s69
	v_lshl_add_u64 v[200:201], s[92:93], 0, v[130:131]
	global_load_lds_dwordx4 v[200:201], off
	s_waitcnt lgkmcnt(8)
	s_barrier
	s_waitcnt lgkmcnt(0)
	v_mfma_f32_16x16x32_bf16 v[124:127], v[150:153], v[168:171], v[124:127]
	v_mfma_f32_16x16x32_bf16 v[120:123], v[160:163], v[168:171], v[120:123]
	v_mfma_f32_16x16x32_bf16 v[116:119], v[150:153], v[176:179], v[116:119]
	v_mfma_f32_16x16x32_bf16 v[112:115], v[160:163], v[176:179], v[112:115]
	v_mfma_f32_16x16x32_bf16 v[100:103], v[150:153], v[184:187], v[100:103]
	v_mfma_f32_16x16x32_bf16 v[96:99], v[160:163], v[184:187], v[96:99]
	v_mfma_f32_16x16x32_bf16 v[84:87], v[150:153], v[192:195], v[84:87]
	v_mfma_f32_16x16x32_bf16 v[80:83], v[160:163], v[192:195], v[80:83]
	v_mfma_f32_16x16x32_bf16 v[124:127], v[156:159], v[172:175], v[124:127]
	v_mfma_f32_16x16x32_bf16 v[120:123], v[164:167], v[172:175], v[120:123]
	v_mfma_f32_16x16x32_bf16 v[116:119], v[156:159], v[180:183], v[116:119]
	v_mfma_f32_16x16x32_bf16 v[112:115], v[164:167], v[180:183], v[112:115]
	v_mfma_f32_16x16x32_bf16 v[100:103], v[156:159], v[188:191], v[100:103]
	v_mfma_f32_16x16x32_bf16 v[96:99], v[164:167], v[188:191], v[96:99]
	v_mfma_f32_16x16x32_bf16 v[84:87], v[156:159], v[196:199], v[84:87]
	v_mfma_f32_16x16x32_bf16 v[80:83], v[164:167], v[196:199], v[80:83]
	s_barrier
	s_add_i32 s92, 0, 0x1c000
	s_add_i32 s83, s83, s1
	v_add_u32_e32 v212, s92, v145
	v_lshl_add_u64 v[216:217], v[216:217], 0, s[6:7]
	s_mov_b32 m0, s83
	ds_read_b128 v[200:203], v212
	ds_read_b128 v[204:207], v212 offset:1024
	ds_read_b128 v[208:211], v212 offset:2048
	ds_read_b128 v[212:215], v212 offset:3072
	global_load_lds_dwordx4 v[216:217], off
	s_add_i32 m0, s83, 0x2000
	v_lshl_add_u64 v[216:217], v[218:219], 0, s[6:7]
	global_load_lds_dwordx4 v[216:217], off
	s_barrier
	s_waitcnt lgkmcnt(0)
	v_mfma_f32_16x16x32_bf16 v[108:111], v[200:203], v[168:171], v[108:111]
	v_mfma_f32_16x16x32_bf16 v[104:107], v[208:211], v[168:171], v[104:107]
	v_mfma_f32_16x16x32_bf16 v[92:95], v[200:203], v[176:179], v[92:95]
	v_mfma_f32_16x16x32_bf16 v[88:91], v[208:211], v[176:179], v[88:91]
	v_mfma_f32_16x16x32_bf16 v[76:79], v[200:203], v[184:187], v[76:79]
	v_mfma_f32_16x16x32_bf16 v[72:75], v[208:211], v[184:187], v[72:75]
	v_mfma_f32_16x16x32_bf16 v[68:71], v[200:203], v[192:195], v[68:71]
	v_mfma_f32_16x16x32_bf16 v[64:67], v[208:211], v[192:195], v[64:67]
	v_mfma_f32_16x16x32_bf16 v[108:111], v[204:207], v[172:175], v[108:111]
	v_mfma_f32_16x16x32_bf16 v[104:107], v[212:215], v[172:175], v[104:107]
	v_mfma_f32_16x16x32_bf16 v[92:95], v[204:207], v[180:183], v[92:95]
	v_mfma_f32_16x16x32_bf16 v[88:91], v[212:215], v[180:183], v[88:91]
	v_mfma_f32_16x16x32_bf16 v[76:79], v[204:207], v[188:191], v[76:79]
	v_mfma_f32_16x16x32_bf16 v[72:75], v[212:215], v[188:191], v[72:75]
	v_mfma_f32_16x16x32_bf16 v[68:71], v[204:207], v[196:199], v[68:71]
	v_mfma_f32_16x16x32_bf16 v[64:67], v[212:215], v[196:199], v[64:67]
	s_mov_b32 m0, s71
	v_lshl_add_u64 v[216:217], v[220:221], 0, s[6:7]
	s_barrier
	ds_read_b128 v[168:171], v148 offset:49152
	ds_read_b128 v[172:175], v148 offset:50176
	ds_read_b128 v[176:179], v148 offset:51200
	ds_read_b128 v[180:183], v148 offset:52224
	ds_read_b128 v[184:187], v148 offset:53248
	ds_read_b128 v[188:191], v148 offset:54272
	ds_read_b128 v[192:195], v148 offset:55296
	ds_read_b128 v[196:199], v148 offset:56320
	global_load_lds_dwordx4 v[216:217], off
	s_mov_b32 m0, s72
	v_lshl_add_u64 v[216:217], v[222:223], 0, s[6:7]
	global_load_lds_dwordx4 v[216:217], off
	s_barrier
	s_waitcnt lgkmcnt(0)
	v_mfma_f32_16x16x32_bf16 v[60:63], v[150:153], v[168:171], v[60:63]
	v_mfma_f32_16x16x32_bf16 v[56:59], v[160:163], v[168:171], v[56:59]
	v_mfma_f32_16x16x32_bf16 v[52:55], v[150:153], v[176:179], v[52:55]
	v_mfma_f32_16x16x32_bf16 v[48:51], v[160:163], v[176:179], v[48:51]
	v_mfma_f32_16x16x32_bf16 v[36:39], v[150:153], v[184:187], v[36:39]
	v_mfma_f32_16x16x32_bf16 v[32:35], v[160:163], v[184:187], v[32:35]
	v_mfma_f32_16x16x32_bf16 v[20:23], v[150:153], v[192:195], v[20:23]
	v_mfma_f32_16x16x32_bf16 v[16:19], v[160:163], v[192:195], v[16:19]
	v_mfma_f32_16x16x32_bf16 v[60:63], v[156:159], v[172:175], v[60:63]
	v_mfma_f32_16x16x32_bf16 v[56:59], v[164:167], v[172:175], v[56:59]
	v_mfma_f32_16x16x32_bf16 v[52:55], v[156:159], v[180:183], v[52:55]
	v_mfma_f32_16x16x32_bf16 v[48:51], v[164:167], v[180:183], v[48:51]
	v_mfma_f32_16x16x32_bf16 v[36:39], v[156:159], v[188:191], v[36:39]
	v_mfma_f32_16x16x32_bf16 v[32:35], v[164:167], v[188:191], v[32:35]
	v_mfma_f32_16x16x32_bf16 v[20:23], v[156:159], v[196:199], v[20:23]
	v_mfma_f32_16x16x32_bf16 v[16:19], v[164:167], v[196:199], v[16:19]
	s_barrier
	s_add_u32 s90, s90, 0x40080
	s_addc_u32 s91, s91, 0
	s_add_i32 s83, s92, s1
	s_mov_b32 m0, s83
	v_lshl_add_u64 v[150:151], s[90:91], 0, v[132:133]
	global_load_lds_dwordx4 v[150:151], off
	s_add_i32 m0, s83, 0x2000
	v_lshl_add_u64 v[150:151], s[90:91], 0, v[128:129]
	global_load_lds_dwordx4 v[150:151], off
	s_waitcnt vmcnt(6)
	s_barrier
	v_mfma_f32_16x16x32_bf16 v[44:47], v[200:203], v[168:171], v[44:47]
	v_mfma_f32_16x16x32_bf16 v[40:43], v[208:211], v[168:171], v[40:43]
	v_mfma_f32_16x16x32_bf16 v[28:31], v[200:203], v[176:179], v[28:31]
	v_mfma_f32_16x16x32_bf16 v[24:27], v[208:211], v[176:179], v[24:27]
	v_mfma_f32_16x16x32_bf16 v[12:15], v[200:203], v[184:187], v[12:15]
	v_mfma_f32_16x16x32_bf16 v[8:11], v[208:211], v[184:187], v[8:11]
	v_mfma_f32_16x16x32_bf16 v[4:7], v[200:203], v[192:195], v[4:7]
	v_mfma_f32_16x16x32_bf16 v[0:3], v[208:211], v[192:195], v[0:3]
	v_mfma_f32_16x16x32_bf16 v[44:47], v[204:207], v[172:175], v[44:47]
	v_mfma_f32_16x16x32_bf16 v[40:43], v[212:215], v[172:175], v[40:43]
	v_mfma_f32_16x16x32_bf16 v[28:31], v[204:207], v[180:183], v[28:31]
	v_mfma_f32_16x16x32_bf16 v[24:27], v[212:215], v[180:183], v[24:27]
	v_mfma_f32_16x16x32_bf16 v[12:15], v[204:207], v[188:191], v[12:15]
	v_mfma_f32_16x16x32_bf16 v[8:11], v[212:215], v[188:191], v[8:11]
	v_mfma_f32_16x16x32_bf16 v[4:7], v[204:207], v[196:199], v[4:7]
	v_mfma_f32_16x16x32_bf16 v[0:3], v[212:215], v[196:199], v[0:3]
	s_add_i32 s82, s82, 2
	s_add_u32 s88, s88, 0x100
	s_addc_u32 s89, s89, 0
	s_add_u32 s80, s80, 0x100
	s_addc_u32 s81, s81, 0
	s_cmp_gt_u32 s82, 13
	s_barrier
	s_cbranch_scc0 .LBB0_38
	v_lshl_add_u32 v152, s8, 8, v144
	v_lshl_or_b32 v150, s77, 8, v146
	v_cvt_pk_bf16_f32 v124, v124, v125
	v_cvt_pk_bf16_f32 v125, v126, v127
	v_cvt_pk_bf16_f32 v126, v120, v121
	v_mov_b64_e32 v[120:121], s[42:43]
	v_ashrrev_i32_e32 v151, 31, v150
	v_cvt_pk_bf16_f32 v68, v68, v69
	v_cvt_pk_bf16_f32 v69, v70, v71
	v_cvt_pk_bf16_f32 v70, v64, v65
	v_add_u32_e32 v64, 0x80, v152
	v_cvt_pk_bf16_f32 v127, v122, v123
	v_mad_i64_i32 v[122:123], s[78:79], v152, s76, v[120:121]
	v_lshlrev_b64 v[150:151], 1, v[150:151]
	v_cvt_pk_bf16_f32 v60, v60, v61
	v_cvt_pk_bf16_f32 v61, v62, v63
	v_cvt_pk_bf16_f32 v62, v56, v57
	v_mad_i64_i32 v[56:57], s[78:79], v64, s76, v[120:121]
	v_lshl_add_u64 v[122:123], v[122:123], 0, v[150:151]
	v_cvt_pk_bf16_f32 v108, v108, v109
	v_cvt_pk_bf16_f32 v109, v110, v111
	v_cvt_pk_bf16_f32 v110, v104, v105
	v_cvt_pk_bf16_f32 v111, v106, v107
	v_lshl_add_u64 v[56:57], v[56:57], 0, v[150:151]
	v_cvt_pk_bf16_f32 v44, v44, v45
	v_cvt_pk_bf16_f32 v45, v46, v47
	v_cvt_pk_bf16_f32 v46, v40, v41
	v_cvt_pk_bf16_f32 v47, v42, v43
	global_store_dwordx4 v[122:123], v[108:111], off offset:256
	global_store_dwordx4 v[56:57], v[44:47], off offset:256
	v_cvt_pk_bf16_f32 v92, v92, v93
	v_or_b32_e32 v108, 16, v152
	v_add_u32_e32 v44, 0x90, v152
	v_mad_i64_i32 v[108:109], s[78:79], v108, s76, v[120:121]
	v_mad_i64_i32 v[44:45], s[78:79], v44, s76, v[120:121]
	v_lshl_add_u64 v[108:109], v[108:109], 0, v[150:151]
	v_cvt_pk_bf16_f32 v93, v94, v95
	v_cvt_pk_bf16_f32 v94, v88, v89
	v_cvt_pk_bf16_f32 v95, v90, v91
	v_lshl_add_u64 v[44:45], v[44:45], 0, v[150:151]
	v_cvt_pk_bf16_f32 v28, v28, v29
	v_cvt_pk_bf16_f32 v29, v30, v31
	v_cvt_pk_bf16_f32 v30, v24, v25
	v_cvt_pk_bf16_f32 v31, v26, v27
	global_store_dwordx4 v[108:109], v[92:95], off offset:256
	global_store_dwordx4 v[44:45], v[28:31], off offset:256
	v_cvt_pk_bf16_f32 v76, v76, v77
	v_or_b32_e32 v92, 32, v152
	v_add_u32_e32 v28, 0xa0, v152
	v_mad_i64_i32 v[92:93], s[78:79], v92, s76, v[120:121]
	v_mad_i64_i32 v[28:29], s[78:79], v28, s76, v[120:121]
	v_lshl_add_u64 v[92:93], v[92:93], 0, v[150:151]
	v_cvt_pk_bf16_f32 v77, v78, v79
	v_cvt_pk_bf16_f32 v78, v72, v73
	v_cvt_pk_bf16_f32 v79, v74, v75
	v_lshl_add_u64 v[28:29], v[28:29], 0, v[150:151]
	v_cvt_pk_bf16_f32 v12, v12, v13
	v_cvt_pk_bf16_f32 v13, v14, v15
	v_cvt_pk_bf16_f32 v14, v8, v9
	v_cvt_pk_bf16_f32 v15, v10, v11
	global_store_dwordx4 v[92:93], v[76:79], off offset:256
	global_store_dwordx4 v[28:29], v[12:15], off offset:256
	v_cvt_pk_bf16_f32 v104, v116, v117
	v_or_b32_e32 v76, 48, v152
	v_add_u32_e32 v12, 0xb0, v152
	v_mad_i64_i32 v[76:77], s[78:79], v76, s76, v[120:121]
	v_mad_i64_i32 v[12:13], s[78:79], v12, s76, v[120:121]
	v_cvt_pk_bf16_f32 v105, v118, v119
	v_cvt_pk_bf16_f32 v106, v112, v113
	v_cvt_pk_bf16_f32 v107, v114, v115
	v_cvt_pk_bf16_f32 v88, v100, v101
	v_cvt_pk_bf16_f32 v89, v102, v103
	v_cvt_pk_bf16_f32 v90, v96, v97
	v_cvt_pk_bf16_f32 v91, v98, v99
	v_cvt_pk_bf16_f32 v72, v84, v85
	v_cvt_pk_bf16_f32 v73, v86, v87
	v_cvt_pk_bf16_f32 v74, v80, v81
	v_cvt_pk_bf16_f32 v75, v82, v83
	v_lshl_add_u64 v[76:77], v[76:77], 0, v[150:151]
	v_cvt_pk_bf16_f32 v71, v66, v67
	v_cvt_pk_bf16_f32 v63, v58, v59
	v_cvt_pk_bf16_f32 v40, v52, v53
	v_cvt_pk_bf16_f32 v41, v54, v55
	v_cvt_pk_bf16_f32 v42, v48, v49
	v_cvt_pk_bf16_f32 v43, v50, v51
	v_cvt_pk_bf16_f32 v24, v36, v37
	v_cvt_pk_bf16_f32 v25, v38, v39
	v_cvt_pk_bf16_f32 v26, v32, v33
	v_cvt_pk_bf16_f32 v27, v34, v35
	v_cvt_pk_bf16_f32 v8, v20, v21
	v_cvt_pk_bf16_f32 v9, v22, v23
	v_cvt_pk_bf16_f32 v10, v16, v17
	v_cvt_pk_bf16_f32 v11, v18, v19
	v_lshl_add_u64 v[12:13], v[12:13], 0, v[150:151]
	v_cvt_pk_bf16_f32 v4, v4, v5
	v_cvt_pk_bf16_f32 v5, v6, v7
	v_cvt_pk_bf16_f32 v6, v0, v1
	v_cvt_pk_bf16_f32 v7, v2, v3
	s_and_b64 vcc, exec, s[4:5]
	s_mov_b32 s77, s10
	s_mov_b32 s8, s12
	s_mov_b64 s[90:91], s[86:87]
	s_mov_b64 s[88:89], s[14:15]
	global_store_dwordx4 v[122:123], v[124:127], off
	global_store_dwordx4 v[108:109], v[104:107], off
	global_store_dwordx4 v[92:93], v[88:91], off
	global_store_dwordx4 v[76:77], v[72:75], off
	global_store_dwordx4 v[76:77], v[68:71], off offset:256
	global_store_dwordx4 v[56:57], v[60:63], off
	global_store_dwordx4 v[44:45], v[40:43], off
	global_store_dwordx4 v[28:29], v[24:27], off
	global_store_dwordx4 v[12:13], v[8:11], off
	global_store_dwordx4 v[12:13], v[4:7], off offset:256
	s_cbranch_vccz .LBB0_35
	s_waitcnt vmcnt(0)
	s_cmpk_gt_u32 s0, 0xff
	v_readlane_b32 s33, v228, 32
	v_readlane_b32 s56, v228, 35
	s_cbranch_scc1 .LBB0_42
	s_barrier

.LBB0_547:
	s_add_u32 s68, s54, s60
	s_addc_u32 s69, s55, s61
	s_add_u32 s64, s68, 0x100
	s_addc_u32 s65, s69, 0
	s_and_b64 s[62:63], s[58:59], exec
	s_cselect_b32 s65, s41, s65
	s_cselect_b32 s64, s82, s64
	s_add_u32 s60, s52, s60
	s_addc_u32 s61, s53, s61
	s_add_u32 s60, s60, 0x100
	s_addc_u32 s61, s61, 0
	s_and_b64 s[58:59], s[58:59], exec
	s_cselect_b32 s67, s25, s61
	s_cselect_b32 s66, s83, s60
	s_add_u32 s68, s68, 0x10080
	s_addc_u32 s69, s69, 0
	s_add_i32 s94, s79, s1
	s_add_i32 m0, s51, 0xc000
	s_add_i32 s95, s51, 0xe000
	s_add_i32 s93, s94, 0x2000
	s_add_u32 s62, s66, 0x10000
	s_addc_u32 s63, s67, 0
	s_add_i32 s92, s72, s1
	ds_read_b128 v[140:143], v149
	ds_read_b128 v[156:159], v149 offset:1024
	ds_read_b128 v[160:163], v149 offset:2048
	ds_read_b128 v[164:167], v149 offset:3072
	s_add_i32 s91, s92, 0x2000
	s_add_i32 s90, 0, 0x18000
	s_add_u32 s60, s64, 0x10000
	s_addc_u32 s61, s65, 0
	s_add_i32 s89, s90, s1
	s_add_i32 s88, s89, 0x2000
	s_add_u32 s58, s66, 0x10080
	s_addc_u32 s59, s67, 0
	s_add_i32 s87, s97, s1
	s_add_i32 s86, s87, 0x2000
	v_lshl_add_u64 v[144:145], s[68:69], 0, v[134:135]
	ds_read_b128 v[168:171], v150
	ds_read_b128 v[172:175], v150 offset:1024
	ds_read_b128 v[176:179], v150 offset:2048
	ds_read_b128 v[180:183], v150 offset:3072
	ds_read_b128 v[184:187], v150 offset:4096
	ds_read_b128 v[188:191], v150 offset:5120
	ds_read_b128 v[192:195], v150 offset:6144
	ds_read_b128 v[196:199], v150 offset:7168
	global_load_lds_dwordx4 v[144:145], off
	s_mov_b32 m0, s95
	v_lshl_add_u64 v[144:145], s[68:69], 0, v[130:131]
	global_load_lds_dwordx4 v[144:145], off
	s_waitcnt lgkmcnt(8)
	s_barrier
	s_waitcnt lgkmcnt(0)
	v_mfma_f32_16x16x32_bf16 v[124:127], v[140:143], v[168:171], v[124:127]
	v_mfma_f32_16x16x32_bf16 v[120:123], v[160:163], v[168:171], v[120:123]
	v_mfma_f32_16x16x32_bf16 v[112:115], v[140:143], v[176:179], v[112:115]
	v_mfma_f32_16x16x32_bf16 v[104:107], v[160:163], v[176:179], v[104:107]
	v_mfma_f32_16x16x32_bf16 v[92:95], v[140:143], v[184:187], v[92:95]
	v_mfma_f32_16x16x32_bf16 v[88:91], v[160:163], v[184:187], v[88:91]
	v_mfma_f32_16x16x32_bf16 v[80:83], v[140:143], v[192:195], v[80:83]
	v_mfma_f32_16x16x32_bf16 v[72:75], v[160:163], v[192:195], v[72:75]
	v_mfma_f32_16x16x32_bf16 v[124:127], v[156:159], v[172:175], v[124:127]
	v_mfma_f32_16x16x32_bf16 v[120:123], v[164:167], v[172:175], v[120:123]
	v_mfma_f32_16x16x32_bf16 v[112:115], v[156:159], v[180:183], v[112:115]
	v_mfma_f32_16x16x32_bf16 v[104:107], v[164:167], v[180:183], v[104:107]
	v_mfma_f32_16x16x32_bf16 v[92:95], v[156:159], v[188:191], v[92:95]
	v_mfma_f32_16x16x32_bf16 v[88:91], v[164:167], v[188:191], v[88:91]
	v_mfma_f32_16x16x32_bf16 v[80:83], v[156:159], v[196:199], v[80:83]
	v_mfma_f32_16x16x32_bf16 v[72:75], v[164:167], v[196:199], v[72:75]
	s_barrier
	s_mov_b32 m0, s94
	v_lshl_add_u64 v[144:145], s[66:67], 0, v[132:133]
	ds_read_b128 v[200:203], v151
	ds_read_b128 v[204:207], v151 offset:1024
	ds_read_b128 v[208:211], v151 offset:2048
	ds_read_b128 v[212:215], v151 offset:3072
	global_load_lds_dwordx4 v[144:145], off
	s_mov_b32 m0, s93
	v_lshl_add_u64 v[152:153], s[66:67], 0, v[128:129]
	global_load_lds_dwordx4 v[152:153], off
	s_barrier
	s_waitcnt lgkmcnt(0)
	v_mfma_f32_16x16x32_bf16 v[116:119], v[200:203], v[168:171], v[116:119]
	v_mfma_f32_16x16x32_bf16 v[108:111], v[208:211], v[168:171], v[108:111]
	v_mfma_f32_16x16x32_bf16 v[100:103], v[200:203], v[176:179], v[100:103]
	v_mfma_f32_16x16x32_bf16 v[96:99], v[208:211], v[176:179], v[96:99]
	v_mfma_f32_16x16x32_bf16 v[84:87], v[200:203], v[184:187], v[84:87]
	v_mfma_f32_16x16x32_bf16 v[76:79], v[208:211], v[184:187], v[76:79]
	v_mfma_f32_16x16x32_bf16 v[68:71], v[200:203], v[192:195], v[68:71]
	v_mfma_f32_16x16x32_bf16 v[64:67], v[208:211], v[192:195], v[64:67]
	v_mfma_f32_16x16x32_bf16 v[116:119], v[204:207], v[172:175], v[116:119]
	v_mfma_f32_16x16x32_bf16 v[108:111], v[212:215], v[172:175], v[108:111]
	v_mfma_f32_16x16x32_bf16 v[100:103], v[204:207], v[180:183], v[100:103]
	v_mfma_f32_16x16x32_bf16 v[96:99], v[212:215], v[180:183], v[96:99]
	v_mfma_f32_16x16x32_bf16 v[84:87], v[204:207], v[188:191], v[84:87]
	v_mfma_f32_16x16x32_bf16 v[76:79], v[212:215], v[188:191], v[76:79]
	v_mfma_f32_16x16x32_bf16 v[68:71], v[204:207], v[196:199], v[68:71]
	v_mfma_f32_16x16x32_bf16 v[64:67], v[212:215], v[196:199], v[64:67]
	s_mov_b32 m0, s51
	v_lshl_add_u64 v[216:217], s[64:65], 0, v[134:135]
	s_barrier
	ds_read_b128 v[168:171], v150 offset:16384
	ds_read_b128 v[172:175], v150 offset:17408
	ds_read_b128 v[176:179], v150 offset:18432
	ds_read_b128 v[180:183], v150 offset:19456
	ds_read_b128 v[184:187], v150 offset:20480
	ds_read_b128 v[188:191], v150 offset:21504
	ds_read_b128 v[192:195], v150 offset:22528
	ds_read_b128 v[196:199], v150 offset:23552
	global_load_lds_dwordx4 v[216:217], off
	s_mov_b32 m0, s71
	v_lshl_add_u64 v[218:219], s[64:65], 0, v[130:131]
	global_load_lds_dwordx4 v[218:219], off
	s_barrier
	s_waitcnt lgkmcnt(0)
	v_mfma_f32_16x16x32_bf16 v[60:63], v[140:143], v[168:171], v[60:63]
	v_mfma_f32_16x16x32_bf16 v[56:59], v[160:163], v[168:171], v[56:59]
	v_mfma_f32_16x16x32_bf16 v[52:55], v[140:143], v[176:179], v[52:55]
	v_mfma_f32_16x16x32_bf16 v[48:51], v[160:163], v[176:179], v[48:51]
	v_mfma_f32_16x16x32_bf16 v[28:31], v[140:143], v[184:187], v[28:31]
	v_mfma_f32_16x16x32_bf16 v[20:23], v[160:163], v[184:187], v[20:23]
	v_mfma_f32_16x16x32_bf16 v[24:27], v[140:143], v[192:195], v[24:27]
	v_mfma_f32_16x16x32_bf16 v[16:19], v[160:163], v[192:195], v[16:19]
	v_mfma_f32_16x16x32_bf16 v[60:63], v[156:159], v[172:175], v[60:63]
	v_mfma_f32_16x16x32_bf16 v[56:59], v[164:167], v[172:175], v[56:59]
	v_mfma_f32_16x16x32_bf16 v[52:55], v[156:159], v[180:183], v[52:55]
	v_mfma_f32_16x16x32_bf16 v[48:51], v[164:167], v[180:183], v[48:51]
	v_mfma_f32_16x16x32_bf16 v[28:31], v[156:159], v[188:191], v[28:31]
	v_mfma_f32_16x16x32_bf16 v[20:23], v[164:167], v[188:191], v[20:23]
	v_mfma_f32_16x16x32_bf16 v[24:27], v[156:159], v[196:199], v[24:27]
	v_mfma_f32_16x16x32_bf16 v[16:19], v[164:167], v[196:199], v[16:19]
	s_barrier
	s_mov_b32 m0, s92
	v_lshl_add_u64 v[140:141], s[62:63], 0, v[132:133]
	global_load_lds_dwordx4 v[140:141], off
	s_mov_b32 m0, s91
	v_lshl_add_u64 v[140:141], s[62:63], 0, v[128:129]
	global_load_lds_dwordx4 v[140:141], off
	s_waitcnt vmcnt(6)
	s_barrier
	v_mfma_f32_16x16x32_bf16 v[44:47], v[200:203], v[168:171], v[44:47]
	v_mfma_f32_16x16x32_bf16 v[40:43], v[208:211], v[168:171], v[40:43]
	v_mfma_f32_16x16x32_bf16 v[36:39], v[200:203], v[176:179], v[36:39]
	v_mfma_f32_16x16x32_bf16 v[32:35], v[208:211], v[176:179], v[32:35]
	v_mfma_f32_16x16x32_bf16 v[12:15], v[200:203], v[184:187], v[12:15]
	v_mfma_f32_16x16x32_bf16 v[4:7], v[208:211], v[184:187], v[4:7]
	v_mfma_f32_16x16x32_bf16 v[8:11], v[200:203], v[192:195], v[8:11]
	v_mfma_f32_16x16x32_bf16 v[0:3], v[208:211], v[192:195], v[0:3]
	v_mfma_f32_16x16x32_bf16 v[44:47], v[204:207], v[172:175], v[44:47]
	v_mfma_f32_16x16x32_bf16 v[40:43], v[212:215], v[172:175], v[40:43]
	v_mfma_f32_16x16x32_bf16 v[36:39], v[204:207], v[180:183], v[36:39]
	v_mfma_f32_16x16x32_bf16 v[32:35], v[212:215], v[180:183], v[32:35]
	v_mfma_f32_16x16x32_bf16 v[12:15], v[204:207], v[188:191], v[12:15]
	v_mfma_f32_16x16x32_bf16 v[4:7], v[212:215], v[188:191], v[4:7]
	v_mfma_f32_16x16x32_bf16 v[8:11], v[204:207], v[196:199], v[8:11]
	v_mfma_f32_16x16x32_bf16 v[0:3], v[212:215], v[196:199], v[0:3]
	v_add_u32_e32 v164, s90, v147
	s_barrier
	ds_read_b128 v[140:143], v164
	ds_read_b128 v[156:159], v164 offset:1024
	ds_read_b128 v[160:163], v164 offset:2048
	ds_read_b128 v[164:167], v164 offset:3072
	s_mov_b32 m0, s73
	v_lshl_add_u64 v[200:201], s[60:61], 0, v[134:135]
	ds_read_b128 v[168:171], v150 offset:32768
	ds_read_b128 v[172:175], v150 offset:33792
	ds_read_b128 v[176:179], v150 offset:34816
	ds_read_b128 v[180:183], v150 offset:35840
	ds_read_b128 v[184:187], v150 offset:36864
	ds_read_b128 v[188:191], v150 offset:37888
	ds_read_b128 v[192:195], v150 offset:38912
	ds_read_b128 v[196:199], v150 offset:39936
	global_load_lds_dwordx4 v[200:201], off
	s_mov_b32 m0, s74
	v_lshl_add_u64 v[200:201], s[60:61], 0, v[130:131]
	global_load_lds_dwordx4 v[200:201], off
	s_waitcnt lgkmcnt(8)
	s_barrier
	s_waitcnt lgkmcnt(0)
	v_mfma_f32_16x16x32_bf16 v[124:127], v[140:143], v[168:171], v[124:127]
	v_mfma_f32_16x16x32_bf16 v[120:123], v[160:163], v[168:171], v[120:123]
	v_mfma_f32_16x16x32_bf16 v[112:115], v[140:143], v[176:179], v[112:115]
	v_mfma_f32_16x16x32_bf16 v[104:107], v[160:163], v[176:179], v[104:107]
	v_mfma_f32_16x16x32_bf16 v[92:95], v[140:143], v[184:187], v[92:95]
	v_mfma_f32_16x16x32_bf16 v[88:91], v[160:163], v[184:187], v[88:91]
	v_mfma_f32_16x16x32_bf16 v[80:83], v[140:143], v[192:195], v[80:83]
	v_mfma_f32_16x16x32_bf16 v[72:75], v[160:163], v[192:195], v[72:75]
	v_mfma_f32_16x16x32_bf16 v[124:127], v[156:159], v[172:175], v[124:127]
	v_mfma_f32_16x16x32_bf16 v[120:123], v[164:167], v[172:175], v[120:123]
	v_mfma_f32_16x16x32_bf16 v[112:115], v[156:159], v[180:183], v[112:115]
	v_mfma_f32_16x16x32_bf16 v[104:107], v[164:167], v[180:183], v[104:107]
	v_mfma_f32_16x16x32_bf16 v[92:95], v[156:159], v[188:191], v[92:95]
	v_mfma_f32_16x16x32_bf16 v[88:91], v[164:167], v[188:191], v[88:91]
	v_mfma_f32_16x16x32_bf16 v[80:83], v[156:159], v[196:199], v[80:83]
	v_mfma_f32_16x16x32_bf16 v[72:75], v[164:167], v[196:199], v[72:75]
	s_barrier
	s_mov_b32 m0, s89
	v_add_u32_e32 v212, s97, v147
	v_lshl_add_u64 v[144:145], v[144:145], 0, s[6:7]
	ds_read_b128 v[200:203], v212
	ds_read_b128 v[204:207], v212 offset:1024
	ds_read_b128 v[208:211], v212 offset:2048
	ds_read_b128 v[212:215], v212 offset:3072
	global_load_lds_dwordx4 v[144:145], off
	s_mov_b32 m0, s88
	v_lshl_add_u64 v[144:145], v[152:153], 0, s[6:7]
	global_load_lds_dwordx4 v[144:145], off
	s_barrier
	s_waitcnt lgkmcnt(0)
	v_mfma_f32_16x16x32_bf16 v[116:119], v[200:203], v[168:171], v[116:119]
	v_mfma_f32_16x16x32_bf16 v[108:111], v[208:211], v[168:171], v[108:111]
	v_mfma_f32_16x16x32_bf16 v[100:103], v[200:203], v[176:179], v[100:103]
	v_mfma_f32_16x16x32_bf16 v[96:99], v[208:211], v[176:179], v[96:99]
	v_mfma_f32_16x16x32_bf16 v[84:87], v[200:203], v[184:187], v[84:87]
	v_mfma_f32_16x16x32_bf16 v[76:79], v[208:211], v[184:187], v[76:79]
	v_mfma_f32_16x16x32_bf16 v[68:71], v[200:203], v[192:195], v[68:71]
	v_mfma_f32_16x16x32_bf16 v[64:67], v[208:211], v[192:195], v[64:67]
	v_mfma_f32_16x16x32_bf16 v[116:119], v[204:207], v[172:175], v[116:119]
	v_mfma_f32_16x16x32_bf16 v[108:111], v[212:215], v[172:175], v[108:111]
	v_mfma_f32_16x16x32_bf16 v[100:103], v[204:207], v[180:183], v[100:103]
	v_mfma_f32_16x16x32_bf16 v[96:99], v[212:215], v[180:183], v[96:99]
	v_mfma_f32_16x16x32_bf16 v[84:87], v[204:207], v[188:191], v[84:87]
	v_mfma_f32_16x16x32_bf16 v[76:79], v[212:215], v[188:191], v[76:79]
	v_mfma_f32_16x16x32_bf16 v[68:71], v[204:207], v[196:199], v[68:71]
	v_mfma_f32_16x16x32_bf16 v[64:67], v[212:215], v[196:199], v[64:67]
	s_mov_b32 m0, s76
	v_lshl_add_u64 v[144:145], v[216:217], 0, s[6:7]
	s_barrier
	ds_read_b128 v[168:171], v150 offset:49152
	ds_read_b128 v[172:175], v150 offset:50176
	ds_read_b128 v[176:179], v150 offset:51200
	ds_read_b128 v[180:183], v150 offset:52224
	ds_read_b128 v[184:187], v150 offset:53248
	ds_read_b128 v[188:191], v150 offset:54272
	ds_read_b128 v[192:195], v150 offset:55296
	ds_read_b128 v[196:199], v150 offset:56320
	global_load_lds_dwordx4 v[144:145], off
	s_mov_b32 m0, s77
	v_lshl_add_u64 v[144:145], v[218:219], 0, s[6:7]
	global_load_lds_dwordx4 v[144:145], off
	s_barrier
	s_waitcnt lgkmcnt(0)
	v_mfma_f32_16x16x32_bf16 v[60:63], v[140:143], v[168:171], v[60:63]
	v_mfma_f32_16x16x32_bf16 v[56:59], v[160:163], v[168:171], v[56:59]
	v_mfma_f32_16x16x32_bf16 v[52:55], v[140:143], v[176:179], v[52:55]
	v_mfma_f32_16x16x32_bf16 v[48:51], v[160:163], v[176:179], v[48:51]
	v_mfma_f32_16x16x32_bf16 v[28:31], v[140:143], v[184:187], v[28:31]
	v_mfma_f32_16x16x32_bf16 v[20:23], v[160:163], v[184:187], v[20:23]
	v_mfma_f32_16x16x32_bf16 v[24:27], v[140:143], v[192:195], v[24:27]
	v_mfma_f32_16x16x32_bf16 v[16:19], v[160:163], v[192:195], v[16:19]
	v_mfma_f32_16x16x32_bf16 v[60:63], v[156:159], v[172:175], v[60:63]
	v_mfma_f32_16x16x32_bf16 v[56:59], v[164:167], v[172:175], v[56:59]
	v_mfma_f32_16x16x32_bf16 v[52:55], v[156:159], v[180:183], v[52:55]
	v_mfma_f32_16x16x32_bf16 v[48:51], v[164:167], v[180:183], v[48:51]
	v_mfma_f32_16x16x32_bf16 v[28:31], v[156:159], v[188:191], v[28:31]
	v_mfma_f32_16x16x32_bf16 v[20:23], v[164:167], v[188:191], v[20:23]
	v_mfma_f32_16x16x32_bf16 v[24:27], v[156:159], v[196:199], v[24:27]
	v_mfma_f32_16x16x32_bf16 v[16:19], v[164:167], v[196:199], v[16:19]
	s_barrier
	s_mov_b32 m0, s87
	v_lshl_add_u64 v[140:141], s[58:59], 0, v[132:133]
	global_load_lds_dwordx4 v[140:141], off
	s_mov_b32 m0, s86
	v_lshl_add_u64 v[140:141], s[58:59], 0, v[128:129]
	global_load_lds_dwordx4 v[140:141], off
	s_waitcnt vmcnt(6)
	s_barrier
	v_mfma_f32_16x16x32_bf16 v[44:47], v[200:203], v[168:171], v[44:47]
	v_mfma_f32_16x16x32_bf16 v[40:43], v[208:211], v[168:171], v[40:43]
	v_mfma_f32_16x16x32_bf16 v[36:39], v[200:203], v[176:179], v[36:39]
	v_mfma_f32_16x16x32_bf16 v[32:35], v[208:211], v[176:179], v[32:35]
	v_mfma_f32_16x16x32_bf16 v[12:15], v[200:203], v[184:187], v[12:15]
	v_mfma_f32_16x16x32_bf16 v[4:7], v[208:211], v[184:187], v[4:7]
	v_mfma_f32_16x16x32_bf16 v[8:11], v[200:203], v[192:195], v[8:11]
	v_mfma_f32_16x16x32_bf16 v[0:3], v[208:211], v[192:195], v[0:3]
	v_mfma_f32_16x16x32_bf16 v[44:47], v[204:207], v[172:175], v[44:47]
	v_mfma_f32_16x16x32_bf16 v[40:43], v[212:215], v[172:175], v[40:43]
	v_mfma_f32_16x16x32_bf16 v[36:39], v[204:207], v[180:183], v[36:39]
	v_mfma_f32_16x16x32_bf16 v[32:35], v[212:215], v[180:183], v[32:35]
	v_mfma_f32_16x16x32_bf16 v[12:15], v[204:207], v[188:191], v[12:15]
	v_mfma_f32_16x16x32_bf16 v[4:7], v[212:215], v[188:191], v[4:7]
	v_mfma_f32_16x16x32_bf16 v[8:11], v[204:207], v[196:199], v[8:11]
	v_mfma_f32_16x16x32_bf16 v[0:3], v[212:215], v[196:199], v[0:3]
	s_andn2_b64 vcc, exec, s[56:57]
	s_mov_b64 s[58:59], -1
	s_mov_b64 s[56:57], 0
	s_mov_b64 s[60:61], 0x100
	s_barrier
	s_cbranch_vccz .LBB0_547
	v_lshl_add_u32 v142, s50, 8, v146
	v_lshl_or_b32 v140, s81, 8, v148
	v_ashrrev_i32_e32 v143, 31, v142
	v_lshlrev_b64 v[144:145], 11, v[142:143]
	v_ashrrev_i32_e32 v141, 31, v140
	v_lshl_add_u64 v[152:153], s[28:29], 0, v[144:145]
	v_lshlrev_b64 v[144:145], 1, v[140:141]
	v_lshl_add_u64 v[140:141], v[152:153], 0, v[144:145]
	v_or_b32_e32 v152, 16, v142
	v_ashrrev_i32_e32 v153, 31, v152
	v_lshlrev_b64 v[152:153], 11, v[152:153]
	global_load_dwordx4 v[156:159], v[140:141], off
	global_load_dwordx4 v[160:163], v[140:141], off offset:256
	v_lshl_add_u64 v[152:153], s[28:29], 0, v[152:153]
	v_lshl_add_u64 v[152:153], v[152:153], 0, v[144:145]
	global_load_dwordx4 v[164:167], v[152:153], off
	global_load_dwordx4 v[168:171], v[152:153], off offset:256
	s_waitcnt vmcnt(0)
	v_lshlrev_b32_e32 v172, 16, v156
	v_and_b32_e32 v173, 0xffff0000, v156
	v_lshlrev_b32_e32 v156, 16, v157
	v_and_b32_e32 v157, 0xffff0000, v157
	v_lshlrev_b32_e32 v176, 16, v160
	v_and_b32_e32 v177, 0xffff0000, v160
	v_lshlrev_b32_e32 v160, 16, v161
	v_and_b32_e32 v161, 0xffff0000, v161
	v_lshlrev_b32_e32 v178, 16, v162
	v_and_b32_e32 v179, 0xffff0000, v162
	v_lshlrev_b32_e32 v162, 16, v163
	v_and_b32_e32 v163, 0xffff0000, v163
	v_lshlrev_b32_e32 v174, 16, v158
	v_and_b32_e32 v175, 0xffff0000, v158
	v_lshlrev_b32_e32 v158, 16, v159
	v_and_b32_e32 v159, 0xffff0000, v159
	v_pk_mul_f32 v[126:127], v[126:127], v[156:157]
	v_pk_mul_f32 v[118:119], v[118:119], v[160:161]
	v_pk_mul_f32 v[156:157], v[110:111], v[162:163]
	v_lshlrev_b32_e32 v160, 16, v164
	v_and_b32_e32 v161, 0xffff0000, v164
	v_lshlrev_b32_e32 v162, 16, v165
	v_and_b32_e32 v163, 0xffff0000, v165
	v_lshlrev_b32_e32 v164, 16, v166
	v_and_b32_e32 v165, 0xffff0000, v166
	v_lshlrev_b32_e32 v166, 16, v167
	v_and_b32_e32 v167, 0xffff0000, v167
	v_pk_mul_f32 v[124:125], v[124:125], v[172:173]
	v_pk_mul_f32 v[122:123], v[122:123], v[158:159]
	v_pk_mul_f32 v[120:121], v[120:121], v[174:175]
	v_lshlrev_b32_e32 v172, 16, v168
	v_and_b32_e32 v173, 0xffff0000, v168
	v_lshlrev_b32_e32 v168, 16, v169
	v_and_b32_e32 v169, 0xffff0000, v169
	v_lshlrev_b32_e32 v174, 16, v170
	v_and_b32_e32 v175, 0xffff0000, v170
	v_lshlrev_b32_e32 v170, 16, v171
	v_and_b32_e32 v171, 0xffff0000, v171
	v_pk_mul_f32 v[114:115], v[114:115], v[162:163]
	v_pk_mul_f32 v[112:113], v[112:113], v[160:161]
	v_pk_mul_f32 v[106:107], v[106:107], v[166:167]
	v_pk_mul_f32 v[104:105], v[104:105], v[164:165]
	v_pk_mul_f32 v[116:117], v[116:117], v[176:177]
	v_pk_mul_f32 v[158:159], v[108:109], v[178:179]
	v_cvt_pk_bf16_f32 v108, v124, v125
	v_cvt_pk_bf16_f32 v109, v126, v127
	v_cvt_pk_bf16_f32 v110, v120, v121
	v_cvt_pk_bf16_f32 v111, v122, v123
	v_pk_mul_f32 v[102:103], v[102:103], v[168:169]
	v_pk_mul_f32 v[100:101], v[100:101], v[172:173]
	v_pk_mul_f32 v[120:121], v[98:99], v[170:171]
	v_pk_mul_f32 v[122:123], v[96:97], v[174:175]
	v_cvt_pk_bf16_f32 v96, v112, v113
	v_cvt_pk_bf16_f32 v97, v114, v115
	v_cvt_pk_bf16_f32 v98, v104, v105
	v_cvt_pk_bf16_f32 v99, v106, v107
	v_cvt_pk_bf16_f32 v116, v116, v117
	v_cvt_pk_bf16_f32 v117, v118, v119
	v_cvt_pk_bf16_f32 v118, v158, v159
	v_cvt_pk_bf16_f32 v119, v156, v157
	global_store_dwordx4 v[140:141], v[108:111], off
	global_store_dwordx4 v[140:141], v[116:119], off offset:256
	v_cvt_pk_bf16_f32 v100, v100, v101
	v_cvt_pk_bf16_f32 v101, v102, v103
	v_cvt_pk_bf16_f32 v102, v122, v123
	v_cvt_pk_bf16_f32 v103, v120, v121
	global_store_dwordx4 v[152:153], v[96:99], off
	global_store_dwordx4 v[152:153], v[100:103], off offset:256
	s_nop 0
	v_or_b32_e32 v96, 32, v142
	v_ashrrev_i32_e32 v97, 31, v96
	v_lshlrev_b64 v[96:97], 11, v[96:97]
	v_or_b32_e32 v104, 48, v142
	v_lshl_add_u64 v[96:97], s[28:29], 0, v[96:97]
	v_ashrrev_i32_e32 v105, 31, v104
	v_lshl_add_u64 v[112:113], v[96:97], 0, v[144:145]
	v_lshlrev_b64 v[104:105], 11, v[104:105]
	global_load_dwordx4 v[96:99], v[112:113], off
	global_load_dwordx4 v[100:103], v[112:113], off offset:256
	v_lshl_add_u64 v[104:105], s[28:29], 0, v[104:105]
	v_lshl_add_u64 v[114:115], v[104:105], 0, v[144:145]
	global_load_dwordx4 v[104:107], v[114:115], off
	global_load_dwordx4 v[108:111], v[114:115], off offset:256
	s_waitcnt vmcnt(0)
	v_lshlrev_b32_e32 v116, 16, v96
	v_and_b32_e32 v117, 0xffff0000, v96
	v_lshlrev_b32_e32 v96, 16, v97
	v_and_b32_e32 v97, 0xffff0000, v97
	v_lshlrev_b32_e32 v120, 16, v100
	v_and_b32_e32 v121, 0xffff0000, v100
	v_lshlrev_b32_e32 v100, 16, v101
	v_and_b32_e32 v101, 0xffff0000, v101
	v_lshlrev_b32_e32 v122, 16, v102
	v_and_b32_e32 v123, 0xffff0000, v102
	v_lshlrev_b32_e32 v102, 16, v103
	v_and_b32_e32 v103, 0xffff0000, v103
	v_lshlrev_b32_e32 v118, 16, v98
	v_and_b32_e32 v119, 0xffff0000, v98
	v_lshlrev_b32_e32 v98, 16, v99
	v_and_b32_e32 v99, 0xffff0000, v99
	v_pk_mul_f32 v[94:95], v[94:95], v[96:97]
	v_pk_mul_f32 v[86:87], v[86:87], v[100:101]
	v_pk_mul_f32 v[96:97], v[78:79], v[102:103]
	v_lshlrev_b32_e32 v100, 16, v104
	v_and_b32_e32 v101, 0xffff0000, v104
	v_lshlrev_b32_e32 v102, 16, v105
	v_and_b32_e32 v103, 0xffff0000, v105
	v_lshlrev_b32_e32 v104, 16, v106
	v_and_b32_e32 v105, 0xffff0000, v106
	v_lshlrev_b32_e32 v106, 16, v107
	v_and_b32_e32 v107, 0xffff0000, v107
	v_pk_mul_f32 v[92:93], v[92:93], v[116:117]
	v_pk_mul_f32 v[90:91], v[90:91], v[98:99]
	v_pk_mul_f32 v[88:89], v[88:89], v[118:119]
	v_lshlrev_b32_e32 v116, 16, v108
	v_and_b32_e32 v117, 0xffff0000, v108
	v_lshlrev_b32_e32 v108, 16, v109
	v_and_b32_e32 v109, 0xffff0000, v109
	v_lshlrev_b32_e32 v118, 16, v110
	v_and_b32_e32 v119, 0xffff0000, v110
	v_lshlrev_b32_e32 v110, 16, v111
	v_and_b32_e32 v111, 0xffff0000, v111
	v_pk_mul_f32 v[82:83], v[82:83], v[102:103]
	v_pk_mul_f32 v[80:81], v[80:81], v[100:101]
	v_pk_mul_f32 v[74:75], v[74:75], v[106:107]
	v_pk_mul_f32 v[72:73], v[72:73], v[104:105]
	v_pk_mul_f32 v[84:85], v[84:85], v[120:121]
	v_pk_mul_f32 v[98:99], v[76:77], v[122:123]
	v_cvt_pk_bf16_f32 v76, v92, v93
	v_cvt_pk_bf16_f32 v77, v94, v95
	v_cvt_pk_bf16_f32 v78, v88, v89
	v_cvt_pk_bf16_f32 v79, v90, v91
	v_pk_mul_f32 v[70:71], v[70:71], v[108:109]
	v_pk_mul_f32 v[68:69], v[68:69], v[116:117]
	v_pk_mul_f32 v[88:89], v[66:67], v[110:111]
	v_pk_mul_f32 v[90:91], v[64:65], v[118:119]
	v_cvt_pk_bf16_f32 v64, v80, v81
	v_cvt_pk_bf16_f32 v65, v82, v83
	v_cvt_pk_bf16_f32 v66, v72, v73
	v_cvt_pk_bf16_f32 v67, v74, v75
	v_cvt_pk_bf16_f32 v84, v84, v85
	v_cvt_pk_bf16_f32 v85, v86, v87
	v_cvt_pk_bf16_f32 v86, v98, v99
	v_cvt_pk_bf16_f32 v87, v96, v97
	global_store_dwordx4 v[112:113], v[76:79], off
	global_store_dwordx4 v[112:113], v[84:87], off offset:256
	v_cvt_pk_bf16_f32 v68, v68, v69
	v_cvt_pk_bf16_f32 v69, v70, v71
	v_cvt_pk_bf16_f32 v70, v90, v91
	v_cvt_pk_bf16_f32 v71, v88, v89
	global_store_dwordx4 v[114:115], v[64:67], off
	global_store_dwordx4 v[114:115], v[68:71], off offset:256
	s_mov_b32 s25, 0x40000
	v_add_co_u32_e32 v80, vcc, s25, v140
	s_mov_b64 s[52:53], 0x40000
	s_nop 0
	v_addc_co_u32_e32 v81, vcc, 0, v141, vcc
	s_mov_b32 s25, 0x48000
	v_lshl_add_u64 v[82:83], v[140:141], 0, s[52:53]
	v_add_co_u32_e32 v84, vcc, s25, v140
	s_mov_b64 s[52:53], 0x48000
	global_load_dwordx4 v[64:67], v[80:81], off
	global_load_dwordx4 v[68:71], v[82:83], off offset:256
	v_addc_co_u32_e32 v85, vcc, 0, v141, vcc
	v_lshl_add_u64 v[86:87], v[140:141], 0, s[52:53]
	global_load_dwordx4 v[72:75], v[84:85], off
	global_load_dwordx4 v[76:79], v[86:87], off offset:256
	s_waitcnt vmcnt(0)
	v_lshlrev_b32_e32 v88, 16, v64
	v_and_b32_e32 v89, 0xffff0000, v64
	v_lshlrev_b32_e32 v64, 16, v65
	v_and_b32_e32 v65, 0xffff0000, v65
	v_lshlrev_b32_e32 v90, 16, v66
	v_and_b32_e32 v91, 0xffff0000, v66
	v_lshlrev_b32_e32 v66, 16, v67
	v_and_b32_e32 v67, 0xffff0000, v67
	v_lshlrev_b32_e32 v92, 16, v68
	v_and_b32_e32 v93, 0xffff0000, v68
	v_lshlrev_b32_e32 v68, 16, v69
	v_and_b32_e32 v69, 0xffff0000, v69
	v_lshlrev_b32_e32 v94, 16, v70
	v_and_b32_e32 v95, 0xffff0000, v70
	v_lshlrev_b32_e32 v70, 16, v71
	v_and_b32_e32 v71, 0xffff0000, v71
	v_lshlrev_b32_e32 v96, 16, v72
	v_and_b32_e32 v97, 0xffff0000, v72
	v_lshlrev_b32_e32 v72, 16, v73
	v_and_b32_e32 v73, 0xffff0000, v73
	v_lshlrev_b32_e32 v98, 16, v74
	v_and_b32_e32 v99, 0xffff0000, v74
	v_lshlrev_b32_e32 v74, 16, v75
	v_and_b32_e32 v75, 0xffff0000, v75
	v_lshlrev_b32_e32 v100, 16, v76
	v_and_b32_e32 v101, 0xffff0000, v76
	v_lshlrev_b32_e32 v76, 16, v77
	v_and_b32_e32 v77, 0xffff0000, v77
	v_lshlrev_b32_e32 v102, 16, v78
	v_and_b32_e32 v103, 0xffff0000, v78
	v_lshlrev_b32_e32 v78, 16, v79
	v_and_b32_e32 v79, 0xffff0000, v79
	v_pk_mul_f32 v[62:63], v[62:63], v[64:65]
	v_pk_mul_f32 v[60:61], v[60:61], v[88:89]
	v_pk_mul_f32 v[58:59], v[58:59], v[66:67]
	v_pk_mul_f32 v[56:57], v[56:57], v[90:91]
	v_pk_mul_f32 v[46:47], v[46:47], v[68:69]
	v_pk_mul_f32 v[44:45], v[44:45], v[92:93]
	v_pk_mul_f32 v[42:43], v[42:43], v[70:71]
	v_pk_mul_f32 v[40:41], v[40:41], v[94:95]
	v_pk_mul_f32 v[54:55], v[54:55], v[72:73]
	v_pk_mul_f32 v[52:53], v[52:53], v[96:97]
	v_pk_mul_f32 v[50:51], v[50:51], v[74:75]
	v_pk_mul_f32 v[48:49], v[48:49], v[98:99]
	v_pk_mul_f32 v[64:65], v[38:39], v[76:77]
	v_pk_mul_f32 v[66:67], v[36:37], v[100:101]
	v_pk_mul_f32 v[68:69], v[34:35], v[78:79]
	v_pk_mul_f32 v[70:71], v[32:33], v[102:103]
	v_cvt_pk_bf16_f32 v32, v60, v61
	v_cvt_pk_bf16_f32 v33, v62, v63
	v_cvt_pk_bf16_f32 v34, v56, v57
	v_cvt_pk_bf16_f32 v35, v58, v59
	v_cvt_pk_bf16_f32 v36, v44, v45
	v_cvt_pk_bf16_f32 v37, v46, v47
	v_cvt_pk_bf16_f32 v38, v40, v41
	v_cvt_pk_bf16_f32 v39, v42, v43
	v_cvt_pk_bf16_f32 v40, v52, v53
	v_cvt_pk_bf16_f32 v41, v54, v55
	v_cvt_pk_bf16_f32 v42, v48, v49
	v_cvt_pk_bf16_f32 v43, v50, v51
	v_cvt_pk_bf16_f32 v44, v66, v67
	v_cvt_pk_bf16_f32 v45, v64, v65
	v_cvt_pk_bf16_f32 v46, v70, v71
	v_cvt_pk_bf16_f32 v47, v68, v69
	global_store_dwordx4 v[80:81], v[32:35], off
	global_store_dwordx4 v[82:83], v[36:39], off offset:256
	global_store_dwordx4 v[84:85], v[40:43], off
	global_store_dwordx4 v[86:87], v[44:47], off offset:256
	v_add_co_u32_e32 v48, vcc, s80, v140
	s_mov_b32 s25, 0x50000
	s_nop 0
	v_addc_co_u32_e32 v49, vcc, 0, v141, vcc
	v_add_co_u32_e32 v52, vcc, s25, v140
	v_lshl_add_u64 v[50:51], v[140:141], 0, s[14:15]
	s_nop 0
	v_addc_co_u32_e32 v53, vcc, 0, v141, vcc
	s_mov_b64 s[52:53], 0x50000
	global_load_dwordx4 v[32:35], v[48:49], off
	global_load_dwordx4 v[36:39], v[50:51], off offset:256
	global_load_dwordx4 v[40:43], v[52:53], off
	v_lshl_add_u64 v[54:55], v[140:141], 0, s[52:53]
	global_load_dwordx4 v[44:47], v[54:55], off offset:256
	s_and_b64 vcc, exec, s[4:5]
	s_mov_b32 s81, s24
	s_mov_b32 s50, s40
	s_mov_b64 s[52:53], s[48:49]
	s_mov_b64 s[54:55], s[46:47]
	s_waitcnt vmcnt(0)
	v_lshlrev_b32_e32 v56, 16, v32
	v_lshlrev_b32_e32 v60, 16, v36
	v_and_b32_e32 v61, 0xffff0000, v36
	v_lshlrev_b32_e32 v36, 16, v37
	v_and_b32_e32 v37, 0xffff0000, v37
	v_lshlrev_b32_e32 v64, 16, v40
	v_and_b32_e32 v65, 0xffff0000, v40
	v_lshlrev_b32_e32 v40, 16, v41
	v_and_b32_e32 v41, 0xffff0000, v41
	v_lshlrev_b32_e32 v66, 16, v42
	v_and_b32_e32 v67, 0xffff0000, v42
	v_lshlrev_b32_e32 v42, 16, v43
	v_and_b32_e32 v43, 0xffff0000, v43
	v_and_b32_e32 v57, 0xffff0000, v32
	v_lshlrev_b32_e32 v32, 16, v33
	v_and_b32_e32 v33, 0xffff0000, v33
	v_lshlrev_b32_e32 v58, 16, v34
	v_and_b32_e32 v59, 0xffff0000, v34
	v_lshlrev_b32_e32 v34, 16, v35
	v_and_b32_e32 v35, 0xffff0000, v35
	v_lshlrev_b32_e32 v62, 16, v38
	v_and_b32_e32 v63, 0xffff0000, v38
	v_lshlrev_b32_e32 v38, 16, v39
	v_and_b32_e32 v39, 0xffff0000, v39
	v_lshlrev_b32_e32 v68, 16, v44
	v_and_b32_e32 v69, 0xffff0000, v44
	v_lshlrev_b32_e32 v44, 16, v45
	v_and_b32_e32 v45, 0xffff0000, v45
	v_lshlrev_b32_e32 v70, 16, v46
	v_and_b32_e32 v71, 0xffff0000, v46
	v_lshlrev_b32_e32 v46, 16, v47
	v_and_b32_e32 v47, 0xffff0000, v47
	v_pk_mul_f32 v[10:11], v[10:11], v[36:37]
	v_pk_mul_f32 v[8:9], v[8:9], v[60:61]
	v_pk_mul_f32 v[30:31], v[30:31], v[40:41]
	v_pk_mul_f32 v[28:29], v[28:29], v[64:65]
	v_pk_mul_f32 v[22:23], v[22:23], v[42:43]
	v_pk_mul_f32 v[20:21], v[20:21], v[66:67]
	v_pk_mul_f32 v[26:27], v[26:27], v[32:33]
	v_pk_mul_f32 v[24:25], v[24:25], v[56:57]
	v_pk_mul_f32 v[18:19], v[18:19], v[34:35]
	v_pk_mul_f32 v[16:17], v[16:17], v[58:59]
	v_pk_mul_f32 v[32:33], v[2:3], v[38:39]
	v_pk_mul_f32 v[34:35], v[0:1], v[62:63]
	v_pk_mul_f32 v[14:15], v[14:15], v[44:45]
	v_pk_mul_f32 v[12:13], v[12:13], v[68:69]
	v_pk_mul_f32 v[36:37], v[6:7], v[46:47]
	v_pk_mul_f32 v[38:39], v[4:5], v[70:71]
	v_cvt_pk_bf16_f32 v4, v8, v9
	v_cvt_pk_bf16_f32 v5, v10, v11
	v_cvt_pk_bf16_f32 v8, v28, v29
	v_cvt_pk_bf16_f32 v9, v30, v31
	v_cvt_pk_bf16_f32 v10, v20, v21
	v_cvt_pk_bf16_f32 v11, v22, v23
	v_cvt_pk_bf16_f32 v0, v24, v25
	v_cvt_pk_bf16_f32 v1, v26, v27
	v_cvt_pk_bf16_f32 v2, v16, v17
	v_cvt_pk_bf16_f32 v3, v18, v19
	v_cvt_pk_bf16_f32 v6, v34, v35
	v_cvt_pk_bf16_f32 v7, v32, v33
	v_cvt_pk_bf16_f32 v12, v12, v13
	v_cvt_pk_bf16_f32 v13, v14, v15
	v_cvt_pk_bf16_f32 v14, v38, v39
	v_cvt_pk_bf16_f32 v15, v36, v37
	global_store_dwordx4 v[52:53], v[8:11], off
	global_store_dwordx4 v[54:55], v[12:15], off offset:256
	global_store_dwordx4 v[48:49], v[0:3], off
	global_store_dwordx4 v[50:51], v[4:7], off offset:256
	s_cbranch_vccz .LBB0_544
	s_waitcnt vmcnt(0)
	v_readlane_b32 s78, v228, 33
	v_readlane_b32 s80, v228, 36
	s_cmpk_gt_u32 s0, 0xff
	v_readlane_b32 s76, v228, 32
	v_readlane_b32 s79, v228, 34
	v_readlane_b32 s77, v228, 35
	v_readlane_b32 s81, v228, 37
	s_cbranch_scc1 .LBB0_551
	s_barrier

.LBB0_569:
	ds_read_b128 v[144:147], v157
	ds_read_b128 v[148:151], v157 offset:1024
	ds_read_b128 v[160:163], v157 offset:2048
	ds_read_b128 v[164:167], v157 offset:3072
	s_add_u32 s60, s58, 0xfffc0080
	s_addc_u32 s61, s59, -1
	s_cmp_eq_u32 s83, 12
	s_cselect_b32 s63, s51, s61
	s_cselect_b32 s62, s79, s60
	s_cselect_b32 s61, s49, s82
	s_cselect_b32 s60, s80, s81
	v_lshl_add_u64 v[200:201], s[58:59], 0, v[136:137]
	s_add_i32 m0, s57, 0xc000
	ds_read_b128 v[168:171], v158
	ds_read_b128 v[172:175], v158 offset:1024
	ds_read_b128 v[176:179], v158 offset:2048
	ds_read_b128 v[180:183], v158 offset:3072
	ds_read_b128 v[184:187], v158 offset:4096
	ds_read_b128 v[188:191], v158 offset:5120
	ds_read_b128 v[192:195], v158 offset:6144
	ds_read_b128 v[196:199], v158 offset:7168
	global_load_lds_dwordx4 v[200:201], off
	s_add_i32 m0, s57, 0xe000
	v_lshl_add_u64 v[200:201], s[58:59], 0, v[138:139]
	global_load_lds_dwordx4 v[200:201], off
	s_waitcnt lgkmcnt(8)
	s_barrier
	s_waitcnt lgkmcnt(0)
	v_mfma_f32_16x16x32_bf16 v[124:127], v[144:147], v[168:171], v[124:127]
	v_mfma_f32_16x16x32_bf16 v[120:123], v[160:163], v[168:171], v[120:123]
	v_mfma_f32_16x16x32_bf16 v[108:111], v[144:147], v[176:179], v[108:111]
	v_mfma_f32_16x16x32_bf16 v[104:107], v[160:163], v[176:179], v[104:107]
	v_mfma_f32_16x16x32_bf16 v[92:95], v[144:147], v[184:187], v[92:95]
	v_mfma_f32_16x16x32_bf16 v[88:91], v[160:163], v[184:187], v[88:91]
	v_mfma_f32_16x16x32_bf16 v[76:79], v[144:147], v[192:195], v[76:79]
	v_mfma_f32_16x16x32_bf16 v[72:75], v[160:163], v[192:195], v[72:75]
	v_mfma_f32_16x16x32_bf16 v[124:127], v[148:151], v[172:175], v[124:127]
	v_mfma_f32_16x16x32_bf16 v[120:123], v[164:167], v[172:175], v[120:123]
	v_mfma_f32_16x16x32_bf16 v[108:111], v[148:151], v[180:183], v[108:111]
	v_mfma_f32_16x16x32_bf16 v[104:107], v[164:167], v[180:183], v[104:107]
	v_mfma_f32_16x16x32_bf16 v[92:95], v[148:151], v[188:191], v[92:95]
	v_mfma_f32_16x16x32_bf16 v[88:91], v[164:167], v[188:191], v[88:91]
	v_mfma_f32_16x16x32_bf16 v[76:79], v[148:151], v[196:199], v[76:79]
	v_mfma_f32_16x16x32_bf16 v[72:75], v[164:167], v[196:199], v[72:75]
	s_barrier
	s_add_i32 s86, s73, s34
	v_lshl_add_u64 v[216:217], s[60:61], 0, v[132:133]
	s_mov_b32 m0, s86
	ds_read_b128 v[200:203], v159
	ds_read_b128 v[204:207], v159 offset:1024
	ds_read_b128 v[208:211], v159 offset:2048
	ds_read_b128 v[212:215], v159 offset:3072
	global_load_lds_dwordx4 v[216:217], off
	s_add_i32 m0, s86, 0x2000
	v_lshl_add_u64 v[218:219], s[60:61], 0, v[128:129]
	global_load_lds_dwordx4 v[218:219], off
	s_barrier
	s_waitcnt lgkmcnt(0)
	v_mfma_f32_16x16x32_bf16 v[116:119], v[200:203], v[168:171], v[116:119]
	v_mfma_f32_16x16x32_bf16 v[112:115], v[208:211], v[168:171], v[112:115]
	v_mfma_f32_16x16x32_bf16 v[100:103], v[200:203], v[176:179], v[100:103]
	v_mfma_f32_16x16x32_bf16 v[96:99], v[208:211], v[176:179], v[96:99]
	v_mfma_f32_16x16x32_bf16 v[84:87], v[200:203], v[184:187], v[84:87]
	v_mfma_f32_16x16x32_bf16 v[80:83], v[208:211], v[184:187], v[80:83]
	v_mfma_f32_16x16x32_bf16 v[68:71], v[200:203], v[192:195], v[68:71]
	v_mfma_f32_16x16x32_bf16 v[64:67], v[208:211], v[192:195], v[64:67]
	v_mfma_f32_16x16x32_bf16 v[116:119], v[204:207], v[172:175], v[116:119]
	v_mfma_f32_16x16x32_bf16 v[112:115], v[212:215], v[172:175], v[112:115]
	v_mfma_f32_16x16x32_bf16 v[100:103], v[204:207], v[180:183], v[100:103]
	v_mfma_f32_16x16x32_bf16 v[96:99], v[212:215], v[180:183], v[96:99]
	v_mfma_f32_16x16x32_bf16 v[84:87], v[204:207], v[188:191], v[84:87]
	v_mfma_f32_16x16x32_bf16 v[80:83], v[212:215], v[188:191], v[80:83]
	v_mfma_f32_16x16x32_bf16 v[68:71], v[204:207], v[196:199], v[68:71]
	v_mfma_f32_16x16x32_bf16 v[64:67], v[212:215], v[196:199], v[64:67]
	s_mov_b32 m0, s57
	v_lshl_add_u64 v[220:221], s[62:63], 0, v[134:135]
	s_barrier
	ds_read_b128 v[168:171], v158 offset:16384
	ds_read_b128 v[172:175], v158 offset:17408
	ds_read_b128 v[176:179], v158 offset:18432
	ds_read_b128 v[180:183], v158 offset:19456
	ds_read_b128 v[184:187], v158 offset:20480
	ds_read_b128 v[188:191], v158 offset:21504
	ds_read_b128 v[192:195], v158 offset:22528
	ds_read_b128 v[196:199], v158 offset:23552
	global_load_lds_dwordx4 v[220:221], off
	s_mov_b32 m0, s65
	v_lshl_add_u64 v[222:223], s[62:63], 0, v[130:131]
	global_load_lds_dwordx4 v[222:223], off
	s_barrier
	s_waitcnt lgkmcnt(0)
	v_mfma_f32_16x16x32_bf16 v[60:63], v[144:147], v[168:171], v[60:63]
	v_mfma_f32_16x16x32_bf16 v[56:59], v[160:163], v[168:171], v[56:59]
	v_mfma_f32_16x16x32_bf16 v[44:47], v[144:147], v[176:179], v[44:47]
	v_mfma_f32_16x16x32_bf16 v[40:43], v[160:163], v[176:179], v[40:43]
	v_mfma_f32_16x16x32_bf16 v[28:31], v[144:147], v[184:187], v[28:31]
	v_mfma_f32_16x16x32_bf16 v[24:27], v[160:163], v[184:187], v[24:27]
	v_mfma_f32_16x16x32_bf16 v[12:15], v[144:147], v[192:195], v[12:15]
	v_mfma_f32_16x16x32_bf16 v[8:11], v[160:163], v[192:195], v[8:11]
	v_mfma_f32_16x16x32_bf16 v[60:63], v[148:151], v[172:175], v[60:63]
	v_mfma_f32_16x16x32_bf16 v[56:59], v[164:167], v[172:175], v[56:59]
	v_mfma_f32_16x16x32_bf16 v[44:47], v[148:151], v[180:183], v[44:47]
	v_mfma_f32_16x16x32_bf16 v[40:43], v[164:167], v[180:183], v[40:43]
	v_mfma_f32_16x16x32_bf16 v[28:31], v[148:151], v[188:191], v[28:31]
	v_mfma_f32_16x16x32_bf16 v[24:27], v[164:167], v[188:191], v[24:27]
	v_mfma_f32_16x16x32_bf16 v[12:15], v[148:151], v[196:199], v[12:15]
	v_mfma_f32_16x16x32_bf16 v[8:11], v[164:167], v[196:199], v[8:11]
	s_barrier
	s_add_u32 s86, s60, 0x40000
	s_addc_u32 s87, s61, 0
	s_add_i32 s88, s72, s34
	s_mov_b32 m0, s88
	v_lshl_add_u64 v[144:145], s[86:87], 0, v[132:133]
	global_load_lds_dwordx4 v[144:145], off
	s_add_i32 m0, s88, 0x2000
	v_lshl_add_u64 v[144:145], s[86:87], 0, v[128:129]
	global_load_lds_dwordx4 v[144:145], off
	s_waitcnt vmcnt(6)
	s_barrier
	v_mfma_f32_16x16x32_bf16 v[52:55], v[200:203], v[168:171], v[52:55]
	v_mfma_f32_16x16x32_bf16 v[48:51], v[208:211], v[168:171], v[48:51]
	v_mfma_f32_16x16x32_bf16 v[36:39], v[200:203], v[176:179], v[36:39]
	v_mfma_f32_16x16x32_bf16 v[32:35], v[208:211], v[176:179], v[32:35]
	v_mfma_f32_16x16x32_bf16 v[20:23], v[200:203], v[184:187], v[20:23]
	v_mfma_f32_16x16x32_bf16 v[16:19], v[208:211], v[184:187], v[16:19]
	v_mfma_f32_16x16x32_bf16 v[4:7], v[200:203], v[192:195], v[4:7]
	v_mfma_f32_16x16x32_bf16 v[0:3], v[208:211], v[192:195], v[0:3]
	v_mfma_f32_16x16x32_bf16 v[52:55], v[204:207], v[172:175], v[52:55]
	v_mfma_f32_16x16x32_bf16 v[48:51], v[212:215], v[172:175], v[48:51]
	v_mfma_f32_16x16x32_bf16 v[36:39], v[204:207], v[180:183], v[36:39]
	v_mfma_f32_16x16x32_bf16 v[32:35], v[212:215], v[180:183], v[32:35]
	v_mfma_f32_16x16x32_bf16 v[20:23], v[204:207], v[188:191], v[20:23]
	v_mfma_f32_16x16x32_bf16 v[16:19], v[212:215], v[188:191], v[16:19]
	v_mfma_f32_16x16x32_bf16 v[4:7], v[204:207], v[196:199], v[4:7]
	v_mfma_f32_16x16x32_bf16 v[0:3], v[212:215], v[196:199], v[0:3]
	s_add_i32 s86, 0, 0x18000
	v_add_u32_e32 v164, s86, v153
	s_barrier
	ds_read_b128 v[144:147], v164
	ds_read_b128 v[148:151], v164 offset:1024
	ds_read_b128 v[160:163], v164 offset:2048
	ds_read_b128 v[164:167], v164 offset:3072
	s_add_u32 s62, s62, 0x40000
	s_addc_u32 s63, s63, 0
	s_mov_b32 m0, s66
	v_lshl_add_u64 v[200:201], s[62:63], 0, v[134:135]
	ds_read_b128 v[168:171], v158 offset:32768
	ds_read_b128 v[172:175], v158 offset:33792
	ds_read_b128 v[176:179], v158 offset:34816
	ds_read_b128 v[180:183], v158 offset:35840
	ds_read_b128 v[184:187], v158 offset:36864
	ds_read_b128 v[188:191], v158 offset:37888
	ds_read_b128 v[192:195], v158 offset:38912
	ds_read_b128 v[196:199], v158 offset:39936
	global_load_lds_dwordx4 v[200:201], off
	s_mov_b32 m0, s67
	v_lshl_add_u64 v[200:201], s[62:63], 0, v[130:131]
	global_load_lds_dwordx4 v[200:201], off
	s_waitcnt lgkmcnt(8)
	s_barrier
	s_waitcnt lgkmcnt(0)
	v_mfma_f32_16x16x32_bf16 v[124:127], v[144:147], v[168:171], v[124:127]
	v_mfma_f32_16x16x32_bf16 v[120:123], v[160:163], v[168:171], v[120:123]
	v_mfma_f32_16x16x32_bf16 v[108:111], v[144:147], v[176:179], v[108:111]
	v_mfma_f32_16x16x32_bf16 v[104:107], v[160:163], v[176:179], v[104:107]
	v_mfma_f32_16x16x32_bf16 v[92:95], v[144:147], v[184:187], v[92:95]
	v_mfma_f32_16x16x32_bf16 v[88:91], v[160:163], v[184:187], v[88:91]
	v_mfma_f32_16x16x32_bf16 v[76:79], v[144:147], v[192:195], v[76:79]
	v_mfma_f32_16x16x32_bf16 v[72:75], v[160:163], v[192:195], v[72:75]
	v_mfma_f32_16x16x32_bf16 v[124:127], v[148:151], v[172:175], v[124:127]
	v_mfma_f32_16x16x32_bf16 v[120:123], v[164:167], v[172:175], v[120:123]
	v_mfma_f32_16x16x32_bf16 v[108:111], v[148:151], v[180:183], v[108:111]
	v_mfma_f32_16x16x32_bf16 v[104:107], v[164:167], v[180:183], v[104:107]
	v_mfma_f32_16x16x32_bf16 v[92:95], v[148:151], v[188:191], v[92:95]
	v_mfma_f32_16x16x32_bf16 v[88:91], v[164:167], v[188:191], v[88:91]
	v_mfma_f32_16x16x32_bf16 v[76:79], v[148:151], v[196:199], v[76:79]
	v_mfma_f32_16x16x32_bf16 v[72:75], v[164:167], v[196:199], v[72:75]
	s_barrier
	s_add_i32 s62, s86, s34
	v_add_u32_e32 v212, s97, v153
	v_lshl_add_u64 v[216:217], v[216:217], 0, s[8:9]
	s_mov_b32 m0, s62
	ds_read_b128 v[200:203], v212
	ds_read_b128 v[204:207], v212 offset:1024
	ds_read_b128 v[208:211], v212 offset:2048
	ds_read_b128 v[212:215], v212 offset:3072
	global_load_lds_dwordx4 v[216:217], off
	s_add_i32 m0, s62, 0x2000
	v_lshl_add_u64 v[216:217], v[218:219], 0, s[8:9]
	global_load_lds_dwordx4 v[216:217], off
	s_barrier
	s_waitcnt lgkmcnt(0)
	v_mfma_f32_16x16x32_bf16 v[116:119], v[200:203], v[168:171], v[116:119]
	v_mfma_f32_16x16x32_bf16 v[112:115], v[208:211], v[168:171], v[112:115]
	v_mfma_f32_16x16x32_bf16 v[100:103], v[200:203], v[176:179], v[100:103]
	v_mfma_f32_16x16x32_bf16 v[96:99], v[208:211], v[176:179], v[96:99]
	v_mfma_f32_16x16x32_bf16 v[84:87], v[200:203], v[184:187], v[84:87]
	v_mfma_f32_16x16x32_bf16 v[80:83], v[208:211], v[184:187], v[80:83]
	v_mfma_f32_16x16x32_bf16 v[68:71], v[200:203], v[192:195], v[68:71]
	v_mfma_f32_16x16x32_bf16 v[64:67], v[208:211], v[192:195], v[64:67]
	v_mfma_f32_16x16x32_bf16 v[116:119], v[204:207], v[172:175], v[116:119]
	v_mfma_f32_16x16x32_bf16 v[112:115], v[212:215], v[172:175], v[112:115]
	v_mfma_f32_16x16x32_bf16 v[100:103], v[204:207], v[180:183], v[100:103]
	v_mfma_f32_16x16x32_bf16 v[96:99], v[212:215], v[180:183], v[96:99]
	v_mfma_f32_16x16x32_bf16 v[84:87], v[204:207], v[188:191], v[84:87]
	v_mfma_f32_16x16x32_bf16 v[80:83], v[212:215], v[188:191], v[80:83]
	v_mfma_f32_16x16x32_bf16 v[68:71], v[204:207], v[196:199], v[68:71]
	v_mfma_f32_16x16x32_bf16 v[64:67], v[212:215], v[196:199], v[64:67]
	s_mov_b32 m0, s69
	v_lshl_add_u64 v[216:217], v[220:221], 0, s[8:9]
	s_barrier
	ds_read_b128 v[168:171], v158 offset:49152
	ds_read_b128 v[172:175], v158 offset:50176
	ds_read_b128 v[176:179], v158 offset:51200
	ds_read_b128 v[180:183], v158 offset:52224
	ds_read_b128 v[184:187], v158 offset:53248
	ds_read_b128 v[188:191], v158 offset:54272
	ds_read_b128 v[192:195], v158 offset:55296
	ds_read_b128 v[196:199], v158 offset:56320
	global_load_lds_dwordx4 v[216:217], off
	s_mov_b32 m0, s70
	v_lshl_add_u64 v[216:217], v[222:223], 0, s[8:9]
	global_load_lds_dwordx4 v[216:217], off
	s_barrier
	s_waitcnt lgkmcnt(0)
	v_mfma_f32_16x16x32_bf16 v[60:63], v[144:147], v[168:171], v[60:63]
	v_mfma_f32_16x16x32_bf16 v[56:59], v[160:163], v[168:171], v[56:59]
	v_mfma_f32_16x16x32_bf16 v[44:47], v[144:147], v[176:179], v[44:47]
	v_mfma_f32_16x16x32_bf16 v[40:43], v[160:163], v[176:179], v[40:43]
	v_mfma_f32_16x16x32_bf16 v[28:31], v[144:147], v[184:187], v[28:31]
	v_mfma_f32_16x16x32_bf16 v[24:27], v[160:163], v[184:187], v[24:27]
	v_mfma_f32_16x16x32_bf16 v[12:15], v[144:147], v[192:195], v[12:15]
	v_mfma_f32_16x16x32_bf16 v[8:11], v[160:163], v[192:195], v[8:11]
	v_mfma_f32_16x16x32_bf16 v[60:63], v[148:151], v[172:175], v[60:63]
	v_mfma_f32_16x16x32_bf16 v[56:59], v[164:167], v[172:175], v[56:59]
	v_mfma_f32_16x16x32_bf16 v[44:47], v[148:151], v[180:183], v[44:47]
	v_mfma_f32_16x16x32_bf16 v[40:43], v[164:167], v[180:183], v[40:43]
	v_mfma_f32_16x16x32_bf16 v[28:31], v[148:151], v[188:191], v[28:31]
	v_mfma_f32_16x16x32_bf16 v[24:27], v[164:167], v[188:191], v[24:27]
	v_mfma_f32_16x16x32_bf16 v[12:15], v[148:151], v[196:199], v[12:15]
	v_mfma_f32_16x16x32_bf16 v[8:11], v[164:167], v[196:199], v[8:11]
	s_barrier
	s_add_u32 s60, s60, 0x40080
	s_addc_u32 s61, s61, 0
	s_add_i32 s62, s97, s34
	s_mov_b32 m0, s62
	v_lshl_add_u64 v[144:145], s[60:61], 0, v[132:133]
	global_load_lds_dwordx4 v[144:145], off
	s_add_i32 m0, s62, 0x2000
	v_lshl_add_u64 v[144:145], s[60:61], 0, v[128:129]
	global_load_lds_dwordx4 v[144:145], off
	s_waitcnt vmcnt(6)
	s_barrier
	v_mfma_f32_16x16x32_bf16 v[52:55], v[200:203], v[168:171], v[52:55]
	v_mfma_f32_16x16x32_bf16 v[48:51], v[208:211], v[168:171], v[48:51]
	v_mfma_f32_16x16x32_bf16 v[36:39], v[200:203], v[176:179], v[36:39]
	v_mfma_f32_16x16x32_bf16 v[32:35], v[208:211], v[176:179], v[32:35]
	v_mfma_f32_16x16x32_bf16 v[20:23], v[200:203], v[184:187], v[20:23]
	v_mfma_f32_16x16x32_bf16 v[16:19], v[208:211], v[184:187], v[16:19]
	v_mfma_f32_16x16x32_bf16 v[4:7], v[200:203], v[192:195], v[4:7]
	v_mfma_f32_16x16x32_bf16 v[0:3], v[208:211], v[192:195], v[0:3]
	v_mfma_f32_16x16x32_bf16 v[52:55], v[204:207], v[172:175], v[52:55]
	v_mfma_f32_16x16x32_bf16 v[48:51], v[212:215], v[172:175], v[48:51]
	v_mfma_f32_16x16x32_bf16 v[36:39], v[204:207], v[180:183], v[36:39]
	v_mfma_f32_16x16x32_bf16 v[32:35], v[212:215], v[180:183], v[32:35]
	v_mfma_f32_16x16x32_bf16 v[20:23], v[204:207], v[188:191], v[20:23]
	v_mfma_f32_16x16x32_bf16 v[16:19], v[212:215], v[188:191], v[16:19]
	v_mfma_f32_16x16x32_bf16 v[4:7], v[204:207], v[196:199], v[4:7]
	v_mfma_f32_16x16x32_bf16 v[0:3], v[212:215], v[196:199], v[0:3]
	s_add_i32 s83, s83, 2
	s_add_u32 s58, s58, 0x100
	s_addc_u32 s59, s59, 0
	s_add_u32 s81, s81, 0x100
	s_addc_u32 s82, s82, 0
	s_cmp_gt_u32 s83, 13
	s_barrier
	s_cbranch_scc0 .LBB0_569
	v_lshl_or_b32 v146, s78, 8, v156
	v_ashrrev_i32_e32 v147, 31, v146
	v_lshl_add_u64 v[144:145], v[146:147], 2, s[44:45]
	global_load_dwordx4 v[160:163], v[144:145], off
	global_load_dwordx4 v[164:167], v[144:145], off offset:16
	v_lshl_add_u32 v148, s56, 8, v152
	v_ashrrev_i32_e32 v149, 31, v148
	v_lshlrev_b64 v[168:169], 12, v[148:149]
	v_lshlrev_b64 v[150:151], 1, v[146:147]
	v_lshl_add_u64 v[146:147], s[6:7], 0, v[168:169]
	v_lshl_add_u64 v[146:147], v[146:147], 0, v[150:151]
	s_mov_b32 s78, s48
	s_mov_b32 s56, s50
	s_mov_b64 s[60:61], s[54:55]
	s_mov_b64 s[58:59], s[52:53]
	s_waitcnt vmcnt(0)
	v_add_f32_e32 v124, v124, v160
	v_add_f32_e32 v120, v120, v164
	v_add_f32_e32 v125, v125, v161
	v_add_f32_e32 v121, v121, v165
	v_add_f32_e32 v126, v126, v162
	v_add_f32_e32 v122, v122, v166
	v_add_f32_e32 v127, v127, v163
	v_add_f32_e32 v123, v123, v167
	v_mul_f32_e32 v124, 0xbfb8aa3b, v124
	v_mul_f32_e32 v120, 0xbfb8aa3b, v120
	v_mul_f32_e32 v125, 0xbfb8aa3b, v125
	v_mul_f32_e32 v121, 0xbfb8aa3b, v121
	v_mul_f32_e32 v126, 0xbfb8aa3b, v126
	v_mul_f32_e32 v122, 0xbfb8aa3b, v122
	v_mul_f32_e32 v127, 0xbfb8aa3b, v127
	v_mul_f32_e32 v123, 0xbfb8aa3b, v123
	v_exp_f32_e32 v124, v124
	v_exp_f32_e32 v120, v120
	v_exp_f32_e32 v125, v125
	v_exp_f32_e32 v121, v121
	v_exp_f32_e32 v126, v126
	v_exp_f32_e32 v122, v122
	v_exp_f32_e32 v127, v127
	v_exp_f32_e32 v123, v123
	v_add_f32_e32 v124, 1.0, v124
	v_add_f32_e32 v120, 1.0, v120
	v_add_f32_e32 v125, 1.0, v125
	v_add_f32_e32 v121, 1.0, v121
	v_add_f32_e32 v126, 1.0, v126
	v_add_f32_e32 v122, 1.0, v122
	v_add_f32_e32 v127, 1.0, v127
	v_add_f32_e32 v123, 1.0, v123
	v_rcp_f32_e32 v124, v124
	v_rcp_f32_e32 v149, v120
	v_rcp_f32_e32 v120, v125
	v_rcp_f32_e32 v125, v121
	v_rcp_f32_e32 v121, v126
	v_rcp_f32_e32 v126, v127
	v_rcp_f32_e32 v127, v122
	v_rcp_f32_e32 v123, v123
	v_cvt_pk_bf16_f32 v120, v124, v120
	v_cvt_pk_bf16_f32 v121, v121, v126
	v_cvt_pk_bf16_f32 v122, v149, v125
	v_cvt_pk_bf16_f32 v123, v127, v123
	global_store_dwordx4 v[146:147], v[120:123], off
	global_load_dwordx4 v[120:123], v[144:145], off offset:512
	s_nop 0
	global_load_dwordx4 v[124:127], v[144:145], off offset:528
	s_waitcnt vmcnt(0)
	v_add_f32_e32 v116, v116, v120
	v_add_f32_e32 v112, v112, v124
	v_add_f32_e32 v117, v117, v121
	v_add_f32_e32 v113, v113, v125
	v_add_f32_e32 v118, v118, v122
	v_add_f32_e32 v114, v114, v126
	v_add_f32_e32 v119, v119, v123
	v_add_f32_e32 v115, v115, v127
	v_mul_f32_e32 v116, 0xbfb8aa3b, v116
	v_mul_f32_e32 v112, 0xbfb8aa3b, v112
	v_mul_f32_e32 v117, 0xbfb8aa3b, v117
	v_mul_f32_e32 v113, 0xbfb8aa3b, v113
	v_mul_f32_e32 v118, 0xbfb8aa3b, v118
	v_mul_f32_e32 v114, 0xbfb8aa3b, v114
	v_mul_f32_e32 v119, 0xbfb8aa3b, v119
	v_mul_f32_e32 v115, 0xbfb8aa3b, v115
	v_exp_f32_e32 v116, v116
	v_exp_f32_e32 v112, v112
	v_exp_f32_e32 v117, v117
	v_exp_f32_e32 v113, v113
	v_exp_f32_e32 v118, v118
	v_exp_f32_e32 v114, v114
	v_exp_f32_e32 v119, v119
	v_exp_f32_e32 v115, v115
	v_add_f32_e32 v116, 1.0, v116
	v_add_f32_e32 v112, 1.0, v112
	v_add_f32_e32 v117, 1.0, v117
	v_add_f32_e32 v113, 1.0, v113
	v_add_f32_e32 v118, 1.0, v118
	v_add_f32_e32 v114, 1.0, v114
	v_add_f32_e32 v119, 1.0, v119
	v_add_f32_e32 v115, 1.0, v115
	v_rcp_f32_e32 v116, v116
	v_rcp_f32_e32 v120, v112
	v_rcp_f32_e32 v112, v117
	v_rcp_f32_e32 v117, v113
	v_rcp_f32_e32 v113, v118
	v_rcp_f32_e32 v118, v119
	v_rcp_f32_e32 v119, v114
	v_rcp_f32_e32 v115, v115
	v_cvt_pk_bf16_f32 v112, v116, v112
	v_cvt_pk_bf16_f32 v113, v113, v118
	v_cvt_pk_bf16_f32 v114, v120, v117
	v_cvt_pk_bf16_f32 v115, v119, v115
	global_store_dwordx4 v[146:147], v[112:115], off offset:256
	global_load_dwordx4 v[112:115], v[144:145], off
	s_nop 0
	global_load_dwordx4 v[116:119], v[144:145], off offset:16
	v_or_b32_e32 v120, 16, v148
	v_ashrrev_i32_e32 v121, 31, v120
	v_lshlrev_b64 v[120:121], 12, v[120:121]
	v_lshl_add_u64 v[120:121], s[6:7], 0, v[120:121]
	v_lshl_add_u64 v[120:121], v[120:121], 0, v[150:151]
	s_waitcnt vmcnt(0)
	v_add_f32_e32 v108, v108, v112
	v_add_f32_e32 v104, v104, v116
	v_add_f32_e32 v109, v109, v113
	v_add_f32_e32 v105, v105, v117
	v_add_f32_e32 v110, v110, v114
	v_add_f32_e32 v106, v106, v118
	v_add_f32_e32 v111, v111, v115
	v_add_f32_e32 v107, v107, v119
	v_mul_f32_e32 v108, 0xbfb8aa3b, v108
	v_mul_f32_e32 v104, 0xbfb8aa3b, v104
	v_mul_f32_e32 v109, 0xbfb8aa3b, v109
	v_mul_f32_e32 v105, 0xbfb8aa3b, v105
	v_mul_f32_e32 v110, 0xbfb8aa3b, v110
	v_mul_f32_e32 v106, 0xbfb8aa3b, v106
	v_mul_f32_e32 v111, 0xbfb8aa3b, v111
	v_mul_f32_e32 v107, 0xbfb8aa3b, v107
	v_exp_f32_e32 v108, v108
	v_exp_f32_e32 v104, v104
	v_exp_f32_e32 v109, v109
	v_exp_f32_e32 v105, v105
	v_exp_f32_e32 v110, v110
	v_exp_f32_e32 v106, v106
	v_exp_f32_e32 v111, v111
	v_exp_f32_e32 v107, v107
	v_add_f32_e32 v108, 1.0, v108
	v_add_f32_e32 v104, 1.0, v104
	v_add_f32_e32 v109, 1.0, v109
	v_add_f32_e32 v105, 1.0, v105
	v_add_f32_e32 v110, 1.0, v110
	v_add_f32_e32 v106, 1.0, v106
	v_add_f32_e32 v111, 1.0, v111
	v_add_f32_e32 v107, 1.0, v107
	v_rcp_f32_e32 v108, v108
	v_rcp_f32_e32 v112, v104
	v_rcp_f32_e32 v104, v109
	v_rcp_f32_e32 v109, v105
	v_rcp_f32_e32 v105, v110
	v_rcp_f32_e32 v110, v111
	v_rcp_f32_e32 v111, v106
	v_rcp_f32_e32 v107, v107
	v_cvt_pk_bf16_f32 v104, v108, v104
	v_cvt_pk_bf16_f32 v105, v105, v110
	v_cvt_pk_bf16_f32 v106, v112, v109
	v_cvt_pk_bf16_f32 v107, v111, v107
	global_store_dwordx4 v[120:121], v[104:107], off
	global_load_dwordx4 v[104:107], v[144:145], off offset:512
	s_nop 0
	global_load_dwordx4 v[108:111], v[144:145], off offset:528
	s_waitcnt vmcnt(0)
	v_add_f32_e32 v100, v100, v104
	v_add_f32_e32 v96, v96, v108
	v_add_f32_e32 v101, v101, v105
	v_add_f32_e32 v97, v97, v109
	v_add_f32_e32 v102, v102, v106
	v_add_f32_e32 v98, v98, v110
	v_add_f32_e32 v103, v103, v107
	v_add_f32_e32 v99, v99, v111
	v_mul_f32_e32 v100, 0xbfb8aa3b, v100
	v_mul_f32_e32 v96, 0xbfb8aa3b, v96
	v_mul_f32_e32 v101, 0xbfb8aa3b, v101
	v_mul_f32_e32 v97, 0xbfb8aa3b, v97
	v_mul_f32_e32 v102, 0xbfb8aa3b, v102
	v_mul_f32_e32 v98, 0xbfb8aa3b, v98
	v_mul_f32_e32 v103, 0xbfb8aa3b, v103
	v_mul_f32_e32 v99, 0xbfb8aa3b, v99
	v_exp_f32_e32 v100, v100
	v_exp_f32_e32 v96, v96
	v_exp_f32_e32 v101, v101
	v_exp_f32_e32 v97, v97
	v_exp_f32_e32 v102, v102
	v_exp_f32_e32 v98, v98
	v_exp_f32_e32 v103, v103
	v_exp_f32_e32 v99, v99
	v_add_f32_e32 v100, 1.0, v100
	v_add_f32_e32 v96, 1.0, v96
	v_add_f32_e32 v101, 1.0, v101
	v_add_f32_e32 v97, 1.0, v97
	v_add_f32_e32 v102, 1.0, v102
	v_add_f32_e32 v98, 1.0, v98
	v_add_f32_e32 v103, 1.0, v103
	v_add_f32_e32 v99, 1.0, v99
	v_rcp_f32_e32 v100, v100
	v_rcp_f32_e32 v104, v96
	v_rcp_f32_e32 v96, v101
	v_rcp_f32_e32 v101, v97
	v_rcp_f32_e32 v97, v102
	v_rcp_f32_e32 v102, v103
	v_rcp_f32_e32 v103, v98
	v_rcp_f32_e32 v99, v99
	v_cvt_pk_bf16_f32 v96, v100, v96
	v_cvt_pk_bf16_f32 v97, v97, v102
	v_cvt_pk_bf16_f32 v98, v104, v101
	v_cvt_pk_bf16_f32 v99, v103, v99
	global_store_dwordx4 v[120:121], v[96:99], off offset:256
	global_load_dwordx4 v[96:99], v[144:145], off
	s_nop 0
	global_load_dwordx4 v[100:103], v[144:145], off offset:16
	v_or_b32_e32 v104, 32, v148
	v_ashrrev_i32_e32 v105, 31, v104
	v_lshlrev_b64 v[104:105], 12, v[104:105]
	v_lshl_add_u64 v[104:105], s[6:7], 0, v[104:105]
	v_lshl_add_u64 v[104:105], v[104:105], 0, v[150:151]
	s_waitcnt vmcnt(0)
	v_add_f32_e32 v92, v92, v96
	v_add_f32_e32 v88, v88, v100
	v_add_f32_e32 v93, v93, v97
	v_add_f32_e32 v89, v89, v101
	v_add_f32_e32 v94, v94, v98
	v_add_f32_e32 v90, v90, v102
	v_add_f32_e32 v95, v95, v99
	v_add_f32_e32 v91, v91, v103
	v_mul_f32_e32 v92, 0xbfb8aa3b, v92
	v_mul_f32_e32 v88, 0xbfb8aa3b, v88
	v_mul_f32_e32 v93, 0xbfb8aa3b, v93
	v_mul_f32_e32 v89, 0xbfb8aa3b, v89
	v_mul_f32_e32 v94, 0xbfb8aa3b, v94
	v_mul_f32_e32 v90, 0xbfb8aa3b, v90
	v_mul_f32_e32 v95, 0xbfb8aa3b, v95
	v_mul_f32_e32 v91, 0xbfb8aa3b, v91
	v_exp_f32_e32 v92, v92
	v_exp_f32_e32 v88, v88
	v_exp_f32_e32 v93, v93
	v_exp_f32_e32 v89, v89
	v_exp_f32_e32 v94, v94
	v_exp_f32_e32 v90, v90
	v_exp_f32_e32 v95, v95
	v_exp_f32_e32 v91, v91
	v_add_f32_e32 v92, 1.0, v92
	v_add_f32_e32 v88, 1.0, v88
	v_add_f32_e32 v93, 1.0, v93
	v_add_f32_e32 v89, 1.0, v89
	v_add_f32_e32 v94, 1.0, v94
	v_add_f32_e32 v90, 1.0, v90
	v_add_f32_e32 v95, 1.0, v95
	v_add_f32_e32 v91, 1.0, v91
	v_rcp_f32_e32 v92, v92
	v_rcp_f32_e32 v96, v88
	v_rcp_f32_e32 v88, v93
	v_rcp_f32_e32 v93, v89
	v_rcp_f32_e32 v89, v94
	v_rcp_f32_e32 v94, v95
	v_rcp_f32_e32 v95, v90
	v_rcp_f32_e32 v91, v91
	v_cvt_pk_bf16_f32 v88, v92, v88
	v_cvt_pk_bf16_f32 v89, v89, v94
	v_cvt_pk_bf16_f32 v90, v96, v93
	v_cvt_pk_bf16_f32 v91, v95, v91
	global_store_dwordx4 v[104:105], v[88:91], off
	global_load_dwordx4 v[88:91], v[144:145], off offset:512
	s_nop 0
	global_load_dwordx4 v[92:95], v[144:145], off offset:528
	s_waitcnt vmcnt(0)
	v_add_f32_e32 v84, v84, v88
	v_add_f32_e32 v80, v80, v92
	v_add_f32_e32 v85, v85, v89
	v_add_f32_e32 v81, v81, v93
	v_add_f32_e32 v86, v86, v90
	v_add_f32_e32 v82, v82, v94
	v_add_f32_e32 v87, v87, v91
	v_add_f32_e32 v83, v83, v95
	v_mul_f32_e32 v84, 0xbfb8aa3b, v84
	v_mul_f32_e32 v80, 0xbfb8aa3b, v80
	v_mul_f32_e32 v85, 0xbfb8aa3b, v85
	v_mul_f32_e32 v81, 0xbfb8aa3b, v81
	v_mul_f32_e32 v86, 0xbfb8aa3b, v86
	v_mul_f32_e32 v82, 0xbfb8aa3b, v82
	v_mul_f32_e32 v87, 0xbfb8aa3b, v87
	v_mul_f32_e32 v83, 0xbfb8aa3b, v83
	v_exp_f32_e32 v84, v84
	v_exp_f32_e32 v80, v80
	v_exp_f32_e32 v85, v85
	v_exp_f32_e32 v81, v81
	v_exp_f32_e32 v86, v86
	v_exp_f32_e32 v82, v82
	v_exp_f32_e32 v87, v87
	v_exp_f32_e32 v83, v83
	v_add_f32_e32 v84, 1.0, v84
	v_add_f32_e32 v80, 1.0, v80
	v_add_f32_e32 v85, 1.0, v85
	v_add_f32_e32 v81, 1.0, v81
	v_add_f32_e32 v86, 1.0, v86
	v_add_f32_e32 v82, 1.0, v82
	v_add_f32_e32 v87, 1.0, v87
	v_add_f32_e32 v83, 1.0, v83
	v_rcp_f32_e32 v84, v84
	v_rcp_f32_e32 v88, v80
	v_rcp_f32_e32 v80, v85
	v_rcp_f32_e32 v85, v81
	v_rcp_f32_e32 v81, v86
	v_rcp_f32_e32 v86, v87
	v_rcp_f32_e32 v87, v82
	v_rcp_f32_e32 v83, v83
	v_cvt_pk_bf16_f32 v80, v84, v80
	v_cvt_pk_bf16_f32 v81, v81, v86
	v_cvt_pk_bf16_f32 v82, v88, v85
	v_cvt_pk_bf16_f32 v83, v87, v83
	global_store_dwordx4 v[104:105], v[80:83], off offset:256
	global_load_dwordx4 v[80:83], v[144:145], off
	s_nop 0
	global_load_dwordx4 v[84:87], v[144:145], off offset:16
	v_or_b32_e32 v88, 48, v148
	v_ashrrev_i32_e32 v89, 31, v88
	v_lshlrev_b64 v[88:89], 12, v[88:89]
	v_lshl_add_u64 v[88:89], s[6:7], 0, v[88:89]
	v_lshl_add_u64 v[88:89], v[88:89], 0, v[150:151]
	s_waitcnt vmcnt(0)
	v_add_f32_e32 v76, v76, v80
	v_add_f32_e32 v72, v72, v84
	v_add_f32_e32 v77, v77, v81
	v_add_f32_e32 v73, v73, v85
	v_add_f32_e32 v78, v78, v82
	v_add_f32_e32 v74, v74, v86
	v_add_f32_e32 v79, v79, v83
	v_add_f32_e32 v75, v75, v87
	v_mul_f32_e32 v76, 0xbfb8aa3b, v76
	v_mul_f32_e32 v72, 0xbfb8aa3b, v72
	v_mul_f32_e32 v77, 0xbfb8aa3b, v77
	v_mul_f32_e32 v73, 0xbfb8aa3b, v73
	v_mul_f32_e32 v78, 0xbfb8aa3b, v78
	v_mul_f32_e32 v74, 0xbfb8aa3b, v74
	v_mul_f32_e32 v79, 0xbfb8aa3b, v79
	v_mul_f32_e32 v75, 0xbfb8aa3b, v75
	v_exp_f32_e32 v76, v76
	v_exp_f32_e32 v72, v72
	v_exp_f32_e32 v77, v77
	v_exp_f32_e32 v73, v73
	v_exp_f32_e32 v78, v78
	v_exp_f32_e32 v74, v74
	v_exp_f32_e32 v79, v79
	v_exp_f32_e32 v75, v75
	v_add_f32_e32 v76, 1.0, v76
	v_add_f32_e32 v72, 1.0, v72
	v_add_f32_e32 v77, 1.0, v77
	v_add_f32_e32 v73, 1.0, v73
	v_add_f32_e32 v78, 1.0, v78
	v_add_f32_e32 v74, 1.0, v74
	v_add_f32_e32 v79, 1.0, v79
	v_add_f32_e32 v75, 1.0, v75
	v_rcp_f32_e32 v76, v76
	v_rcp_f32_e32 v80, v72
	v_rcp_f32_e32 v72, v77
	v_rcp_f32_e32 v77, v73
	v_rcp_f32_e32 v73, v78
	v_rcp_f32_e32 v78, v79
	v_rcp_f32_e32 v79, v74
	v_rcp_f32_e32 v75, v75
	v_cvt_pk_bf16_f32 v72, v76, v72
	v_cvt_pk_bf16_f32 v73, v73, v78
	v_cvt_pk_bf16_f32 v74, v80, v77
	v_cvt_pk_bf16_f32 v75, v79, v75
	global_store_dwordx4 v[88:89], v[72:75], off
	global_load_dwordx4 v[72:75], v[144:145], off offset:512
	s_nop 0
	global_load_dwordx4 v[76:79], v[144:145], off offset:528
	s_waitcnt vmcnt(0)
	v_add_f32_e32 v68, v68, v72
	v_add_f32_e32 v64, v64, v76
	v_add_f32_e32 v69, v69, v73
	v_add_f32_e32 v65, v65, v77
	v_add_f32_e32 v70, v70, v74
	v_add_f32_e32 v66, v66, v78
	v_add_f32_e32 v71, v71, v75
	v_add_f32_e32 v67, v67, v79
	v_mul_f32_e32 v68, 0xbfb8aa3b, v68
	v_mul_f32_e32 v64, 0xbfb8aa3b, v64
	v_mul_f32_e32 v69, 0xbfb8aa3b, v69
	v_mul_f32_e32 v65, 0xbfb8aa3b, v65
	v_mul_f32_e32 v70, 0xbfb8aa3b, v70
	v_mul_f32_e32 v66, 0xbfb8aa3b, v66
	v_mul_f32_e32 v71, 0xbfb8aa3b, v71
	v_mul_f32_e32 v67, 0xbfb8aa3b, v67
	v_exp_f32_e32 v68, v68
	v_exp_f32_e32 v64, v64
	v_exp_f32_e32 v69, v69
	v_exp_f32_e32 v65, v65
	v_exp_f32_e32 v70, v70
	v_exp_f32_e32 v66, v66
	v_exp_f32_e32 v71, v71
	v_exp_f32_e32 v67, v67
	v_add_f32_e32 v68, 1.0, v68
	v_add_f32_e32 v64, 1.0, v64
	v_add_f32_e32 v69, 1.0, v69
	v_add_f32_e32 v65, 1.0, v65
	v_add_f32_e32 v70, 1.0, v70
	v_add_f32_e32 v66, 1.0, v66
	v_add_f32_e32 v71, 1.0, v71
	v_add_f32_e32 v67, 1.0, v67
	v_rcp_f32_e32 v68, v68
	v_rcp_f32_e32 v72, v64
	v_rcp_f32_e32 v64, v69
	v_rcp_f32_e32 v69, v65
	v_rcp_f32_e32 v65, v70
	v_rcp_f32_e32 v70, v71
	v_rcp_f32_e32 v71, v66
	v_rcp_f32_e32 v67, v67
	v_cvt_pk_bf16_f32 v64, v68, v64
	v_cvt_pk_bf16_f32 v65, v65, v70
	v_cvt_pk_bf16_f32 v66, v72, v69
	v_cvt_pk_bf16_f32 v67, v71, v67
	global_store_dwordx4 v[88:89], v[64:67], off offset:256
	global_load_dwordx4 v[64:67], v[144:145], off
	s_nop 0
	global_load_dwordx4 v[68:71], v[144:145], off offset:16
	v_add_co_u32_e32 v72, vcc, s74, v146
	s_waitcnt vmcnt(0)
	v_add_f32_e32 v60, v60, v64
	v_add_f32_e32 v56, v56, v68
	v_add_f32_e32 v61, v61, v65
	v_add_f32_e32 v57, v57, v69
	v_add_f32_e32 v62, v62, v66
	v_add_f32_e32 v58, v58, v70
	v_add_f32_e32 v63, v63, v67
	v_add_f32_e32 v59, v59, v71
	v_mul_f32_e32 v60, 0xbfb8aa3b, v60
	v_mul_f32_e32 v56, 0xbfb8aa3b, v56
	v_mul_f32_e32 v61, 0xbfb8aa3b, v61
	v_mul_f32_e32 v57, 0xbfb8aa3b, v57
	v_mul_f32_e32 v62, 0xbfb8aa3b, v62
	v_mul_f32_e32 v58, 0xbfb8aa3b, v58
	v_mul_f32_e32 v63, 0xbfb8aa3b, v63
	v_mul_f32_e32 v59, 0xbfb8aa3b, v59
	v_exp_f32_e32 v60, v60
	v_exp_f32_e32 v56, v56
	v_exp_f32_e32 v61, v61
	v_exp_f32_e32 v57, v57
	v_exp_f32_e32 v62, v62
	v_exp_f32_e32 v58, v58
	v_exp_f32_e32 v63, v63
	v_exp_f32_e32 v59, v59
	v_add_f32_e32 v60, 1.0, v60
	v_add_f32_e32 v56, 1.0, v56
	v_add_f32_e32 v61, 1.0, v61
	v_add_f32_e32 v57, 1.0, v57
	v_add_f32_e32 v62, 1.0, v62
	v_add_f32_e32 v58, 1.0, v58
	v_add_f32_e32 v63, 1.0, v63
	v_add_f32_e32 v59, 1.0, v59
	v_rcp_f32_e32 v60, v60
	v_rcp_f32_e32 v64, v56
	v_rcp_f32_e32 v56, v61
	v_rcp_f32_e32 v61, v57
	v_rcp_f32_e32 v57, v62
	v_rcp_f32_e32 v62, v63
	v_rcp_f32_e32 v63, v58
	v_rcp_f32_e32 v59, v59
	v_addc_co_u32_e32 v73, vcc, 0, v147, vcc
	v_cvt_pk_bf16_f32 v56, v60, v56
	v_cvt_pk_bf16_f32 v57, v57, v62
	v_cvt_pk_bf16_f32 v58, v64, v61
	v_cvt_pk_bf16_f32 v59, v63, v59
	global_store_dwordx4 v[72:73], v[56:59], off
	global_load_dwordx4 v[56:59], v[144:145], off offset:512
	s_nop 0
	global_load_dwordx4 v[60:63], v[144:145], off offset:528
	v_lshl_add_u64 v[64:65], v[146:147], 0, s[14:15]
	s_waitcnt vmcnt(0)
	v_add_f32_e32 v52, v52, v56
	v_add_f32_e32 v48, v48, v60
	v_add_f32_e32 v53, v53, v57
	v_add_f32_e32 v49, v49, v61
	v_add_f32_e32 v54, v54, v58
	v_add_f32_e32 v50, v50, v62
	v_add_f32_e32 v55, v55, v59
	v_add_f32_e32 v51, v51, v63
	v_mul_f32_e32 v52, 0xbfb8aa3b, v52
	v_mul_f32_e32 v48, 0xbfb8aa3b, v48
	v_mul_f32_e32 v53, 0xbfb8aa3b, v53
	v_mul_f32_e32 v49, 0xbfb8aa3b, v49
	v_mul_f32_e32 v54, 0xbfb8aa3b, v54
	v_mul_f32_e32 v50, 0xbfb8aa3b, v50
	v_mul_f32_e32 v55, 0xbfb8aa3b, v55
	v_mul_f32_e32 v51, 0xbfb8aa3b, v51
	v_exp_f32_e32 v52, v52
	v_exp_f32_e32 v48, v48
	v_exp_f32_e32 v53, v53
	v_exp_f32_e32 v49, v49
	v_exp_f32_e32 v54, v54
	v_exp_f32_e32 v50, v50
	v_exp_f32_e32 v55, v55
	v_exp_f32_e32 v51, v51
	v_add_f32_e32 v52, 1.0, v52
	v_add_f32_e32 v48, 1.0, v48
	v_add_f32_e32 v53, 1.0, v53
	v_add_f32_e32 v49, 1.0, v49
	v_add_f32_e32 v54, 1.0, v54
	v_add_f32_e32 v50, 1.0, v50
	v_add_f32_e32 v55, 1.0, v55
	v_add_f32_e32 v51, 1.0, v51
	v_rcp_f32_e32 v52, v52
	v_rcp_f32_e32 v56, v48
	v_rcp_f32_e32 v48, v53
	v_rcp_f32_e32 v53, v49
	v_rcp_f32_e32 v49, v54
	v_rcp_f32_e32 v54, v55
	v_rcp_f32_e32 v55, v50
	v_rcp_f32_e32 v51, v51
	v_cvt_pk_bf16_f32 v48, v52, v48
	v_cvt_pk_bf16_f32 v49, v49, v54
	v_cvt_pk_bf16_f32 v50, v56, v53
	v_cvt_pk_bf16_f32 v51, v55, v51
	global_store_dwordx4 v[64:65], v[48:51], off offset:256
	global_load_dwordx4 v[48:51], v[144:145], off
	s_nop 0
	global_load_dwordx4 v[52:55], v[144:145], off offset:16
	v_add_co_u32_e32 v56, vcc, s75, v146
	s_waitcnt vmcnt(0)
	v_add_f32_e32 v44, v44, v48
	v_add_f32_e32 v40, v40, v52
	v_add_f32_e32 v45, v45, v49
	v_add_f32_e32 v41, v41, v53
	v_add_f32_e32 v46, v46, v50
	v_add_f32_e32 v42, v42, v54
	v_add_f32_e32 v47, v47, v51
	v_add_f32_e32 v43, v43, v55
	v_mul_f32_e32 v44, 0xbfb8aa3b, v44
	v_mul_f32_e32 v40, 0xbfb8aa3b, v40
	v_mul_f32_e32 v45, 0xbfb8aa3b, v45
	v_mul_f32_e32 v41, 0xbfb8aa3b, v41
	v_mul_f32_e32 v46, 0xbfb8aa3b, v46
	v_mul_f32_e32 v42, 0xbfb8aa3b, v42
	v_mul_f32_e32 v47, 0xbfb8aa3b, v47
	v_mul_f32_e32 v43, 0xbfb8aa3b, v43
	v_exp_f32_e32 v44, v44
	v_exp_f32_e32 v40, v40
	v_exp_f32_e32 v45, v45
	v_exp_f32_e32 v41, v41
	v_exp_f32_e32 v46, v46
	v_exp_f32_e32 v42, v42
	v_exp_f32_e32 v47, v47
	v_exp_f32_e32 v43, v43
	v_add_f32_e32 v44, 1.0, v44
	v_add_f32_e32 v40, 1.0, v40
	v_add_f32_e32 v45, 1.0, v45
	v_add_f32_e32 v41, 1.0, v41
	v_add_f32_e32 v46, 1.0, v46
	v_add_f32_e32 v42, 1.0, v42
	v_add_f32_e32 v47, 1.0, v47
	v_add_f32_e32 v43, 1.0, v43
	v_rcp_f32_e32 v44, v44
	v_rcp_f32_e32 v48, v40
	v_rcp_f32_e32 v40, v45
	v_rcp_f32_e32 v45, v41
	v_rcp_f32_e32 v41, v46
	v_rcp_f32_e32 v46, v47
	v_rcp_f32_e32 v47, v42
	v_rcp_f32_e32 v43, v43
	v_addc_co_u32_e32 v57, vcc, 0, v147, vcc
	v_cvt_pk_bf16_f32 v40, v44, v40
	v_cvt_pk_bf16_f32 v41, v41, v46
	v_cvt_pk_bf16_f32 v42, v48, v45
	v_cvt_pk_bf16_f32 v43, v47, v43
	global_store_dwordx4 v[56:57], v[40:43], off
	global_load_dwordx4 v[40:43], v[144:145], off offset:512
	s_nop 0
	global_load_dwordx4 v[44:47], v[144:145], off offset:528
	v_lshl_add_u64 v[48:49], v[146:147], 0, s[24:25]
	s_waitcnt vmcnt(0)
	v_add_f32_e32 v36, v36, v40
	v_add_f32_e32 v32, v32, v44
	v_add_f32_e32 v37, v37, v41
	v_add_f32_e32 v33, v33, v45
	v_add_f32_e32 v38, v38, v42
	v_add_f32_e32 v34, v34, v46
	v_add_f32_e32 v39, v39, v43
	v_add_f32_e32 v35, v35, v47
	v_mul_f32_e32 v36, 0xbfb8aa3b, v36
	v_mul_f32_e32 v32, 0xbfb8aa3b, v32
	v_mul_f32_e32 v37, 0xbfb8aa3b, v37
	v_mul_f32_e32 v33, 0xbfb8aa3b, v33
	v_mul_f32_e32 v38, 0xbfb8aa3b, v38
	v_mul_f32_e32 v34, 0xbfb8aa3b, v34
	v_mul_f32_e32 v39, 0xbfb8aa3b, v39
	v_mul_f32_e32 v35, 0xbfb8aa3b, v35
	v_exp_f32_e32 v36, v36
	v_exp_f32_e32 v32, v32
	v_exp_f32_e32 v37, v37
	v_exp_f32_e32 v33, v33
	v_exp_f32_e32 v38, v38
	v_exp_f32_e32 v34, v34
	v_exp_f32_e32 v39, v39
	v_exp_f32_e32 v35, v35
	v_add_f32_e32 v36, 1.0, v36
	v_add_f32_e32 v32, 1.0, v32
	v_add_f32_e32 v37, 1.0, v37
	v_add_f32_e32 v33, 1.0, v33
	v_add_f32_e32 v38, 1.0, v38
	v_add_f32_e32 v34, 1.0, v34
	v_add_f32_e32 v39, 1.0, v39
	v_add_f32_e32 v35, 1.0, v35
	v_rcp_f32_e32 v36, v36
	v_rcp_f32_e32 v40, v32
	v_rcp_f32_e32 v32, v37
	v_rcp_f32_e32 v37, v33
	v_rcp_f32_e32 v33, v38
	v_rcp_f32_e32 v38, v39
	v_rcp_f32_e32 v39, v34
	v_rcp_f32_e32 v35, v35
	v_cvt_pk_bf16_f32 v32, v36, v32
	v_cvt_pk_bf16_f32 v33, v33, v38
	v_cvt_pk_bf16_f32 v34, v40, v37
	v_cvt_pk_bf16_f32 v35, v39, v35
	global_store_dwordx4 v[48:49], v[32:35], off offset:256
	global_load_dwordx4 v[32:35], v[144:145], off
	s_nop 0
	global_load_dwordx4 v[36:39], v[144:145], off offset:16
	v_add_co_u32_e32 v40, vcc, s76, v146
	s_waitcnt vmcnt(0)
	v_add_f32_e32 v28, v28, v32
	v_add_f32_e32 v24, v24, v36
	v_add_f32_e32 v29, v29, v33
	v_add_f32_e32 v25, v25, v37
	v_add_f32_e32 v30, v30, v34
	v_add_f32_e32 v26, v26, v38
	v_add_f32_e32 v31, v31, v35
	v_add_f32_e32 v27, v27, v39
	v_mul_f32_e32 v28, 0xbfb8aa3b, v28
	v_mul_f32_e32 v24, 0xbfb8aa3b, v24
	v_mul_f32_e32 v29, 0xbfb8aa3b, v29
	v_mul_f32_e32 v25, 0xbfb8aa3b, v25
	v_mul_f32_e32 v30, 0xbfb8aa3b, v30
	v_mul_f32_e32 v26, 0xbfb8aa3b, v26
	v_mul_f32_e32 v31, 0xbfb8aa3b, v31
	v_mul_f32_e32 v27, 0xbfb8aa3b, v27
	v_exp_f32_e32 v28, v28
	v_exp_f32_e32 v24, v24
	v_exp_f32_e32 v29, v29
	v_exp_f32_e32 v25, v25
	v_exp_f32_e32 v30, v30
	v_exp_f32_e32 v26, v26
	v_exp_f32_e32 v31, v31
	v_exp_f32_e32 v27, v27
	v_add_f32_e32 v28, 1.0, v28
	v_add_f32_e32 v24, 1.0, v24
	v_add_f32_e32 v29, 1.0, v29
	v_add_f32_e32 v25, 1.0, v25
	v_add_f32_e32 v30, 1.0, v30
	v_add_f32_e32 v26, 1.0, v26
	v_add_f32_e32 v31, 1.0, v31
	v_add_f32_e32 v27, 1.0, v27
	v_rcp_f32_e32 v28, v28
	v_rcp_f32_e32 v32, v24
	v_rcp_f32_e32 v24, v29
	v_rcp_f32_e32 v29, v25
	v_rcp_f32_e32 v25, v30
	v_rcp_f32_e32 v30, v31
	v_rcp_f32_e32 v31, v26
	v_rcp_f32_e32 v27, v27
	v_addc_co_u32_e32 v41, vcc, 0, v147, vcc
	v_cvt_pk_bf16_f32 v24, v28, v24
	v_cvt_pk_bf16_f32 v25, v25, v30
	v_cvt_pk_bf16_f32 v26, v32, v29
	v_cvt_pk_bf16_f32 v27, v31, v27
	global_store_dwordx4 v[40:41], v[24:27], off
	global_load_dwordx4 v[24:27], v[144:145], off offset:512
	s_nop 0
	global_load_dwordx4 v[28:31], v[144:145], off offset:528
	v_lshl_add_u64 v[32:33], v[146:147], 0, s[40:41]
	s_waitcnt vmcnt(0)
	v_add_f32_e32 v20, v20, v24
	v_add_f32_e32 v16, v16, v28
	v_add_f32_e32 v21, v21, v25
	v_add_f32_e32 v17, v17, v29
	v_add_f32_e32 v22, v22, v26
	v_add_f32_e32 v18, v18, v30
	v_add_f32_e32 v23, v23, v27
	v_add_f32_e32 v19, v19, v31
	v_mul_f32_e32 v20, 0xbfb8aa3b, v20
	v_mul_f32_e32 v16, 0xbfb8aa3b, v16
	v_mul_f32_e32 v21, 0xbfb8aa3b, v21
	v_mul_f32_e32 v17, 0xbfb8aa3b, v17
	v_mul_f32_e32 v22, 0xbfb8aa3b, v22
	v_mul_f32_e32 v18, 0xbfb8aa3b, v18
	v_mul_f32_e32 v23, 0xbfb8aa3b, v23
	v_mul_f32_e32 v19, 0xbfb8aa3b, v19
	v_exp_f32_e32 v20, v20
	v_exp_f32_e32 v16, v16
	v_exp_f32_e32 v21, v21
	v_exp_f32_e32 v17, v17
	v_exp_f32_e32 v22, v22
	v_exp_f32_e32 v18, v18
	v_exp_f32_e32 v23, v23
	v_exp_f32_e32 v19, v19
	v_add_f32_e32 v20, 1.0, v20
	v_add_f32_e32 v16, 1.0, v16
	v_add_f32_e32 v21, 1.0, v21
	v_add_f32_e32 v17, 1.0, v17
	v_add_f32_e32 v22, 1.0, v22
	v_add_f32_e32 v18, 1.0, v18
	v_add_f32_e32 v23, 1.0, v23
	v_add_f32_e32 v19, 1.0, v19
	v_rcp_f32_e32 v20, v20
	v_rcp_f32_e32 v24, v16
	v_rcp_f32_e32 v16, v21
	v_rcp_f32_e32 v21, v17
	v_rcp_f32_e32 v17, v22
	v_rcp_f32_e32 v22, v23
	v_rcp_f32_e32 v23, v18
	v_rcp_f32_e32 v19, v19
	v_cvt_pk_bf16_f32 v16, v20, v16
	v_cvt_pk_bf16_f32 v17, v17, v22
	v_cvt_pk_bf16_f32 v18, v24, v21
	v_cvt_pk_bf16_f32 v19, v23, v19
	global_store_dwordx4 v[32:33], v[16:19], off offset:256
	global_load_dwordx4 v[16:19], v[144:145], off
	s_nop 0
	global_load_dwordx4 v[20:23], v[144:145], off offset:16
	v_add_co_u32_e32 v24, vcc, s77, v146
	s_waitcnt vmcnt(0)
	v_add_f32_e32 v12, v12, v16
	v_add_f32_e32 v8, v8, v20
	v_add_f32_e32 v13, v13, v17
	v_add_f32_e32 v9, v9, v21
	v_add_f32_e32 v14, v14, v18
	v_add_f32_e32 v10, v10, v22
	v_add_f32_e32 v15, v15, v19
	v_add_f32_e32 v11, v11, v23
	v_mul_f32_e32 v12, 0xbfb8aa3b, v12
	v_mul_f32_e32 v8, 0xbfb8aa3b, v8
	v_mul_f32_e32 v13, 0xbfb8aa3b, v13
	v_mul_f32_e32 v9, 0xbfb8aa3b, v9
	v_mul_f32_e32 v14, 0xbfb8aa3b, v14
	v_mul_f32_e32 v10, 0xbfb8aa3b, v10
	v_mul_f32_e32 v15, 0xbfb8aa3b, v15
	v_mul_f32_e32 v11, 0xbfb8aa3b, v11
	v_exp_f32_e32 v12, v12
	v_exp_f32_e32 v8, v8
	v_exp_f32_e32 v13, v13
	v_exp_f32_e32 v9, v9
	v_exp_f32_e32 v14, v14
	v_exp_f32_e32 v10, v10
	v_exp_f32_e32 v15, v15
	v_exp_f32_e32 v11, v11
	v_add_f32_e32 v12, 1.0, v12
	v_add_f32_e32 v8, 1.0, v8
	v_add_f32_e32 v13, 1.0, v13
	v_add_f32_e32 v9, 1.0, v9
	v_add_f32_e32 v14, 1.0, v14
	v_add_f32_e32 v10, 1.0, v10
	v_add_f32_e32 v15, 1.0, v15
	v_add_f32_e32 v11, 1.0, v11
	v_rcp_f32_e32 v12, v12
	v_rcp_f32_e32 v16, v8
	v_rcp_f32_e32 v8, v13
	v_rcp_f32_e32 v13, v9
	v_rcp_f32_e32 v9, v14
	v_rcp_f32_e32 v14, v15
	v_rcp_f32_e32 v15, v10
	v_rcp_f32_e32 v11, v11
	v_addc_co_u32_e32 v25, vcc, 0, v147, vcc
	v_cvt_pk_bf16_f32 v8, v12, v8
	v_cvt_pk_bf16_f32 v9, v9, v14
	v_cvt_pk_bf16_f32 v10, v16, v13
	v_cvt_pk_bf16_f32 v11, v15, v11
	global_store_dwordx4 v[24:25], v[8:11], off
	global_load_dwordx4 v[8:11], v[144:145], off offset:512
	s_nop 0
	global_load_dwordx4 v[12:15], v[144:145], off offset:528
	s_and_b64 vcc, exec, s[4:5]
	v_lshl_add_u64 v[16:17], v[146:147], 0, s[46:47]
	s_waitcnt vmcnt(0)
	v_add_f32_e32 v4, v4, v8
	v_add_f32_e32 v0, v0, v12
	v_add_f32_e32 v5, v5, v9
	v_add_f32_e32 v1, v1, v13
	v_add_f32_e32 v6, v6, v10
	v_add_f32_e32 v2, v2, v14
	v_add_f32_e32 v7, v7, v11
	v_add_f32_e32 v3, v3, v15
	v_mul_f32_e32 v4, 0xbfb8aa3b, v4
	v_mul_f32_e32 v0, 0xbfb8aa3b, v0
	v_mul_f32_e32 v5, 0xbfb8aa3b, v5
	v_mul_f32_e32 v1, 0xbfb8aa3b, v1
	v_mul_f32_e32 v6, 0xbfb8aa3b, v6
	v_mul_f32_e32 v2, 0xbfb8aa3b, v2
	v_mul_f32_e32 v7, 0xbfb8aa3b, v7
	v_mul_f32_e32 v3, 0xbfb8aa3b, v3
	v_exp_f32_e32 v4, v4
	v_exp_f32_e32 v0, v0
	v_exp_f32_e32 v5, v5
	v_exp_f32_e32 v1, v1
	v_exp_f32_e32 v6, v6
	v_exp_f32_e32 v2, v2
	v_exp_f32_e32 v7, v7
	v_exp_f32_e32 v3, v3
	v_add_f32_e32 v4, 1.0, v4
	v_add_f32_e32 v0, 1.0, v0
	v_add_f32_e32 v5, 1.0, v5
	v_add_f32_e32 v1, 1.0, v1
	v_add_f32_e32 v6, 1.0, v6
	v_add_f32_e32 v2, 1.0, v2
	v_add_f32_e32 v7, 1.0, v7
	v_add_f32_e32 v3, 1.0, v3
	v_rcp_f32_e32 v4, v4
	v_rcp_f32_e32 v8, v0
	v_rcp_f32_e32 v0, v5
	v_rcp_f32_e32 v5, v1
	v_rcp_f32_e32 v1, v6
	v_rcp_f32_e32 v6, v7
	v_rcp_f32_e32 v7, v2
	v_rcp_f32_e32 v3, v3
	v_cvt_pk_bf16_f32 v0, v4, v0
	v_cvt_pk_bf16_f32 v1, v1, v6
	v_cvt_pk_bf16_f32 v2, v8, v5
	v_cvt_pk_bf16_f32 v3, v7, v3
	global_store_dwordx4 v[16:17], v[0:3], off offset:256
	s_cbranch_vccz .LBB0_566
	s_waitcnt vmcnt(0)
	v_readlane_b32 s78, v228, 33
	s_cmpk_gt_u32 s0, 0xff
	v_readlane_b32 s76, v228, 32
	v_readlane_b32 s79, v228, 34
	v_readlane_b32 s77, v228, 35
	s_cbranch_scc1 .LBB0_573
	s_barrier

.LBB0_591:
	ds_read_b128 v[144:147], v151
	ds_read_b128 v[156:159], v151 offset:1024
	ds_read_b128 v[160:163], v151 offset:2048
	ds_read_b128 v[164:167], v151 offset:3072
	s_add_u32 s52, s50, 0xfffe0080
	s_addc_u32 s53, s51, -1
	s_cmp_eq_u32 s68, 4
	s_cselect_b32 s55, s41, s53
	s_cselect_b32 s54, s64, s52
	s_cselect_b32 s53, s25, s67
	s_cselect_b32 s52, s65, s66
	v_lshl_add_u64 v[200:201], s[50:51], 0, v[136:137]
	s_add_i32 m0, s35, 0xc000
	ds_read_b128 v[168:171], v152
	ds_read_b128 v[172:175], v152 offset:1024
	ds_read_b128 v[176:179], v152 offset:2048
	ds_read_b128 v[180:183], v152 offset:3072
	ds_read_b128 v[184:187], v152 offset:4096
	ds_read_b128 v[188:191], v152 offset:5120
	ds_read_b128 v[192:195], v152 offset:6144
	ds_read_b128 v[196:199], v152 offset:7168
	global_load_lds_dwordx4 v[200:201], off
	s_add_i32 m0, s35, 0xe000
	v_lshl_add_u64 v[200:201], s[50:51], 0, v[138:139]
	global_load_lds_dwordx4 v[200:201], off
	s_waitcnt lgkmcnt(8)
	s_barrier
	s_waitcnt lgkmcnt(0)
	v_mfma_f32_16x16x32_bf16 v[124:127], v[144:147], v[168:171], v[124:127]
	v_mfma_f32_16x16x32_bf16 v[120:123], v[160:163], v[168:171], v[120:123]
	v_mfma_f32_16x16x32_bf16 v[108:111], v[144:147], v[176:179], v[108:111]
	v_mfma_f32_16x16x32_bf16 v[104:107], v[160:163], v[176:179], v[104:107]
	v_mfma_f32_16x16x32_bf16 v[92:95], v[144:147], v[184:187], v[92:95]
	v_mfma_f32_16x16x32_bf16 v[88:91], v[160:163], v[184:187], v[88:91]
	v_mfma_f32_16x16x32_bf16 v[76:79], v[144:147], v[192:195], v[76:79]
	v_mfma_f32_16x16x32_bf16 v[72:75], v[160:163], v[192:195], v[72:75]
	v_mfma_f32_16x16x32_bf16 v[124:127], v[156:159], v[172:175], v[124:127]
	v_mfma_f32_16x16x32_bf16 v[120:123], v[164:167], v[172:175], v[120:123]
	v_mfma_f32_16x16x32_bf16 v[108:111], v[156:159], v[180:183], v[108:111]
	v_mfma_f32_16x16x32_bf16 v[104:107], v[164:167], v[180:183], v[104:107]
	v_mfma_f32_16x16x32_bf16 v[92:95], v[156:159], v[188:191], v[92:95]
	v_mfma_f32_16x16x32_bf16 v[88:91], v[164:167], v[188:191], v[88:91]
	v_mfma_f32_16x16x32_bf16 v[76:79], v[156:159], v[196:199], v[76:79]
	v_mfma_f32_16x16x32_bf16 v[72:75], v[164:167], v[196:199], v[72:75]
	s_barrier
	s_add_i32 s69, s62, s1
	v_lshl_add_u64 v[216:217], s[52:53], 0, v[132:133]
	s_mov_b32 m0, s69
	ds_read_b128 v[200:203], v153
	ds_read_b128 v[204:207], v153 offset:1024
	ds_read_b128 v[208:211], v153 offset:2048
	ds_read_b128 v[212:215], v153 offset:3072
	global_load_lds_dwordx4 v[216:217], off
	s_add_i32 m0, s69, 0x2000
	v_lshl_add_u64 v[218:219], s[52:53], 0, v[128:129]
	global_load_lds_dwordx4 v[218:219], off
	s_barrier
	s_waitcnt lgkmcnt(0)
	v_mfma_f32_16x16x32_bf16 v[116:119], v[200:203], v[168:171], v[116:119]
	v_mfma_f32_16x16x32_bf16 v[112:115], v[208:211], v[168:171], v[112:115]
	v_mfma_f32_16x16x32_bf16 v[100:103], v[200:203], v[176:179], v[100:103]
	v_mfma_f32_16x16x32_bf16 v[96:99], v[208:211], v[176:179], v[96:99]
	v_mfma_f32_16x16x32_bf16 v[84:87], v[200:203], v[184:187], v[84:87]
	v_mfma_f32_16x16x32_bf16 v[80:83], v[208:211], v[184:187], v[80:83]
	v_mfma_f32_16x16x32_bf16 v[68:71], v[200:203], v[192:195], v[68:71]
	v_mfma_f32_16x16x32_bf16 v[64:67], v[208:211], v[192:195], v[64:67]
	v_mfma_f32_16x16x32_bf16 v[116:119], v[204:207], v[172:175], v[116:119]
	v_mfma_f32_16x16x32_bf16 v[112:115], v[212:215], v[172:175], v[112:115]
	v_mfma_f32_16x16x32_bf16 v[100:103], v[204:207], v[180:183], v[100:103]
	v_mfma_f32_16x16x32_bf16 v[96:99], v[212:215], v[180:183], v[96:99]
	v_mfma_f32_16x16x32_bf16 v[84:87], v[204:207], v[188:191], v[84:87]
	v_mfma_f32_16x16x32_bf16 v[80:83], v[212:215], v[188:191], v[80:83]
	v_mfma_f32_16x16x32_bf16 v[68:71], v[204:207], v[196:199], v[68:71]
	v_mfma_f32_16x16x32_bf16 v[64:67], v[212:215], v[196:199], v[64:67]
	s_mov_b32 m0, s35
	v_lshl_add_u64 v[220:221], s[54:55], 0, v[134:135]
	s_barrier
	ds_read_b128 v[168:171], v152 offset:16384
	ds_read_b128 v[172:175], v152 offset:17408
	ds_read_b128 v[176:179], v152 offset:18432
	ds_read_b128 v[180:183], v152 offset:19456
	ds_read_b128 v[184:187], v152 offset:20480
	ds_read_b128 v[188:191], v152 offset:21504
	ds_read_b128 v[192:195], v152 offset:22528
	ds_read_b128 v[196:199], v152 offset:23552
	global_load_lds_dwordx4 v[220:221], off
	s_mov_b32 m0, s49
	v_lshl_add_u64 v[222:223], s[54:55], 0, v[130:131]
	global_load_lds_dwordx4 v[222:223], off
	s_barrier
	s_waitcnt lgkmcnt(0)
	v_mfma_f32_16x16x32_bf16 v[60:63], v[144:147], v[168:171], v[60:63]
	v_mfma_f32_16x16x32_bf16 v[56:59], v[160:163], v[168:171], v[56:59]
	v_mfma_f32_16x16x32_bf16 v[44:47], v[144:147], v[176:179], v[44:47]
	v_mfma_f32_16x16x32_bf16 v[40:43], v[160:163], v[176:179], v[40:43]
	v_mfma_f32_16x16x32_bf16 v[28:31], v[144:147], v[184:187], v[28:31]
	v_mfma_f32_16x16x32_bf16 v[24:27], v[160:163], v[184:187], v[24:27]
	v_mfma_f32_16x16x32_bf16 v[12:15], v[144:147], v[192:195], v[12:15]
	v_mfma_f32_16x16x32_bf16 v[8:11], v[160:163], v[192:195], v[8:11]
	v_mfma_f32_16x16x32_bf16 v[60:63], v[156:159], v[172:175], v[60:63]
	v_mfma_f32_16x16x32_bf16 v[56:59], v[164:167], v[172:175], v[56:59]
	v_mfma_f32_16x16x32_bf16 v[44:47], v[156:159], v[180:183], v[44:47]
	v_mfma_f32_16x16x32_bf16 v[40:43], v[164:167], v[180:183], v[40:43]
	v_mfma_f32_16x16x32_bf16 v[28:31], v[156:159], v[188:191], v[28:31]
	v_mfma_f32_16x16x32_bf16 v[24:27], v[164:167], v[188:191], v[24:27]
	v_mfma_f32_16x16x32_bf16 v[12:15], v[156:159], v[196:199], v[12:15]
	v_mfma_f32_16x16x32_bf16 v[8:11], v[164:167], v[196:199], v[8:11]
	s_barrier
	s_add_u32 s70, s52, 0x20000
	s_addc_u32 s71, s53, 0
	s_add_i32 s69, s72, s1
	s_mov_b32 m0, s69
	v_lshl_add_u64 v[144:145], s[70:71], 0, v[132:133]
	global_load_lds_dwordx4 v[144:145], off
	s_add_i32 m0, s69, 0x2000
	v_lshl_add_u64 v[144:145], s[70:71], 0, v[128:129]
	global_load_lds_dwordx4 v[144:145], off
	s_waitcnt vmcnt(6)
	s_barrier
	v_mfma_f32_16x16x32_bf16 v[52:55], v[200:203], v[168:171], v[52:55]
	v_mfma_f32_16x16x32_bf16 v[48:51], v[208:211], v[168:171], v[48:51]
	v_mfma_f32_16x16x32_bf16 v[36:39], v[200:203], v[176:179], v[36:39]
	v_mfma_f32_16x16x32_bf16 v[32:35], v[208:211], v[176:179], v[32:35]
	v_mfma_f32_16x16x32_bf16 v[20:23], v[200:203], v[184:187], v[20:23]
	v_mfma_f32_16x16x32_bf16 v[16:19], v[208:211], v[184:187], v[16:19]
	v_mfma_f32_16x16x32_bf16 v[4:7], v[200:203], v[192:195], v[4:7]
	v_mfma_f32_16x16x32_bf16 v[0:3], v[208:211], v[192:195], v[0:3]
	v_mfma_f32_16x16x32_bf16 v[52:55], v[204:207], v[172:175], v[52:55]
	v_mfma_f32_16x16x32_bf16 v[48:51], v[212:215], v[172:175], v[48:51]
	v_mfma_f32_16x16x32_bf16 v[36:39], v[204:207], v[180:183], v[36:39]
	v_mfma_f32_16x16x32_bf16 v[32:35], v[212:215], v[180:183], v[32:35]
	v_mfma_f32_16x16x32_bf16 v[20:23], v[204:207], v[188:191], v[20:23]
	v_mfma_f32_16x16x32_bf16 v[16:19], v[212:215], v[188:191], v[16:19]
	v_mfma_f32_16x16x32_bf16 v[4:7], v[204:207], v[196:199], v[4:7]
	v_mfma_f32_16x16x32_bf16 v[0:3], v[212:215], v[196:199], v[0:3]
	s_add_i32 s69, 0, 0x18000
	v_add_u32_e32 v164, s69, v149
	s_barrier
	ds_read_b128 v[144:147], v164
	ds_read_b128 v[156:159], v164 offset:1024
	ds_read_b128 v[160:163], v164 offset:2048
	ds_read_b128 v[164:167], v164 offset:3072
	s_add_u32 s54, s54, 0x20000
	s_addc_u32 s55, s55, 0
	s_mov_b32 m0, s56
	v_lshl_add_u64 v[200:201], s[54:55], 0, v[134:135]
	ds_read_b128 v[168:171], v152 offset:32768
	ds_read_b128 v[172:175], v152 offset:33792
	ds_read_b128 v[176:179], v152 offset:34816
	ds_read_b128 v[180:183], v152 offset:35840
	ds_read_b128 v[184:187], v152 offset:36864
	ds_read_b128 v[188:191], v152 offset:37888
	ds_read_b128 v[192:195], v152 offset:38912
	ds_read_b128 v[196:199], v152 offset:39936
	global_load_lds_dwordx4 v[200:201], off
	s_mov_b32 m0, s57
	v_lshl_add_u64 v[200:201], s[54:55], 0, v[130:131]
	global_load_lds_dwordx4 v[200:201], off
	s_waitcnt lgkmcnt(8)
	s_barrier
	s_waitcnt lgkmcnt(0)
	v_mfma_f32_16x16x32_bf16 v[124:127], v[144:147], v[168:171], v[124:127]
	v_mfma_f32_16x16x32_bf16 v[120:123], v[160:163], v[168:171], v[120:123]
	v_mfma_f32_16x16x32_bf16 v[108:111], v[144:147], v[176:179], v[108:111]
	v_mfma_f32_16x16x32_bf16 v[104:107], v[160:163], v[176:179], v[104:107]
	v_mfma_f32_16x16x32_bf16 v[92:95], v[144:147], v[184:187], v[92:95]
	v_mfma_f32_16x16x32_bf16 v[88:91], v[160:163], v[184:187], v[88:91]
	v_mfma_f32_16x16x32_bf16 v[76:79], v[144:147], v[192:195], v[76:79]
	v_mfma_f32_16x16x32_bf16 v[72:75], v[160:163], v[192:195], v[72:75]
	v_mfma_f32_16x16x32_bf16 v[124:127], v[156:159], v[172:175], v[124:127]
	v_mfma_f32_16x16x32_bf16 v[120:123], v[164:167], v[172:175], v[120:123]
	v_mfma_f32_16x16x32_bf16 v[108:111], v[156:159], v[180:183], v[108:111]
	v_mfma_f32_16x16x32_bf16 v[104:107], v[164:167], v[180:183], v[104:107]
	v_mfma_f32_16x16x32_bf16 v[92:95], v[156:159], v[188:191], v[92:95]
	v_mfma_f32_16x16x32_bf16 v[88:91], v[164:167], v[188:191], v[88:91]
	v_mfma_f32_16x16x32_bf16 v[76:79], v[156:159], v[196:199], v[76:79]
	v_mfma_f32_16x16x32_bf16 v[72:75], v[164:167], v[196:199], v[72:75]
	s_barrier
	s_add_i32 s54, s69, s1
	v_add_u32_e32 v212, s97, v149
	v_lshl_add_u64 v[216:217], v[216:217], 0, s[20:21]
	s_mov_b32 m0, s54
	ds_read_b128 v[200:203], v212
	ds_read_b128 v[204:207], v212 offset:1024
	ds_read_b128 v[208:211], v212 offset:2048
	ds_read_b128 v[212:215], v212 offset:3072
	global_load_lds_dwordx4 v[216:217], off
	s_add_i32 m0, s54, 0x2000
	v_lshl_add_u64 v[216:217], v[218:219], 0, s[20:21]
	global_load_lds_dwordx4 v[216:217], off
	s_barrier
	s_waitcnt lgkmcnt(0)
	v_mfma_f32_16x16x32_bf16 v[116:119], v[200:203], v[168:171], v[116:119]
	v_mfma_f32_16x16x32_bf16 v[112:115], v[208:211], v[168:171], v[112:115]
	v_mfma_f32_16x16x32_bf16 v[100:103], v[200:203], v[176:179], v[100:103]
	v_mfma_f32_16x16x32_bf16 v[96:99], v[208:211], v[176:179], v[96:99]
	v_mfma_f32_16x16x32_bf16 v[84:87], v[200:203], v[184:187], v[84:87]
	v_mfma_f32_16x16x32_bf16 v[80:83], v[208:211], v[184:187], v[80:83]
	v_mfma_f32_16x16x32_bf16 v[68:71], v[200:203], v[192:195], v[68:71]
	v_mfma_f32_16x16x32_bf16 v[64:67], v[208:211], v[192:195], v[64:67]
	v_mfma_f32_16x16x32_bf16 v[116:119], v[204:207], v[172:175], v[116:119]
	v_mfma_f32_16x16x32_bf16 v[112:115], v[212:215], v[172:175], v[112:115]
	v_mfma_f32_16x16x32_bf16 v[100:103], v[204:207], v[180:183], v[100:103]
	v_mfma_f32_16x16x32_bf16 v[96:99], v[212:215], v[180:183], v[96:99]
	v_mfma_f32_16x16x32_bf16 v[84:87], v[204:207], v[188:191], v[84:87]
	v_mfma_f32_16x16x32_bf16 v[80:83], v[212:215], v[188:191], v[80:83]
	v_mfma_f32_16x16x32_bf16 v[68:71], v[204:207], v[196:199], v[68:71]
	v_mfma_f32_16x16x32_bf16 v[64:67], v[212:215], v[196:199], v[64:67]
	s_mov_b32 m0, s59
	v_lshl_add_u64 v[216:217], v[220:221], 0, s[20:21]
	s_barrier
	ds_read_b128 v[168:171], v152 offset:49152
	ds_read_b128 v[172:175], v152 offset:50176
	ds_read_b128 v[176:179], v152 offset:51200
	ds_read_b128 v[180:183], v152 offset:52224
	ds_read_b128 v[184:187], v152 offset:53248
	ds_read_b128 v[188:191], v152 offset:54272
	ds_read_b128 v[192:195], v152 offset:55296
	ds_read_b128 v[196:199], v152 offset:56320
	global_load_lds_dwordx4 v[216:217], off
	s_mov_b32 m0, s60
	v_lshl_add_u64 v[216:217], v[222:223], 0, s[20:21]
	global_load_lds_dwordx4 v[216:217], off
	s_barrier
	s_waitcnt lgkmcnt(0)
	v_mfma_f32_16x16x32_bf16 v[60:63], v[144:147], v[168:171], v[60:63]
	v_mfma_f32_16x16x32_bf16 v[56:59], v[160:163], v[168:171], v[56:59]
	v_mfma_f32_16x16x32_bf16 v[44:47], v[144:147], v[176:179], v[44:47]
	v_mfma_f32_16x16x32_bf16 v[40:43], v[160:163], v[176:179], v[40:43]
	v_mfma_f32_16x16x32_bf16 v[28:31], v[144:147], v[184:187], v[28:31]
	v_mfma_f32_16x16x32_bf16 v[24:27], v[160:163], v[184:187], v[24:27]
	v_mfma_f32_16x16x32_bf16 v[12:15], v[144:147], v[192:195], v[12:15]
	v_mfma_f32_16x16x32_bf16 v[8:11], v[160:163], v[192:195], v[8:11]
	v_mfma_f32_16x16x32_bf16 v[60:63], v[156:159], v[172:175], v[60:63]
	v_mfma_f32_16x16x32_bf16 v[56:59], v[164:167], v[172:175], v[56:59]
	v_mfma_f32_16x16x32_bf16 v[44:47], v[156:159], v[180:183], v[44:47]
	v_mfma_f32_16x16x32_bf16 v[40:43], v[164:167], v[180:183], v[40:43]
	v_mfma_f32_16x16x32_bf16 v[28:31], v[156:159], v[188:191], v[28:31]
	v_mfma_f32_16x16x32_bf16 v[24:27], v[164:167], v[188:191], v[24:27]
	v_mfma_f32_16x16x32_bf16 v[12:15], v[156:159], v[196:199], v[12:15]
	v_mfma_f32_16x16x32_bf16 v[8:11], v[164:167], v[196:199], v[8:11]
	s_barrier
	s_add_u32 s52, s52, 0x20080
	s_addc_u32 s53, s53, 0
	s_add_i32 s54, s97, s1
	s_mov_b32 m0, s54
	v_lshl_add_u64 v[144:145], s[52:53], 0, v[132:133]
	global_load_lds_dwordx4 v[144:145], off
	s_add_i32 m0, s54, 0x2000
	v_lshl_add_u64 v[144:145], s[52:53], 0, v[128:129]
	global_load_lds_dwordx4 v[144:145], off
	s_waitcnt vmcnt(6)
	s_barrier
	v_mfma_f32_16x16x32_bf16 v[52:55], v[200:203], v[168:171], v[52:55]
	v_mfma_f32_16x16x32_bf16 v[48:51], v[208:211], v[168:171], v[48:51]
	v_mfma_f32_16x16x32_bf16 v[36:39], v[200:203], v[176:179], v[36:39]
	v_mfma_f32_16x16x32_bf16 v[32:35], v[208:211], v[176:179], v[32:35]
	v_mfma_f32_16x16x32_bf16 v[20:23], v[200:203], v[184:187], v[20:23]
	v_mfma_f32_16x16x32_bf16 v[16:19], v[208:211], v[184:187], v[16:19]
	v_mfma_f32_16x16x32_bf16 v[4:7], v[200:203], v[192:195], v[4:7]
	v_mfma_f32_16x16x32_bf16 v[0:3], v[208:211], v[192:195], v[0:3]
	v_mfma_f32_16x16x32_bf16 v[52:55], v[204:207], v[172:175], v[52:55]
	v_mfma_f32_16x16x32_bf16 v[48:51], v[212:215], v[172:175], v[48:51]
	v_mfma_f32_16x16x32_bf16 v[36:39], v[204:207], v[180:183], v[36:39]
	v_mfma_f32_16x16x32_bf16 v[32:35], v[212:215], v[180:183], v[32:35]
	v_mfma_f32_16x16x32_bf16 v[20:23], v[204:207], v[188:191], v[20:23]
	v_mfma_f32_16x16x32_bf16 v[16:19], v[212:215], v[188:191], v[16:19]
	v_mfma_f32_16x16x32_bf16 v[4:7], v[204:207], v[196:199], v[4:7]
	v_mfma_f32_16x16x32_bf16 v[0:3], v[212:215], v[196:199], v[0:3]
	s_add_i32 s68, s68, 2
	s_add_u32 s50, s50, 0x100
	s_addc_u32 s51, s51, 0
	s_add_u32 s66, s66, 0x100
	s_addc_u32 s67, s67, 0
	s_cmp_gt_u32 s68, 5
	s_barrier
	s_cbranch_scc0 .LBB0_591
	v_lshl_add_u32 v146, s48, 8, v148
	v_lshl_or_b32 v144, s63, 8, v150
	v_ashrrev_i32_e32 v147, 31, v146
	v_lshlrev_b64 v[156:157], 12, v[146:147]
	v_ashrrev_i32_e32 v145, 31, v144
	v_lshl_add_u64 v[156:157], s[6:7], 0, v[156:157]
	v_lshlrev_b64 v[144:145], 1, v[144:145]
	v_lshl_add_u64 v[160:161], v[156:157], 0, v[144:145]
	global_load_dwordx4 v[156:159], v[160:161], off
	s_nop 0
	global_load_dwordx4 v[160:163], v[160:161], off offset:256
	v_or_b32_e32 v164, 16, v146
	v_lshlrev_b64 v[166:167], 11, v[146:147]
	v_ashrrev_i32_e32 v165, 31, v164
	v_lshl_add_u64 v[166:167], s[14:15], 0, v[166:167]
	v_lshlrev_b64 v[168:169], 12, v[164:165]
	v_lshl_add_u64 v[166:167], v[166:167], 0, v[144:145]
	v_lshl_add_u64 v[168:169], s[6:7], 0, v[168:169]
	v_lshl_add_u64 v[168:169], v[168:169], 0, v[144:145]
	s_and_b64 vcc, exec, s[4:5]
	s_mov_b32 s63, s24
	s_mov_b32 s48, s40
	s_mov_b64 s[52:53], s[46:47]
	s_mov_b64 s[50:51], s[44:45]
	s_waitcnt vmcnt(0)
	v_lshlrev_b32_e32 v170, 16, v156
	v_and_b32_e32 v171, 0xffff0000, v156
	v_lshlrev_b32_e32 v156, 16, v157
	v_and_b32_e32 v157, 0xffff0000, v157
	v_lshlrev_b32_e32 v172, 16, v158
	v_and_b32_e32 v173, 0xffff0000, v158
	v_lshlrev_b32_e32 v158, 16, v159
	v_and_b32_e32 v159, 0xffff0000, v159
	v_lshlrev_b32_e32 v174, 16, v160
	v_and_b32_e32 v175, 0xffff0000, v160
	v_lshlrev_b32_e32 v160, 16, v161
	v_and_b32_e32 v161, 0xffff0000, v161
	v_lshlrev_b32_e32 v176, 16, v162
	v_and_b32_e32 v177, 0xffff0000, v162
	v_lshlrev_b32_e32 v162, 16, v163
	v_and_b32_e32 v163, 0xffff0000, v163
	v_pk_mul_f32 v[126:127], v[126:127], v[156:157]
	v_pk_mul_f32 v[124:125], v[124:125], v[170:171]
	v_pk_mul_f32 v[122:123], v[122:123], v[158:159]
	v_pk_mul_f32 v[120:121], v[120:121], v[172:173]
	v_pk_mul_f32 v[156:157], v[118:119], v[160:161]
	v_pk_mul_f32 v[158:159], v[116:117], v[174:175]
	v_cvt_pk_bf16_f32 v116, v124, v125
	v_cvt_pk_bf16_f32 v117, v126, v127
	v_cvt_pk_bf16_f32 v118, v120, v121
	v_cvt_pk_bf16_f32 v119, v122, v123
	v_pk_mul_f32 v[120:121], v[114:115], v[162:163]
	v_pk_mul_f32 v[114:115], v[112:113], v[176:177]
	global_store_dwordx4 v[166:167], v[116:119], off
	v_cvt_pk_bf16_f32 v112, v158, v159
	v_cvt_pk_bf16_f32 v113, v156, v157
	v_cvt_pk_bf16_f32 v114, v114, v115
	v_cvt_pk_bf16_f32 v115, v120, v121
	global_load_dwordx4 v[116:119], v[168:169], off
	v_or_b32_e32 v120, 32, v146
	global_store_dwordx4 v[166:167], v[112:115], off offset:256
	global_load_dwordx4 v[112:115], v[168:169], off offset:256
	v_ashrrev_i32_e32 v121, 31, v120
	v_lshlrev_b64 v[122:123], 11, v[164:165]
	v_lshlrev_b64 v[124:125], 12, v[120:121]
	v_lshl_add_u64 v[122:123], s[14:15], 0, v[122:123]
	v_lshl_add_u64 v[124:125], s[6:7], 0, v[124:125]
	v_lshl_add_u64 v[122:123], v[122:123], 0, v[144:145]
	v_lshl_add_u64 v[124:125], v[124:125], 0, v[144:145]
	s_waitcnt vmcnt(0)
	v_lshlrev_b32_e32 v126, 16, v116
	v_and_b32_e32 v127, 0xffff0000, v116
	v_lshlrev_b32_e32 v116, 16, v117
	v_and_b32_e32 v117, 0xffff0000, v117
	v_lshlrev_b32_e32 v156, 16, v118
	v_and_b32_e32 v157, 0xffff0000, v118
	v_lshlrev_b32_e32 v118, 16, v119
	v_and_b32_e32 v119, 0xffff0000, v119
	v_lshlrev_b32_e32 v158, 16, v112
	v_and_b32_e32 v159, 0xffff0000, v112
	v_lshlrev_b32_e32 v112, 16, v113
	v_and_b32_e32 v113, 0xffff0000, v113
	v_lshlrev_b32_e32 v160, 16, v114
	v_and_b32_e32 v161, 0xffff0000, v114
	v_lshlrev_b32_e32 v114, 16, v115
	v_and_b32_e32 v115, 0xffff0000, v115
	v_pk_mul_f32 v[110:111], v[110:111], v[116:117]
	v_pk_mul_f32 v[108:109], v[108:109], v[126:127]
	v_pk_mul_f32 v[106:107], v[106:107], v[118:119]
	v_pk_mul_f32 v[104:105], v[104:105], v[156:157]
	v_pk_mul_f32 v[112:113], v[102:103], v[112:113]
	v_pk_mul_f32 v[116:117], v[100:101], v[158:159]
	v_cvt_pk_bf16_f32 v100, v108, v109
	v_cvt_pk_bf16_f32 v101, v110, v111
	v_cvt_pk_bf16_f32 v102, v104, v105
	v_cvt_pk_bf16_f32 v103, v106, v107
	v_pk_mul_f32 v[104:105], v[98:99], v[114:115]
	v_pk_mul_f32 v[98:99], v[96:97], v[160:161]
	global_store_dwordx4 v[122:123], v[100:103], off
	v_cvt_pk_bf16_f32 v96, v116, v117
	v_cvt_pk_bf16_f32 v97, v112, v113
	v_cvt_pk_bf16_f32 v98, v98, v99
	v_cvt_pk_bf16_f32 v99, v104, v105
	global_load_dwordx4 v[100:103], v[124:125], off
	v_or_b32_e32 v104, 48, v146
	global_store_dwordx4 v[122:123], v[96:99], off offset:256
	global_load_dwordx4 v[96:99], v[124:125], off offset:256
	v_ashrrev_i32_e32 v105, 31, v104
	v_lshlrev_b64 v[106:107], 11, v[120:121]
	v_lshlrev_b64 v[108:109], 12, v[104:105]
	v_lshl_add_u64 v[106:107], s[14:15], 0, v[106:107]
	v_lshl_add_u64 v[108:109], s[6:7], 0, v[108:109]
	v_lshl_add_u64 v[106:107], v[106:107], 0, v[144:145]
	v_lshl_add_u64 v[108:109], v[108:109], 0, v[144:145]
	s_waitcnt vmcnt(0)
	v_lshlrev_b32_e32 v110, 16, v100
	v_and_b32_e32 v111, 0xffff0000, v100
	v_lshlrev_b32_e32 v100, 16, v101
	v_and_b32_e32 v101, 0xffff0000, v101
	v_lshlrev_b32_e32 v112, 16, v102
	v_and_b32_e32 v113, 0xffff0000, v102
	v_lshlrev_b32_e32 v102, 16, v103
	v_and_b32_e32 v103, 0xffff0000, v103
	v_lshlrev_b32_e32 v114, 16, v96
	v_and_b32_e32 v115, 0xffff0000, v96
	v_lshlrev_b32_e32 v96, 16, v97
	v_and_b32_e32 v97, 0xffff0000, v97
	v_lshlrev_b32_e32 v116, 16, v98
	v_and_b32_e32 v117, 0xffff0000, v98
	v_lshlrev_b32_e32 v98, 16, v99
	v_and_b32_e32 v99, 0xffff0000, v99
	v_pk_mul_f32 v[94:95], v[94:95], v[100:101]
	v_pk_mul_f32 v[92:93], v[92:93], v[110:111]
	v_pk_mul_f32 v[90:91], v[90:91], v[102:103]
	v_pk_mul_f32 v[88:89], v[88:89], v[112:113]
	v_pk_mul_f32 v[96:97], v[86:87], v[96:97]
	v_pk_mul_f32 v[100:101], v[84:85], v[114:115]
	v_cvt_pk_bf16_f32 v84, v92, v93
	v_cvt_pk_bf16_f32 v85, v94, v95
	v_cvt_pk_bf16_f32 v86, v88, v89
	v_cvt_pk_bf16_f32 v87, v90, v91
	v_pk_mul_f32 v[88:89], v[82:83], v[98:99]
	v_pk_mul_f32 v[82:83], v[80:81], v[116:117]
	global_store_dwordx4 v[106:107], v[84:87], off
	v_cvt_pk_bf16_f32 v80, v100, v101
	v_cvt_pk_bf16_f32 v81, v96, v97
	v_cvt_pk_bf16_f32 v82, v82, v83
	v_cvt_pk_bf16_f32 v83, v88, v89
	global_load_dwordx4 v[84:87], v[108:109], off
	v_add_u32_e32 v88, 0x80, v146
	global_store_dwordx4 v[106:107], v[80:83], off offset:256
	global_load_dwordx4 v[80:83], v[108:109], off offset:256
	v_ashrrev_i32_e32 v89, 31, v88
	v_lshlrev_b64 v[90:91], 11, v[104:105]
	v_lshlrev_b64 v[92:93], 12, v[88:89]
	v_lshl_add_u64 v[90:91], s[14:15], 0, v[90:91]
	v_lshl_add_u64 v[92:93], s[6:7], 0, v[92:93]
	v_lshl_add_u64 v[90:91], v[90:91], 0, v[144:145]
	v_lshl_add_u64 v[92:93], v[92:93], 0, v[144:145]
	s_waitcnt vmcnt(0)
	v_lshlrev_b32_e32 v94, 16, v84
	v_and_b32_e32 v95, 0xffff0000, v84
	v_lshlrev_b32_e32 v84, 16, v85
	v_and_b32_e32 v85, 0xffff0000, v85
	v_lshlrev_b32_e32 v96, 16, v86
	v_and_b32_e32 v97, 0xffff0000, v86
	v_lshlrev_b32_e32 v86, 16, v87
	v_and_b32_e32 v87, 0xffff0000, v87
	v_lshlrev_b32_e32 v98, 16, v80
	v_and_b32_e32 v99, 0xffff0000, v80
	v_lshlrev_b32_e32 v80, 16, v81
	v_and_b32_e32 v81, 0xffff0000, v81
	v_lshlrev_b32_e32 v100, 16, v82
	v_and_b32_e32 v101, 0xffff0000, v82
	v_lshlrev_b32_e32 v82, 16, v83
	v_and_b32_e32 v83, 0xffff0000, v83
	v_pk_mul_f32 v[78:79], v[78:79], v[84:85]
	v_pk_mul_f32 v[76:77], v[76:77], v[94:95]
	v_pk_mul_f32 v[74:75], v[74:75], v[86:87]
	v_pk_mul_f32 v[72:73], v[72:73], v[96:97]
	v_pk_mul_f32 v[80:81], v[70:71], v[80:81]
	v_pk_mul_f32 v[84:85], v[68:69], v[98:99]
	v_cvt_pk_bf16_f32 v68, v76, v77
	v_cvt_pk_bf16_f32 v69, v78, v79
	v_cvt_pk_bf16_f32 v70, v72, v73
	v_cvt_pk_bf16_f32 v71, v74, v75
	v_pk_mul_f32 v[72:73], v[66:67], v[82:83]
	v_pk_mul_f32 v[66:67], v[64:65], v[100:101]
	global_store_dwordx4 v[90:91], v[68:71], off
	v_cvt_pk_bf16_f32 v64, v84, v85
	v_cvt_pk_bf16_f32 v65, v80, v81
	v_cvt_pk_bf16_f32 v66, v66, v67
	v_cvt_pk_bf16_f32 v67, v72, v73
	global_load_dwordx4 v[68:71], v[92:93], off
	v_add_u32_e32 v72, 0x90, v146
	global_store_dwordx4 v[90:91], v[64:67], off offset:256
	global_load_dwordx4 v[64:67], v[92:93], off offset:256
	v_ashrrev_i32_e32 v73, 31, v72
	v_lshlrev_b64 v[74:75], 11, v[88:89]
	v_lshlrev_b64 v[76:77], 12, v[72:73]
	v_lshl_add_u64 v[74:75], s[14:15], 0, v[74:75]
	v_lshl_add_u64 v[76:77], s[6:7], 0, v[76:77]
	v_lshl_add_u64 v[74:75], v[74:75], 0, v[144:145]
	v_lshl_add_u64 v[76:77], v[76:77], 0, v[144:145]
	s_waitcnt vmcnt(0)
	v_lshlrev_b32_e32 v78, 16, v68
	v_and_b32_e32 v79, 0xffff0000, v68
	v_lshlrev_b32_e32 v68, 16, v69
	v_and_b32_e32 v69, 0xffff0000, v69
	v_lshlrev_b32_e32 v80, 16, v70
	v_and_b32_e32 v81, 0xffff0000, v70
	v_lshlrev_b32_e32 v70, 16, v71
	v_and_b32_e32 v71, 0xffff0000, v71
	v_lshlrev_b32_e32 v82, 16, v64
	v_and_b32_e32 v83, 0xffff0000, v64
	v_lshlrev_b32_e32 v64, 16, v65
	v_and_b32_e32 v65, 0xffff0000, v65
	v_lshlrev_b32_e32 v84, 16, v66
	v_and_b32_e32 v85, 0xffff0000, v66
	v_lshlrev_b32_e32 v66, 16, v67
	v_and_b32_e32 v67, 0xffff0000, v67
	v_pk_mul_f32 v[62:63], v[62:63], v[68:69]
	v_pk_mul_f32 v[60:61], v[60:61], v[78:79]
	v_pk_mul_f32 v[58:59], v[58:59], v[70:71]
	v_pk_mul_f32 v[56:57], v[56:57], v[80:81]
	v_pk_mul_f32 v[64:65], v[54:55], v[64:65]
	v_pk_mul_f32 v[68:69], v[52:53], v[82:83]
	v_cvt_pk_bf16_f32 v52, v60, v61
	v_cvt_pk_bf16_f32 v53, v62, v63
	v_cvt_pk_bf16_f32 v54, v56, v57
	v_cvt_pk_bf16_f32 v55, v58, v59
	v_pk_mul_f32 v[56:57], v[50:51], v[66:67]
	v_pk_mul_f32 v[50:51], v[48:49], v[84:85]
	global_store_dwordx4 v[74:75], v[52:55], off
	v_cvt_pk_bf16_f32 v48, v68, v69
	v_cvt_pk_bf16_f32 v49, v64, v65
	v_cvt_pk_bf16_f32 v50, v50, v51
	v_cvt_pk_bf16_f32 v51, v56, v57
	global_load_dwordx4 v[52:55], v[76:77], off
	v_add_u32_e32 v56, 0xa0, v146
	global_store_dwordx4 v[74:75], v[48:51], off offset:256
	global_load_dwordx4 v[48:51], v[76:77], off offset:256
	v_ashrrev_i32_e32 v57, 31, v56
	v_lshlrev_b64 v[58:59], 11, v[72:73]
	v_lshlrev_b64 v[60:61], 12, v[56:57]
	v_lshl_add_u64 v[58:59], s[14:15], 0, v[58:59]
	v_lshl_add_u64 v[60:61], s[6:7], 0, v[60:61]
	v_lshl_add_u64 v[58:59], v[58:59], 0, v[144:145]
	v_lshl_add_u64 v[60:61], v[60:61], 0, v[144:145]
	s_waitcnt vmcnt(0)
	v_lshlrev_b32_e32 v62, 16, v52
	v_and_b32_e32 v63, 0xffff0000, v52
	v_lshlrev_b32_e32 v52, 16, v53
	v_and_b32_e32 v53, 0xffff0000, v53
	v_lshlrev_b32_e32 v64, 16, v54
	v_and_b32_e32 v65, 0xffff0000, v54
	v_lshlrev_b32_e32 v54, 16, v55
	v_and_b32_e32 v55, 0xffff0000, v55
	v_lshlrev_b32_e32 v66, 16, v48
	v_and_b32_e32 v67, 0xffff0000, v48
	v_lshlrev_b32_e32 v48, 16, v49
	v_and_b32_e32 v49, 0xffff0000, v49
	v_lshlrev_b32_e32 v68, 16, v50
	v_and_b32_e32 v69, 0xffff0000, v50
	v_lshlrev_b32_e32 v50, 16, v51
	v_and_b32_e32 v51, 0xffff0000, v51
	v_pk_mul_f32 v[46:47], v[46:47], v[52:53]
	v_pk_mul_f32 v[44:45], v[44:45], v[62:63]
	v_pk_mul_f32 v[42:43], v[42:43], v[54:55]
	v_pk_mul_f32 v[40:41], v[40:41], v[64:65]
	v_pk_mul_f32 v[48:49], v[38:39], v[48:49]
	v_pk_mul_f32 v[52:53], v[36:37], v[66:67]
	v_cvt_pk_bf16_f32 v36, v44, v45
	v_cvt_pk_bf16_f32 v37, v46, v47
	v_cvt_pk_bf16_f32 v38, v40, v41
	v_cvt_pk_bf16_f32 v39, v42, v43
	v_pk_mul_f32 v[40:41], v[34:35], v[50:51]
	v_pk_mul_f32 v[34:35], v[32:33], v[68:69]
	global_store_dwordx4 v[58:59], v[36:39], off
	v_cvt_pk_bf16_f32 v32, v52, v53
	v_cvt_pk_bf16_f32 v33, v48, v49
	v_cvt_pk_bf16_f32 v34, v34, v35
	v_cvt_pk_bf16_f32 v35, v40, v41
	global_load_dwordx4 v[36:39], v[60:61], off
	v_add_u32_e32 v40, 0xb0, v146
	global_store_dwordx4 v[58:59], v[32:35], off offset:256
	global_load_dwordx4 v[32:35], v[60:61], off offset:256
	v_ashrrev_i32_e32 v41, 31, v40
	v_lshlrev_b64 v[42:43], 11, v[56:57]
	v_lshlrev_b64 v[44:45], 12, v[40:41]
	v_lshl_add_u64 v[42:43], s[14:15], 0, v[42:43]
	v_lshl_add_u64 v[44:45], s[6:7], 0, v[44:45]
	v_lshl_add_u64 v[42:43], v[42:43], 0, v[144:145]
	v_lshl_add_u64 v[44:45], v[44:45], 0, v[144:145]
	s_waitcnt vmcnt(0)
	v_lshlrev_b32_e32 v46, 16, v36
	v_and_b32_e32 v47, 0xffff0000, v36
	v_lshlrev_b32_e32 v36, 16, v37
	v_and_b32_e32 v37, 0xffff0000, v37
	v_lshlrev_b32_e32 v48, 16, v38
	v_and_b32_e32 v49, 0xffff0000, v38
	v_lshlrev_b32_e32 v38, 16, v39
	v_and_b32_e32 v39, 0xffff0000, v39
	v_lshlrev_b32_e32 v50, 16, v32
	v_and_b32_e32 v51, 0xffff0000, v32
	v_lshlrev_b32_e32 v32, 16, v33
	v_and_b32_e32 v33, 0xffff0000, v33
	v_lshlrev_b32_e32 v52, 16, v34
	v_and_b32_e32 v53, 0xffff0000, v34
	v_lshlrev_b32_e32 v34, 16, v35
	v_and_b32_e32 v35, 0xffff0000, v35
	v_pk_mul_f32 v[30:31], v[30:31], v[36:37]
	v_pk_mul_f32 v[28:29], v[28:29], v[46:47]
	v_pk_mul_f32 v[26:27], v[26:27], v[38:39]
	v_pk_mul_f32 v[24:25], v[24:25], v[48:49]
	v_pk_mul_f32 v[32:33], v[22:23], v[32:33]
	v_pk_mul_f32 v[36:37], v[20:21], v[50:51]
	v_cvt_pk_bf16_f32 v20, v28, v29
	v_cvt_pk_bf16_f32 v21, v30, v31
	v_cvt_pk_bf16_f32 v22, v24, v25
	v_cvt_pk_bf16_f32 v23, v26, v27
	v_pk_mul_f32 v[24:25], v[18:19], v[34:35]
	v_pk_mul_f32 v[18:19], v[16:17], v[52:53]
	global_store_dwordx4 v[42:43], v[20:23], off
	v_cvt_pk_bf16_f32 v16, v36, v37
	v_cvt_pk_bf16_f32 v17, v32, v33
	v_cvt_pk_bf16_f32 v18, v18, v19
	v_cvt_pk_bf16_f32 v19, v24, v25
	global_load_dwordx4 v[20:23], v[44:45], off
	v_lshlrev_b64 v[24:25], 11, v[40:41]
	global_store_dwordx4 v[42:43], v[16:19], off offset:256
	global_load_dwordx4 v[16:19], v[44:45], off offset:256
	v_lshl_add_u64 v[24:25], s[14:15], 0, v[24:25]
	v_lshl_add_u64 v[24:25], v[24:25], 0, v[144:145]
	s_waitcnt vmcnt(0)
	v_lshlrev_b32_e32 v26, 16, v20
	v_and_b32_e32 v27, 0xffff0000, v20
	v_lshlrev_b32_e32 v20, 16, v21
	v_and_b32_e32 v21, 0xffff0000, v21
	v_lshlrev_b32_e32 v28, 16, v22
	v_and_b32_e32 v29, 0xffff0000, v22
	v_lshlrev_b32_e32 v22, 16, v23
	v_and_b32_e32 v23, 0xffff0000, v23
	v_lshlrev_b32_e32 v30, 16, v16
	v_and_b32_e32 v31, 0xffff0000, v16
	v_lshlrev_b32_e32 v16, 16, v17
	v_and_b32_e32 v17, 0xffff0000, v17
	v_lshlrev_b32_e32 v32, 16, v18
	v_and_b32_e32 v33, 0xffff0000, v18
	v_lshlrev_b32_e32 v18, 16, v19
	v_and_b32_e32 v19, 0xffff0000, v19
	v_pk_mul_f32 v[14:15], v[14:15], v[20:21]
	v_pk_mul_f32 v[12:13], v[12:13], v[26:27]
	v_pk_mul_f32 v[10:11], v[10:11], v[22:23]
	v_pk_mul_f32 v[8:9], v[8:9], v[28:29]
	v_pk_mul_f32 v[6:7], v[6:7], v[16:17]
	v_pk_mul_f32 v[4:5], v[4:5], v[30:31]
	v_pk_mul_f32 v[16:17], v[2:3], v[18:19]
	v_pk_mul_f32 v[18:19], v[0:1], v[32:33]
	v_cvt_pk_bf16_f32 v0, v12, v13
	v_cvt_pk_bf16_f32 v1, v14, v15
	v_cvt_pk_bf16_f32 v2, v8, v9
	v_cvt_pk_bf16_f32 v3, v10, v11
	v_cvt_pk_bf16_f32 v4, v4, v5
	v_cvt_pk_bf16_f32 v5, v6, v7
	v_cvt_pk_bf16_f32 v6, v18, v19
	v_cvt_pk_bf16_f32 v7, v16, v17
	global_store_dwordx4 v[24:25], v[0:3], off
	global_store_dwordx4 v[24:25], v[4:7], off offset:256
	s_cbranch_vccz .LBB0_588
	s_waitcnt vmcnt(0)
	s_cmpk_gt_u32 s0, 0xff
	s_cbranch_scc1 .LBB0_595
	s_barrier

.LBB0_603:
	ds_read_b128 v[144:147], v153
	ds_read_b128 v[158:161], v153 offset:1024
	ds_read_b128 v[162:165], v153 offset:2048
	ds_read_b128 v[166:169], v153 offset:3072
	s_add_u32 s50, s48, 0xfffc0080
	s_addc_u32 s51, s49, -1
	s_cmp_eq_u32 s66, 12
	s_cselect_b32 s53, s25, s51
	s_cselect_b32 s52, s62, s50
	s_cselect_b32 s51, s23, s65
	s_cselect_b32 s50, s63, s64
	v_lshl_add_u64 v[148:149], s[48:49], 0, v[136:137]
	s_add_i32 m0, s35, 0xc000
	ds_read_b128 v[170:173], v156
	ds_read_b128 v[174:177], v156 offset:1024
	ds_read_b128 v[178:181], v156 offset:2048
	ds_read_b128 v[182:185], v156 offset:3072
	ds_read_b128 v[186:189], v156 offset:4096
	ds_read_b128 v[190:193], v156 offset:5120
	ds_read_b128 v[194:197], v156 offset:6144
	ds_read_b128 v[198:201], v156 offset:7168
	global_load_lds_dwordx4 v[148:149], off
	s_add_i32 m0, s35, 0xe000
	v_lshl_add_u64 v[148:149], s[48:49], 0, v[138:139]
	global_load_lds_dwordx4 v[148:149], off
	s_waitcnt lgkmcnt(8)
	s_barrier
	s_waitcnt lgkmcnt(0)
	v_mfma_f32_16x16x32_bf16 v[124:127], v[144:147], v[170:173], v[124:127]
	v_mfma_f32_16x16x32_bf16 v[120:123], v[162:165], v[170:173], v[120:123]
	v_mfma_f32_16x16x32_bf16 v[108:111], v[144:147], v[178:181], v[108:111]
	v_mfma_f32_16x16x32_bf16 v[104:107], v[162:165], v[178:181], v[104:107]
	v_mfma_f32_16x16x32_bf16 v[92:95], v[144:147], v[186:189], v[92:95]
	v_mfma_f32_16x16x32_bf16 v[88:91], v[162:165], v[186:189], v[88:91]
	v_mfma_f32_16x16x32_bf16 v[76:79], v[144:147], v[194:197], v[76:79]
	v_mfma_f32_16x16x32_bf16 v[72:75], v[162:165], v[194:197], v[72:75]
	v_mfma_f32_16x16x32_bf16 v[124:127], v[158:161], v[174:177], v[124:127]
	v_mfma_f32_16x16x32_bf16 v[120:123], v[166:169], v[174:177], v[120:123]
	v_mfma_f32_16x16x32_bf16 v[108:111], v[158:161], v[182:185], v[108:111]
	v_mfma_f32_16x16x32_bf16 v[104:107], v[166:169], v[182:185], v[104:107]
	v_mfma_f32_16x16x32_bf16 v[92:95], v[158:161], v[190:193], v[92:95]
	v_mfma_f32_16x16x32_bf16 v[88:91], v[166:169], v[190:193], v[88:91]
	v_mfma_f32_16x16x32_bf16 v[76:79], v[158:161], v[198:201], v[76:79]
	v_mfma_f32_16x16x32_bf16 v[72:75], v[166:169], v[198:201], v[72:75]
	s_barrier
	s_add_i32 s67, s60, s1
	v_lshl_add_u64 v[148:149], s[50:51], 0, v[132:133]
	s_mov_b32 m0, s67
	ds_read_b128 v[202:205], v157
	ds_read_b128 v[206:209], v157 offset:1024
	ds_read_b128 v[210:213], v157 offset:2048
	ds_read_b128 v[214:217], v157 offset:3072
	global_load_lds_dwordx4 v[148:149], off
	s_add_i32 m0, s67, 0x2000
	v_lshl_add_u64 v[218:219], s[50:51], 0, v[128:129]
	global_load_lds_dwordx4 v[218:219], off
	s_barrier
	s_waitcnt lgkmcnt(0)
	v_mfma_f32_16x16x32_bf16 v[116:119], v[202:205], v[170:173], v[116:119]
	v_mfma_f32_16x16x32_bf16 v[112:115], v[210:213], v[170:173], v[112:115]
	v_mfma_f32_16x16x32_bf16 v[100:103], v[202:205], v[178:181], v[100:103]
	v_mfma_f32_16x16x32_bf16 v[96:99], v[210:213], v[178:181], v[96:99]
	v_mfma_f32_16x16x32_bf16 v[84:87], v[202:205], v[186:189], v[84:87]
	v_mfma_f32_16x16x32_bf16 v[80:83], v[210:213], v[186:189], v[80:83]
	v_mfma_f32_16x16x32_bf16 v[68:71], v[202:205], v[194:197], v[68:71]
	v_mfma_f32_16x16x32_bf16 v[64:67], v[210:213], v[194:197], v[64:67]
	v_mfma_f32_16x16x32_bf16 v[116:119], v[206:209], v[174:177], v[116:119]
	v_mfma_f32_16x16x32_bf16 v[112:115], v[214:217], v[174:177], v[112:115]
	v_mfma_f32_16x16x32_bf16 v[100:103], v[206:209], v[182:185], v[100:103]
	v_mfma_f32_16x16x32_bf16 v[96:99], v[214:217], v[182:185], v[96:99]
	v_mfma_f32_16x16x32_bf16 v[84:87], v[206:209], v[190:193], v[84:87]
	v_mfma_f32_16x16x32_bf16 v[80:83], v[214:217], v[190:193], v[80:83]
	v_mfma_f32_16x16x32_bf16 v[68:71], v[206:209], v[198:201], v[68:71]
	v_mfma_f32_16x16x32_bf16 v[64:67], v[214:217], v[198:201], v[64:67]
	s_mov_b32 m0, s35
	v_lshl_add_u64 v[220:221], s[52:53], 0, v[134:135]
	s_barrier
	ds_read_b128 v[170:173], v156 offset:16384
	ds_read_b128 v[174:177], v156 offset:17408
	ds_read_b128 v[178:181], v156 offset:18432
	ds_read_b128 v[182:185], v156 offset:19456
	ds_read_b128 v[186:189], v156 offset:20480
	ds_read_b128 v[190:193], v156 offset:21504
	ds_read_b128 v[194:197], v156 offset:22528
	ds_read_b128 v[198:201], v156 offset:23552
	global_load_lds_dwordx4 v[220:221], off
	s_mov_b32 m0, s47
	v_lshl_add_u64 v[222:223], s[52:53], 0, v[130:131]
	global_load_lds_dwordx4 v[222:223], off
	s_barrier
	s_waitcnt lgkmcnt(0)
	v_mfma_f32_16x16x32_bf16 v[60:63], v[144:147], v[170:173], v[60:63]
	v_mfma_f32_16x16x32_bf16 v[56:59], v[162:165], v[170:173], v[56:59]
	v_mfma_f32_16x16x32_bf16 v[44:47], v[144:147], v[178:181], v[44:47]
	v_mfma_f32_16x16x32_bf16 v[40:43], v[162:165], v[178:181], v[40:43]
	v_mfma_f32_16x16x32_bf16 v[28:31], v[144:147], v[186:189], v[28:31]
	v_mfma_f32_16x16x32_bf16 v[24:27], v[162:165], v[186:189], v[24:27]
	v_mfma_f32_16x16x32_bf16 v[12:15], v[144:147], v[194:197], v[12:15]
	v_mfma_f32_16x16x32_bf16 v[8:11], v[162:165], v[194:197], v[8:11]
	v_mfma_f32_16x16x32_bf16 v[60:63], v[158:161], v[174:177], v[60:63]
	v_mfma_f32_16x16x32_bf16 v[56:59], v[166:169], v[174:177], v[56:59]
	v_mfma_f32_16x16x32_bf16 v[44:47], v[158:161], v[182:185], v[44:47]
	v_mfma_f32_16x16x32_bf16 v[40:43], v[166:169], v[182:185], v[40:43]
	v_mfma_f32_16x16x32_bf16 v[28:31], v[158:161], v[190:193], v[28:31]
	v_mfma_f32_16x16x32_bf16 v[24:27], v[166:169], v[190:193], v[24:27]
	v_mfma_f32_16x16x32_bf16 v[12:15], v[158:161], v[198:201], v[12:15]
	v_mfma_f32_16x16x32_bf16 v[8:11], v[166:169], v[198:201], v[8:11]
	s_barrier
	s_add_u32 s68, s50, 0x40000
	s_addc_u32 s69, s51, 0
	s_add_i32 s67, s72, s1
	s_mov_b32 m0, s67
	v_lshl_add_u64 v[144:145], s[68:69], 0, v[132:133]
	global_load_lds_dwordx4 v[144:145], off
	s_add_i32 m0, s67, 0x2000
	v_lshl_add_u64 v[144:145], s[68:69], 0, v[128:129]
	global_load_lds_dwordx4 v[144:145], off
	s_waitcnt vmcnt(6)
	s_barrier
	v_mfma_f32_16x16x32_bf16 v[52:55], v[202:205], v[170:173], v[52:55]
	v_mfma_f32_16x16x32_bf16 v[48:51], v[210:213], v[170:173], v[48:51]
	v_mfma_f32_16x16x32_bf16 v[36:39], v[202:205], v[178:181], v[36:39]
	v_mfma_f32_16x16x32_bf16 v[32:35], v[210:213], v[178:181], v[32:35]
	v_mfma_f32_16x16x32_bf16 v[20:23], v[202:205], v[186:189], v[20:23]
	v_mfma_f32_16x16x32_bf16 v[16:19], v[210:213], v[186:189], v[16:19]
	v_mfma_f32_16x16x32_bf16 v[4:7], v[202:205], v[194:197], v[4:7]
	v_mfma_f32_16x16x32_bf16 v[0:3], v[210:213], v[194:197], v[0:3]
	v_mfma_f32_16x16x32_bf16 v[52:55], v[206:209], v[174:177], v[52:55]
	v_mfma_f32_16x16x32_bf16 v[48:51], v[214:217], v[174:177], v[48:51]
	v_mfma_f32_16x16x32_bf16 v[36:39], v[206:209], v[182:185], v[36:39]
	v_mfma_f32_16x16x32_bf16 v[32:35], v[214:217], v[182:185], v[32:35]
	v_mfma_f32_16x16x32_bf16 v[20:23], v[206:209], v[190:193], v[20:23]
	v_mfma_f32_16x16x32_bf16 v[16:19], v[214:217], v[190:193], v[16:19]
	v_mfma_f32_16x16x32_bf16 v[4:7], v[206:209], v[198:201], v[4:7]
	v_mfma_f32_16x16x32_bf16 v[0:3], v[214:217], v[198:201], v[0:3]
	s_add_i32 s67, 0, 0x18000
	v_add_u32_e32 v166, s67, v151
	s_barrier
	ds_read_b128 v[144:147], v166
	ds_read_b128 v[158:161], v166 offset:1024
	ds_read_b128 v[162:165], v166 offset:2048
	ds_read_b128 v[166:169], v166 offset:3072
	s_add_u32 s52, s52, 0x40000
	s_addc_u32 s53, s53, 0
	s_mov_b32 m0, s54
	v_lshl_add_u64 v[202:203], s[52:53], 0, v[134:135]
	ds_read_b128 v[170:173], v156 offset:32768
	ds_read_b128 v[174:177], v156 offset:33792
	ds_read_b128 v[178:181], v156 offset:34816
	ds_read_b128 v[182:185], v156 offset:35840
	ds_read_b128 v[186:189], v156 offset:36864
	ds_read_b128 v[190:193], v156 offset:37888
	ds_read_b128 v[194:197], v156 offset:38912
	ds_read_b128 v[198:201], v156 offset:39936
	global_load_lds_dwordx4 v[202:203], off
	s_mov_b32 m0, s55
	v_lshl_add_u64 v[202:203], s[52:53], 0, v[130:131]
	global_load_lds_dwordx4 v[202:203], off
	s_waitcnt lgkmcnt(8)
	s_barrier
	s_waitcnt lgkmcnt(0)
	v_mfma_f32_16x16x32_bf16 v[124:127], v[144:147], v[170:173], v[124:127]
	v_mfma_f32_16x16x32_bf16 v[120:123], v[162:165], v[170:173], v[120:123]
	v_mfma_f32_16x16x32_bf16 v[108:111], v[144:147], v[178:181], v[108:111]
	v_mfma_f32_16x16x32_bf16 v[104:107], v[162:165], v[178:181], v[104:107]
	v_mfma_f32_16x16x32_bf16 v[92:95], v[144:147], v[186:189], v[92:95]
	v_mfma_f32_16x16x32_bf16 v[88:91], v[162:165], v[186:189], v[88:91]
	v_mfma_f32_16x16x32_bf16 v[76:79], v[144:147], v[194:197], v[76:79]
	v_mfma_f32_16x16x32_bf16 v[72:75], v[162:165], v[194:197], v[72:75]
	v_mfma_f32_16x16x32_bf16 v[124:127], v[158:161], v[174:177], v[124:127]
	v_mfma_f32_16x16x32_bf16 v[120:123], v[166:169], v[174:177], v[120:123]
	v_mfma_f32_16x16x32_bf16 v[108:111], v[158:161], v[182:185], v[108:111]
	v_mfma_f32_16x16x32_bf16 v[104:107], v[166:169], v[182:185], v[104:107]
	v_mfma_f32_16x16x32_bf16 v[92:95], v[158:161], v[190:193], v[92:95]
	v_mfma_f32_16x16x32_bf16 v[88:91], v[166:169], v[190:193], v[88:91]
	v_mfma_f32_16x16x32_bf16 v[76:79], v[158:161], v[198:201], v[76:79]
	v_mfma_f32_16x16x32_bf16 v[72:75], v[166:169], v[198:201], v[72:75]
	s_barrier
	s_add_i32 s52, s67, s1
	v_add_u32_e32 v214, s97, v151
	v_lshl_add_u64 v[148:149], v[148:149], 0, s[20:21]
	s_mov_b32 m0, s52
	ds_read_b128 v[202:205], v214
	ds_read_b128 v[206:209], v214 offset:1024
	ds_read_b128 v[210:213], v214 offset:2048
	ds_read_b128 v[214:217], v214 offset:3072
	global_load_lds_dwordx4 v[148:149], off
	s_add_i32 m0, s52, 0x2000
	v_lshl_add_u64 v[148:149], v[218:219], 0, s[20:21]
	global_load_lds_dwordx4 v[148:149], off
	s_barrier
	s_waitcnt lgkmcnt(0)
	v_mfma_f32_16x16x32_bf16 v[116:119], v[202:205], v[170:173], v[116:119]
	v_mfma_f32_16x16x32_bf16 v[112:115], v[210:213], v[170:173], v[112:115]
	v_mfma_f32_16x16x32_bf16 v[100:103], v[202:205], v[178:181], v[100:103]
	v_mfma_f32_16x16x32_bf16 v[96:99], v[210:213], v[178:181], v[96:99]
	v_mfma_f32_16x16x32_bf16 v[84:87], v[202:205], v[186:189], v[84:87]
	v_mfma_f32_16x16x32_bf16 v[80:83], v[210:213], v[186:189], v[80:83]
	v_mfma_f32_16x16x32_bf16 v[68:71], v[202:205], v[194:197], v[68:71]
	v_mfma_f32_16x16x32_bf16 v[64:67], v[210:213], v[194:197], v[64:67]
	v_mfma_f32_16x16x32_bf16 v[116:119], v[206:209], v[174:177], v[116:119]
	v_mfma_f32_16x16x32_bf16 v[112:115], v[214:217], v[174:177], v[112:115]
	v_mfma_f32_16x16x32_bf16 v[100:103], v[206:209], v[182:185], v[100:103]
	v_mfma_f32_16x16x32_bf16 v[96:99], v[214:217], v[182:185], v[96:99]
	v_mfma_f32_16x16x32_bf16 v[84:87], v[206:209], v[190:193], v[84:87]
	v_mfma_f32_16x16x32_bf16 v[80:83], v[214:217], v[190:193], v[80:83]
	v_mfma_f32_16x16x32_bf16 v[68:71], v[206:209], v[198:201], v[68:71]
	v_mfma_f32_16x16x32_bf16 v[64:67], v[214:217], v[198:201], v[64:67]
	s_mov_b32 m0, s57
	v_lshl_add_u64 v[148:149], v[220:221], 0, s[20:21]
	s_barrier
	ds_read_b128 v[170:173], v156 offset:49152
	ds_read_b128 v[174:177], v156 offset:50176
	ds_read_b128 v[178:181], v156 offset:51200
	ds_read_b128 v[182:185], v156 offset:52224
	ds_read_b128 v[186:189], v156 offset:53248
	ds_read_b128 v[190:193], v156 offset:54272
	ds_read_b128 v[194:197], v156 offset:55296
	ds_read_b128 v[198:201], v156 offset:56320
	global_load_lds_dwordx4 v[148:149], off
	s_mov_b32 m0, s58
	v_lshl_add_u64 v[148:149], v[222:223], 0, s[20:21]
	global_load_lds_dwordx4 v[148:149], off
	s_barrier
	s_waitcnt lgkmcnt(0)
	v_mfma_f32_16x16x32_bf16 v[60:63], v[144:147], v[170:173], v[60:63]
	v_mfma_f32_16x16x32_bf16 v[56:59], v[162:165], v[170:173], v[56:59]
	v_mfma_f32_16x16x32_bf16 v[44:47], v[144:147], v[178:181], v[44:47]
	v_mfma_f32_16x16x32_bf16 v[40:43], v[162:165], v[178:181], v[40:43]
	v_mfma_f32_16x16x32_bf16 v[28:31], v[144:147], v[186:189], v[28:31]
	v_mfma_f32_16x16x32_bf16 v[24:27], v[162:165], v[186:189], v[24:27]
	v_mfma_f32_16x16x32_bf16 v[12:15], v[144:147], v[194:197], v[12:15]
	v_mfma_f32_16x16x32_bf16 v[8:11], v[162:165], v[194:197], v[8:11]
	v_mfma_f32_16x16x32_bf16 v[60:63], v[158:161], v[174:177], v[60:63]
	v_mfma_f32_16x16x32_bf16 v[56:59], v[166:169], v[174:177], v[56:59]
	v_mfma_f32_16x16x32_bf16 v[44:47], v[158:161], v[182:185], v[44:47]
	v_mfma_f32_16x16x32_bf16 v[40:43], v[166:169], v[182:185], v[40:43]
	v_mfma_f32_16x16x32_bf16 v[28:31], v[158:161], v[190:193], v[28:31]
	v_mfma_f32_16x16x32_bf16 v[24:27], v[166:169], v[190:193], v[24:27]
	v_mfma_f32_16x16x32_bf16 v[12:15], v[158:161], v[198:201], v[12:15]
	v_mfma_f32_16x16x32_bf16 v[8:11], v[166:169], v[198:201], v[8:11]
	s_barrier
	s_add_u32 s50, s50, 0x40080
	s_addc_u32 s51, s51, 0
	s_add_i32 s52, s97, s1
	s_mov_b32 m0, s52
	v_lshl_add_u64 v[144:145], s[50:51], 0, v[132:133]
	global_load_lds_dwordx4 v[144:145], off
	s_add_i32 m0, s52, 0x2000
	v_lshl_add_u64 v[144:145], s[50:51], 0, v[128:129]
	global_load_lds_dwordx4 v[144:145], off
	s_waitcnt vmcnt(6)
	s_barrier
	v_mfma_f32_16x16x32_bf16 v[52:55], v[202:205], v[170:173], v[52:55]
	v_mfma_f32_16x16x32_bf16 v[48:51], v[210:213], v[170:173], v[48:51]
	v_mfma_f32_16x16x32_bf16 v[36:39], v[202:205], v[178:181], v[36:39]
	v_mfma_f32_16x16x32_bf16 v[32:35], v[210:213], v[178:181], v[32:35]
	v_mfma_f32_16x16x32_bf16 v[20:23], v[202:205], v[186:189], v[20:23]
	v_mfma_f32_16x16x32_bf16 v[16:19], v[210:213], v[186:189], v[16:19]
	v_mfma_f32_16x16x32_bf16 v[4:7], v[202:205], v[194:197], v[4:7]
	v_mfma_f32_16x16x32_bf16 v[0:3], v[210:213], v[194:197], v[0:3]
	v_mfma_f32_16x16x32_bf16 v[52:55], v[206:209], v[174:177], v[52:55]
	v_mfma_f32_16x16x32_bf16 v[48:51], v[214:217], v[174:177], v[48:51]
	v_mfma_f32_16x16x32_bf16 v[36:39], v[206:209], v[182:185], v[36:39]
	v_mfma_f32_16x16x32_bf16 v[32:35], v[214:217], v[182:185], v[32:35]
	v_mfma_f32_16x16x32_bf16 v[20:23], v[206:209], v[190:193], v[20:23]
	v_mfma_f32_16x16x32_bf16 v[16:19], v[214:217], v[190:193], v[16:19]
	v_mfma_f32_16x16x32_bf16 v[4:7], v[206:209], v[198:201], v[4:7]
	v_mfma_f32_16x16x32_bf16 v[0:3], v[214:217], v[198:201], v[0:3]
	s_add_i32 s66, s66, 2
	s_add_u32 s48, s48, 0x100
	s_addc_u32 s49, s49, 0
	s_add_u32 s64, s64, 0x100
	s_addc_u32 s65, s65, 0
	s_cmp_gt_u32 s66, 13
	s_barrier
	s_cbranch_scc0 .LBB0_603
	v_lshl_add_u32 v146, s46, 8, v150
	v_lshl_or_b32 v144, s61, 8, v152
	v_ashrrev_i32_e32 v147, 31, v146
	v_lshlrev_b64 v[148:149], 12, v[146:147]
	v_ashrrev_i32_e32 v145, 31, v144
	v_lshl_add_u64 v[148:149], s[6:7], 0, v[148:149]
	v_lshlrev_b64 v[144:145], 1, v[144:145]
	v_lshlrev_b64 v[162:163], 11, v[146:147]
	v_lshl_add_u64 v[148:149], v[148:149], 0, v[144:145]
	v_lshl_add_u64 v[162:163], s[14:15], 0, v[162:163]
	global_load_dwordx4 v[158:161], v[148:149], off offset:2048
	v_lshl_add_u64 v[182:183], v[162:163], 0, v[144:145]
	global_load_dwordx4 v[162:165], v[182:183], off
	global_load_dwordx4 v[166:169], v[148:149], off offset:2304
	global_load_dwordx4 v[170:173], v[182:183], off offset:256
	v_or_b32_e32 v148, 16, v146
	v_ashrrev_i32_e32 v149, 31, v148
	v_lshlrev_b64 v[174:175], 12, v[148:149]
	v_lshlrev_b64 v[148:149], 11, v[148:149]
	v_lshl_add_u64 v[148:149], s[14:15], 0, v[148:149]
	v_lshl_add_u64 v[174:175], s[6:7], 0, v[174:175]
	v_lshl_add_u64 v[148:149], v[148:149], 0, v[144:145]
	v_lshl_add_u64 v[184:185], v[174:175], 0, v[144:145]
	global_load_dwordx4 v[174:177], v[148:149], off
	global_load_dwordx4 v[178:181], v[148:149], off offset:256
	s_and_b64 vcc, exec, s[4:5]
	s_mov_b32 s61, s22
	s_mov_b32 s46, s24
	s_mov_b64 s[50:51], s[44:45]
	s_mov_b64 s[48:49], s[40:41]
	s_waitcnt vmcnt(0)
	v_lshlrev_b32_e32 v190, 16, v162
	v_lshlrev_b32_e32 v186, 16, v158
	v_and_b32_e32 v187, 0xffff0000, v158
	v_lshlrev_b32_e32 v158, 16, v159
	v_and_b32_e32 v159, 0xffff0000, v159
	v_lshlrev_b32_e32 v188, 16, v160
	v_and_b32_e32 v189, 0xffff0000, v160
	v_lshlrev_b32_e32 v160, 16, v161
	v_and_b32_e32 v161, 0xffff0000, v161
	v_and_b32_e32 v191, 0xffff0000, v162
	v_lshlrev_b32_e32 v162, 16, v163
	v_and_b32_e32 v163, 0xffff0000, v163
	v_lshlrev_b32_e32 v192, 16, v164
	v_and_b32_e32 v193, 0xffff0000, v164
	v_lshlrev_b32_e32 v164, 16, v165
	v_and_b32_e32 v165, 0xffff0000, v165
	v_lshlrev_b32_e32 v194, 16, v166
	v_and_b32_e32 v195, 0xffff0000, v166
	v_lshlrev_b32_e32 v166, 16, v167
	v_and_b32_e32 v167, 0xffff0000, v167
	v_lshlrev_b32_e32 v196, 16, v168
	v_and_b32_e32 v197, 0xffff0000, v168
	v_lshlrev_b32_e32 v168, 16, v169
	v_and_b32_e32 v169, 0xffff0000, v169
	v_lshlrev_b32_e32 v198, 16, v170
	v_and_b32_e32 v199, 0xffff0000, v170
	v_lshlrev_b32_e32 v170, 16, v171
	v_and_b32_e32 v171, 0xffff0000, v171
	v_lshlrev_b32_e32 v200, 16, v172
	v_and_b32_e32 v201, 0xffff0000, v172
	v_lshlrev_b32_e32 v172, 16, v173
	v_and_b32_e32 v173, 0xffff0000, v173
	v_pk_fma_f32 v[126:127], v[126:127], v[158:159], v[162:163]
	v_pk_fma_f32 v[124:125], v[124:125], v[186:187], v[190:191]
	v_pk_fma_f32 v[122:123], v[122:123], v[160:161], v[164:165]
	v_pk_fma_f32 v[120:121], v[120:121], v[188:189], v[192:193]
	v_pk_fma_f32 v[158:159], v[118:119], v[166:167], v[170:171]
	v_pk_fma_f32 v[160:161], v[116:117], v[194:195], v[198:199]
	v_cvt_pk_bf16_f32 v116, v124, v125
	v_cvt_pk_bf16_f32 v117, v126, v127
	v_cvt_pk_bf16_f32 v118, v120, v121
	v_cvt_pk_bf16_f32 v119, v122, v123
	v_pk_fma_f32 v[120:121], v[114:115], v[168:169], v[172:173]
	v_pk_fma_f32 v[114:115], v[112:113], v[196:197], v[200:201]
	global_store_dwordx4 v[182:183], v[116:119], off
	v_cvt_pk_bf16_f32 v112, v160, v161
	v_cvt_pk_bf16_f32 v113, v158, v159
	v_cvt_pk_bf16_f32 v114, v114, v115
	v_cvt_pk_bf16_f32 v115, v120, v121
	global_load_dwordx4 v[116:119], v[184:185], off offset:2048
	v_lshlrev_b32_e32 v162, 16, v174
	global_store_dwordx4 v[182:183], v[112:115], off offset:256
	global_load_dwordx4 v[120:123], v[184:185], off offset:2304
	v_and_b32_e32 v163, 0xffff0000, v174
	v_or_b32_e32 v112, 32, v146
	v_ashrrev_i32_e32 v113, 31, v112
	v_lshlrev_b64 v[114:115], 12, v[112:113]
	v_lshlrev_b64 v[112:113], 11, v[112:113]
	v_lshlrev_b32_e32 v164, 16, v175
	v_and_b32_e32 v165, 0xffff0000, v175
	v_lshlrev_b32_e32 v166, 16, v176
	v_and_b32_e32 v167, 0xffff0000, v176
	v_lshlrev_b32_e32 v168, 16, v177
	v_and_b32_e32 v169, 0xffff0000, v177
	v_lshlrev_b32_e32 v170, 16, v178
	v_and_b32_e32 v171, 0xffff0000, v178
	v_lshlrev_b32_e32 v172, 16, v179
	v_and_b32_e32 v173, 0xffff0000, v179
	v_lshlrev_b32_e32 v174, 16, v180
	v_and_b32_e32 v175, 0xffff0000, v180
	v_lshlrev_b32_e32 v176, 16, v181
	v_and_b32_e32 v177, 0xffff0000, v181
	v_lshl_add_u64 v[112:113], s[14:15], 0, v[112:113]
	v_lshl_add_u64 v[114:115], s[6:7], 0, v[114:115]
	v_lshl_add_u64 v[112:113], v[112:113], 0, v[144:145]
	v_lshl_add_u64 v[114:115], v[114:115], 0, v[144:145]
	global_load_dwordx4 v[124:127], v[112:113], off
	global_load_dwordx4 v[158:161], v[112:113], off offset:256
	s_waitcnt vmcnt(0)
	v_lshlrev_b32_e32 v178, 16, v116
	v_and_b32_e32 v179, 0xffff0000, v116
	v_lshlrev_b32_e32 v116, 16, v117
	v_and_b32_e32 v117, 0xffff0000, v117
	v_lshlrev_b32_e32 v180, 16, v118
	v_and_b32_e32 v181, 0xffff0000, v118
	v_lshlrev_b32_e32 v118, 16, v119
	v_and_b32_e32 v119, 0xffff0000, v119
	v_lshlrev_b32_e32 v182, 16, v120
	v_and_b32_e32 v183, 0xffff0000, v120
	v_lshlrev_b32_e32 v120, 16, v121
	v_and_b32_e32 v121, 0xffff0000, v121
	v_lshlrev_b32_e32 v184, 16, v122
	v_and_b32_e32 v185, 0xffff0000, v122
	v_lshlrev_b32_e32 v122, 16, v123
	v_and_b32_e32 v123, 0xffff0000, v123
	v_pk_fma_f32 v[110:111], v[110:111], v[116:117], v[164:165]
	v_pk_fma_f32 v[108:109], v[108:109], v[178:179], v[162:163]
	v_pk_fma_f32 v[106:107], v[106:107], v[118:119], v[168:169]
	v_pk_fma_f32 v[104:105], v[104:105], v[180:181], v[166:167]
	v_pk_fma_f32 v[116:117], v[102:103], v[120:121], v[172:173]
	v_pk_fma_f32 v[118:119], v[100:101], v[182:183], v[170:171]
	v_cvt_pk_bf16_f32 v100, v108, v109
	v_cvt_pk_bf16_f32 v101, v110, v111
	v_cvt_pk_bf16_f32 v102, v104, v105
	v_cvt_pk_bf16_f32 v103, v106, v107
	v_pk_fma_f32 v[104:105], v[98:99], v[122:123], v[176:177]
	v_pk_fma_f32 v[98:99], v[96:97], v[184:185], v[174:175]
	global_store_dwordx4 v[148:149], v[100:103], off
	v_cvt_pk_bf16_f32 v96, v118, v119
	v_cvt_pk_bf16_f32 v97, v116, v117
	v_cvt_pk_bf16_f32 v98, v98, v99
	v_cvt_pk_bf16_f32 v99, v104, v105
	global_load_dwordx4 v[100:103], v[114:115], off offset:2048
	v_lshlrev_b32_e32 v118, 16, v124
	global_store_dwordx4 v[148:149], v[96:99], off offset:256
	global_load_dwordx4 v[104:107], v[114:115], off offset:2304
	v_and_b32_e32 v119, 0xffff0000, v124
	v_or_b32_e32 v96, 48, v146
	v_ashrrev_i32_e32 v97, 31, v96
	v_lshlrev_b64 v[98:99], 12, v[96:97]
	v_lshlrev_b64 v[96:97], 11, v[96:97]
	v_lshlrev_b32_e32 v120, 16, v125
	v_and_b32_e32 v121, 0xffff0000, v125
	v_lshlrev_b32_e32 v122, 16, v126
	v_and_b32_e32 v123, 0xffff0000, v126
	v_lshlrev_b32_e32 v124, 16, v127
	v_and_b32_e32 v125, 0xffff0000, v127
	v_lshl_add_u64 v[96:97], s[14:15], 0, v[96:97]
	v_lshlrev_b32_e32 v126, 16, v158
	v_and_b32_e32 v127, 0xffff0000, v158
	v_lshlrev_b32_e32 v148, 16, v159
	v_and_b32_e32 v149, 0xffff0000, v159
	v_lshlrev_b32_e32 v158, 16, v160
	v_and_b32_e32 v159, 0xffff0000, v160
	v_lshlrev_b32_e32 v160, 16, v161
	v_and_b32_e32 v161, 0xffff0000, v161
	v_lshl_add_u64 v[98:99], s[6:7], 0, v[98:99]
	v_lshl_add_u64 v[96:97], v[96:97], 0, v[144:145]
	v_lshl_add_u64 v[98:99], v[98:99], 0, v[144:145]
	global_load_dwordx4 v[108:111], v[96:97], off
	global_load_dwordx4 v[114:117], v[96:97], off offset:256
	s_waitcnt vmcnt(0)
	v_lshlrev_b32_e32 v162, 16, v100
	v_and_b32_e32 v163, 0xffff0000, v100
	v_lshlrev_b32_e32 v100, 16, v101
	v_and_b32_e32 v101, 0xffff0000, v101
	v_lshlrev_b32_e32 v164, 16, v102
	v_and_b32_e32 v165, 0xffff0000, v102
	v_lshlrev_b32_e32 v102, 16, v103
	v_and_b32_e32 v103, 0xffff0000, v103
	v_lshlrev_b32_e32 v166, 16, v104
	v_and_b32_e32 v167, 0xffff0000, v104
	v_lshlrev_b32_e32 v104, 16, v105
	v_and_b32_e32 v105, 0xffff0000, v105
	v_lshlrev_b32_e32 v168, 16, v106
	v_and_b32_e32 v169, 0xffff0000, v106
	v_lshlrev_b32_e32 v106, 16, v107
	v_and_b32_e32 v107, 0xffff0000, v107
	v_pk_fma_f32 v[94:95], v[94:95], v[100:101], v[120:121]
	v_pk_fma_f32 v[92:93], v[92:93], v[162:163], v[118:119]
	v_pk_fma_f32 v[90:91], v[90:91], v[102:103], v[124:125]
	v_pk_fma_f32 v[88:89], v[88:89], v[164:165], v[122:123]
	v_pk_fma_f32 v[100:101], v[86:87], v[104:105], v[148:149]
	v_pk_fma_f32 v[102:103], v[84:85], v[166:167], v[126:127]
	v_cvt_pk_bf16_f32 v84, v92, v93
	v_cvt_pk_bf16_f32 v85, v94, v95
	v_cvt_pk_bf16_f32 v86, v88, v89
	v_cvt_pk_bf16_f32 v87, v90, v91
	v_pk_fma_f32 v[88:89], v[82:83], v[106:107], v[160:161]
	v_pk_fma_f32 v[82:83], v[80:81], v[168:169], v[158:159]
	global_store_dwordx4 v[112:113], v[84:87], off
	v_cvt_pk_bf16_f32 v80, v102, v103
	v_cvt_pk_bf16_f32 v81, v100, v101
	v_cvt_pk_bf16_f32 v82, v82, v83
	v_cvt_pk_bf16_f32 v83, v88, v89
	global_load_dwordx4 v[84:87], v[98:99], off offset:2048
	v_lshlrev_b32_e32 v102, 16, v108
	global_store_dwordx4 v[112:113], v[80:83], off offset:256
	global_load_dwordx4 v[88:91], v[98:99], off offset:2304
	v_and_b32_e32 v103, 0xffff0000, v108
	v_add_u32_e32 v80, 0x80, v146
	v_ashrrev_i32_e32 v81, 31, v80
	v_lshlrev_b64 v[82:83], 12, v[80:81]
	v_lshlrev_b64 v[80:81], 11, v[80:81]
	v_lshlrev_b32_e32 v104, 16, v109
	v_and_b32_e32 v105, 0xffff0000, v109
	v_lshlrev_b32_e32 v106, 16, v110
	v_and_b32_e32 v107, 0xffff0000, v110
	v_lshlrev_b32_e32 v108, 16, v111
	v_and_b32_e32 v109, 0xffff0000, v111
	v_lshl_add_u64 v[80:81], s[14:15], 0, v[80:81]
	v_lshlrev_b32_e32 v110, 16, v114
	v_and_b32_e32 v111, 0xffff0000, v114
	v_lshlrev_b32_e32 v112, 16, v115
	v_and_b32_e32 v113, 0xffff0000, v115
	v_lshlrev_b32_e32 v114, 16, v116
	v_and_b32_e32 v115, 0xffff0000, v116
	v_lshlrev_b32_e32 v116, 16, v117
	v_and_b32_e32 v117, 0xffff0000, v117
	v_lshl_add_u64 v[82:83], s[6:7], 0, v[82:83]
	v_lshl_add_u64 v[80:81], v[80:81], 0, v[144:145]
	v_lshl_add_u64 v[82:83], v[82:83], 0, v[144:145]
	global_load_dwordx4 v[92:95], v[80:81], off
	global_load_dwordx4 v[98:101], v[80:81], off offset:256
	s_waitcnt vmcnt(0)
	v_lshlrev_b32_e32 v118, 16, v84
	v_and_b32_e32 v119, 0xffff0000, v84
	v_lshlrev_b32_e32 v84, 16, v85
	v_and_b32_e32 v85, 0xffff0000, v85
	v_lshlrev_b32_e32 v120, 16, v86
	v_and_b32_e32 v121, 0xffff0000, v86
	v_lshlrev_b32_e32 v86, 16, v87
	v_and_b32_e32 v87, 0xffff0000, v87
	v_lshlrev_b32_e32 v122, 16, v88
	v_and_b32_e32 v123, 0xffff0000, v88
	v_lshlrev_b32_e32 v88, 16, v89
	v_and_b32_e32 v89, 0xffff0000, v89
	v_lshlrev_b32_e32 v124, 16, v90
	v_and_b32_e32 v125, 0xffff0000, v90
	v_lshlrev_b32_e32 v90, 16, v91
	v_and_b32_e32 v91, 0xffff0000, v91
	v_pk_fma_f32 v[78:79], v[78:79], v[84:85], v[104:105]
	v_pk_fma_f32 v[76:77], v[76:77], v[118:119], v[102:103]
	v_pk_fma_f32 v[74:75], v[74:75], v[86:87], v[108:109]
	v_pk_fma_f32 v[72:73], v[72:73], v[120:121], v[106:107]
	v_pk_fma_f32 v[84:85], v[70:71], v[88:89], v[112:113]
	v_pk_fma_f32 v[86:87], v[68:69], v[122:123], v[110:111]
	v_cvt_pk_bf16_f32 v68, v76, v77
	v_cvt_pk_bf16_f32 v69, v78, v79
	v_cvt_pk_bf16_f32 v70, v72, v73
	v_cvt_pk_bf16_f32 v71, v74, v75
	v_pk_fma_f32 v[72:73], v[66:67], v[90:91], v[116:117]
	v_pk_fma_f32 v[66:67], v[64:65], v[124:125], v[114:115]
	global_store_dwordx4 v[96:97], v[68:71], off
	v_cvt_pk_bf16_f32 v64, v86, v87
	v_cvt_pk_bf16_f32 v65, v84, v85
	v_cvt_pk_bf16_f32 v66, v66, v67
	v_cvt_pk_bf16_f32 v67, v72, v73
	global_load_dwordx4 v[68:71], v[82:83], off offset:2048
	v_lshlrev_b32_e32 v86, 16, v92
	global_store_dwordx4 v[96:97], v[64:67], off offset:256
	global_load_dwordx4 v[72:75], v[82:83], off offset:2304
	v_and_b32_e32 v87, 0xffff0000, v92
	v_add_u32_e32 v64, 0x90, v146
	v_ashrrev_i32_e32 v65, 31, v64
	v_lshlrev_b64 v[66:67], 12, v[64:65]
	v_lshlrev_b64 v[64:65], 11, v[64:65]
	v_lshlrev_b32_e32 v88, 16, v93
	v_and_b32_e32 v89, 0xffff0000, v93
	v_lshlrev_b32_e32 v90, 16, v94
	v_and_b32_e32 v91, 0xffff0000, v94
	v_lshlrev_b32_e32 v92, 16, v95
	v_and_b32_e32 v93, 0xffff0000, v95
	v_lshl_add_u64 v[64:65], s[14:15], 0, v[64:65]
	v_lshlrev_b32_e32 v94, 16, v98
	v_and_b32_e32 v95, 0xffff0000, v98
	v_lshlrev_b32_e32 v96, 16, v99
	v_and_b32_e32 v97, 0xffff0000, v99
	v_lshlrev_b32_e32 v98, 16, v100
	v_and_b32_e32 v99, 0xffff0000, v100
	v_lshlrev_b32_e32 v100, 16, v101
	v_and_b32_e32 v101, 0xffff0000, v101
	v_lshl_add_u64 v[66:67], s[6:7], 0, v[66:67]
	v_lshl_add_u64 v[64:65], v[64:65], 0, v[144:145]
	v_lshl_add_u64 v[66:67], v[66:67], 0, v[144:145]
	global_load_dwordx4 v[76:79], v[64:65], off
	global_load_dwordx4 v[82:85], v[64:65], off offset:256
	s_waitcnt vmcnt(0)
	v_lshlrev_b32_e32 v102, 16, v68
	v_and_b32_e32 v103, 0xffff0000, v68
	v_lshlrev_b32_e32 v68, 16, v69
	v_and_b32_e32 v69, 0xffff0000, v69
	v_lshlrev_b32_e32 v104, 16, v70
	v_and_b32_e32 v105, 0xffff0000, v70
	v_lshlrev_b32_e32 v70, 16, v71
	v_and_b32_e32 v71, 0xffff0000, v71
	v_lshlrev_b32_e32 v106, 16, v72
	v_and_b32_e32 v107, 0xffff0000, v72
	v_lshlrev_b32_e32 v72, 16, v73
	v_and_b32_e32 v73, 0xffff0000, v73
	v_lshlrev_b32_e32 v108, 16, v74
	v_and_b32_e32 v109, 0xffff0000, v74
	v_lshlrev_b32_e32 v74, 16, v75
	v_and_b32_e32 v75, 0xffff0000, v75
	v_pk_fma_f32 v[62:63], v[62:63], v[68:69], v[88:89]
	v_pk_fma_f32 v[60:61], v[60:61], v[102:103], v[86:87]
	v_pk_fma_f32 v[58:59], v[58:59], v[70:71], v[92:93]
	v_pk_fma_f32 v[56:57], v[56:57], v[104:105], v[90:91]
	v_pk_fma_f32 v[68:69], v[54:55], v[72:73], v[96:97]
	v_pk_fma_f32 v[70:71], v[52:53], v[106:107], v[94:95]
	v_cvt_pk_bf16_f32 v52, v60, v61
	v_cvt_pk_bf16_f32 v53, v62, v63
	v_cvt_pk_bf16_f32 v54, v56, v57
	v_cvt_pk_bf16_f32 v55, v58, v59
	v_pk_fma_f32 v[56:57], v[50:51], v[74:75], v[100:101]
	v_pk_fma_f32 v[50:51], v[48:49], v[108:109], v[98:99]
	global_store_dwordx4 v[80:81], v[52:55], off
	v_cvt_pk_bf16_f32 v48, v70, v71
	v_cvt_pk_bf16_f32 v49, v68, v69
	v_cvt_pk_bf16_f32 v50, v50, v51
	v_cvt_pk_bf16_f32 v51, v56, v57
	global_load_dwordx4 v[52:55], v[66:67], off offset:2048
	v_lshlrev_b32_e32 v70, 16, v76
	global_store_dwordx4 v[80:81], v[48:51], off offset:256
	global_load_dwordx4 v[56:59], v[66:67], off offset:2304
	v_and_b32_e32 v71, 0xffff0000, v76
	v_add_u32_e32 v48, 0xa0, v146
	v_ashrrev_i32_e32 v49, 31, v48
	v_lshlrev_b64 v[50:51], 12, v[48:49]
	v_lshlrev_b64 v[48:49], 11, v[48:49]
	v_lshlrev_b32_e32 v72, 16, v77
	v_and_b32_e32 v73, 0xffff0000, v77
	v_lshlrev_b32_e32 v74, 16, v78
	v_and_b32_e32 v75, 0xffff0000, v78
	v_lshlrev_b32_e32 v76, 16, v79
	v_and_b32_e32 v77, 0xffff0000, v79
	v_lshl_add_u64 v[48:49], s[14:15], 0, v[48:49]
	v_lshlrev_b32_e32 v78, 16, v82
	v_and_b32_e32 v79, 0xffff0000, v82
	v_lshlrev_b32_e32 v80, 16, v83
	v_and_b32_e32 v81, 0xffff0000, v83
	v_lshlrev_b32_e32 v82, 16, v84
	v_and_b32_e32 v83, 0xffff0000, v84
	v_lshlrev_b32_e32 v84, 16, v85
	v_and_b32_e32 v85, 0xffff0000, v85
	v_lshl_add_u64 v[50:51], s[6:7], 0, v[50:51]
	v_lshl_add_u64 v[48:49], v[48:49], 0, v[144:145]
	v_lshl_add_u64 v[50:51], v[50:51], 0, v[144:145]
	global_load_dwordx4 v[60:63], v[48:49], off
	global_load_dwordx4 v[66:69], v[48:49], off offset:256
	s_waitcnt vmcnt(0)
	v_lshlrev_b32_e32 v86, 16, v52
	v_and_b32_e32 v87, 0xffff0000, v52
	v_lshlrev_b32_e32 v52, 16, v53
	v_and_b32_e32 v53, 0xffff0000, v53
	v_lshlrev_b32_e32 v88, 16, v54
	v_and_b32_e32 v89, 0xffff0000, v54
	v_lshlrev_b32_e32 v54, 16, v55
	v_and_b32_e32 v55, 0xffff0000, v55
	v_lshlrev_b32_e32 v90, 16, v56
	v_and_b32_e32 v91, 0xffff0000, v56
	v_lshlrev_b32_e32 v56, 16, v57
	v_and_b32_e32 v57, 0xffff0000, v57
	v_lshlrev_b32_e32 v92, 16, v58
	v_and_b32_e32 v93, 0xffff0000, v58
	v_lshlrev_b32_e32 v58, 16, v59
	v_and_b32_e32 v59, 0xffff0000, v59
	v_pk_fma_f32 v[46:47], v[46:47], v[52:53], v[72:73]
	v_pk_fma_f32 v[44:45], v[44:45], v[86:87], v[70:71]
	v_pk_fma_f32 v[42:43], v[42:43], v[54:55], v[76:77]
	v_pk_fma_f32 v[40:41], v[40:41], v[88:89], v[74:75]
	v_pk_fma_f32 v[52:53], v[38:39], v[56:57], v[80:81]
	v_pk_fma_f32 v[54:55], v[36:37], v[90:91], v[78:79]
	v_cvt_pk_bf16_f32 v36, v44, v45
	v_cvt_pk_bf16_f32 v37, v46, v47
	v_cvt_pk_bf16_f32 v38, v40, v41
	v_cvt_pk_bf16_f32 v39, v42, v43
	v_pk_fma_f32 v[40:41], v[34:35], v[58:59], v[84:85]
	v_pk_fma_f32 v[34:35], v[32:33], v[92:93], v[82:83]
	global_store_dwordx4 v[64:65], v[36:39], off
	v_cvt_pk_bf16_f32 v32, v54, v55
	v_cvt_pk_bf16_f32 v33, v52, v53
	v_cvt_pk_bf16_f32 v34, v34, v35
	v_cvt_pk_bf16_f32 v35, v40, v41
	global_load_dwordx4 v[36:39], v[50:51], off offset:2048
	v_add_u32_e32 v40, 0xb0, v146
	global_store_dwordx4 v[64:65], v[32:35], off offset:256
	global_load_dwordx4 v[32:35], v[50:51], off offset:2304
	v_ashrrev_i32_e32 v41, 31, v40
	v_lshlrev_b64 v[42:43], 12, v[40:41]
	v_lshlrev_b64 v[40:41], 11, v[40:41]
	v_lshlrev_b32_e32 v54, 16, v60
	v_and_b32_e32 v55, 0xffff0000, v60
	v_lshlrev_b32_e32 v56, 16, v61
	v_and_b32_e32 v57, 0xffff0000, v61
	v_lshlrev_b32_e32 v58, 16, v62
	v_and_b32_e32 v59, 0xffff0000, v62
	v_lshlrev_b32_e32 v60, 16, v63
	v_and_b32_e32 v61, 0xffff0000, v63
	v_lshl_add_u64 v[40:41], s[14:15], 0, v[40:41]
	v_lshlrev_b32_e32 v62, 16, v66
	v_and_b32_e32 v63, 0xffff0000, v66
	v_lshlrev_b32_e32 v64, 16, v67
	v_and_b32_e32 v65, 0xffff0000, v67
	v_lshlrev_b32_e32 v66, 16, v68
	v_and_b32_e32 v67, 0xffff0000, v68
	v_lshlrev_b32_e32 v68, 16, v69
	v_and_b32_e32 v69, 0xffff0000, v69
	v_lshl_add_u64 v[42:43], s[6:7], 0, v[42:43]
	v_lshl_add_u64 v[52:53], v[40:41], 0, v[144:145]
	v_lshl_add_u64 v[50:51], v[42:43], 0, v[144:145]
	global_load_dwordx4 v[40:43], v[52:53], off
	global_load_dwordx4 v[44:47], v[52:53], off offset:256
	s_waitcnt vmcnt(0)
	v_lshlrev_b32_e32 v70, 16, v36
	v_and_b32_e32 v71, 0xffff0000, v36
	v_lshlrev_b32_e32 v36, 16, v37
	v_and_b32_e32 v37, 0xffff0000, v37
	v_lshlrev_b32_e32 v72, 16, v38
	v_and_b32_e32 v73, 0xffff0000, v38
	v_lshlrev_b32_e32 v38, 16, v39
	v_and_b32_e32 v39, 0xffff0000, v39
	v_lshlrev_b32_e32 v74, 16, v32
	v_and_b32_e32 v75, 0xffff0000, v32
	v_lshlrev_b32_e32 v32, 16, v33
	v_and_b32_e32 v33, 0xffff0000, v33
	v_lshlrev_b32_e32 v76, 16, v34
	v_and_b32_e32 v77, 0xffff0000, v34
	v_lshlrev_b32_e32 v34, 16, v35
	v_and_b32_e32 v35, 0xffff0000, v35
	v_pk_fma_f32 v[30:31], v[30:31], v[36:37], v[56:57]
	v_pk_fma_f32 v[28:29], v[28:29], v[70:71], v[54:55]
	v_pk_fma_f32 v[26:27], v[26:27], v[38:39], v[60:61]
	v_pk_fma_f32 v[24:25], v[24:25], v[72:73], v[58:59]
	v_pk_fma_f32 v[32:33], v[22:23], v[32:33], v[64:65]
	v_pk_fma_f32 v[36:37], v[20:21], v[74:75], v[62:63]
	v_cvt_pk_bf16_f32 v20, v28, v29
	v_cvt_pk_bf16_f32 v21, v30, v31
	v_cvt_pk_bf16_f32 v22, v24, v25
	v_cvt_pk_bf16_f32 v23, v26, v27
	v_pk_fma_f32 v[24:25], v[18:19], v[34:35], v[68:69]
	v_pk_fma_f32 v[18:19], v[16:17], v[76:77], v[66:67]
	global_store_dwordx4 v[48:49], v[20:23], off
	v_cvt_pk_bf16_f32 v16, v36, v37
	v_cvt_pk_bf16_f32 v17, v32, v33
	v_cvt_pk_bf16_f32 v18, v18, v19
	v_cvt_pk_bf16_f32 v19, v24, v25
	global_load_dwordx4 v[20:23], v[50:51], off offset:2048
	v_lshlrev_b32_e32 v24, 16, v40
	global_store_dwordx4 v[48:49], v[16:19], off offset:256
	global_load_dwordx4 v[16:19], v[50:51], off offset:2304
	v_and_b32_e32 v25, 0xffff0000, v40
	v_lshlrev_b32_e32 v26, 16, v41
	v_and_b32_e32 v27, 0xffff0000, v41
	v_lshlrev_b32_e32 v28, 16, v42
	v_and_b32_e32 v29, 0xffff0000, v42
	v_lshlrev_b32_e32 v30, 16, v43
	v_and_b32_e32 v31, 0xffff0000, v43
	v_lshlrev_b32_e32 v32, 16, v44
	v_and_b32_e32 v33, 0xffff0000, v44
	v_lshlrev_b32_e32 v34, 16, v45
	v_and_b32_e32 v35, 0xffff0000, v45
	v_lshlrev_b32_e32 v36, 16, v46
	v_and_b32_e32 v37, 0xffff0000, v46
	v_lshlrev_b32_e32 v38, 16, v47
	v_and_b32_e32 v39, 0xffff0000, v47
	s_waitcnt vmcnt(0)
	v_lshlrev_b32_e32 v40, 16, v20
	v_and_b32_e32 v41, 0xffff0000, v20
	v_lshlrev_b32_e32 v20, 16, v21
	v_and_b32_e32 v21, 0xffff0000, v21
	v_lshlrev_b32_e32 v42, 16, v22
	v_and_b32_e32 v43, 0xffff0000, v22
	v_lshlrev_b32_e32 v22, 16, v23
	v_and_b32_e32 v23, 0xffff0000, v23
	v_lshlrev_b32_e32 v44, 16, v16
	v_and_b32_e32 v45, 0xffff0000, v16
	v_lshlrev_b32_e32 v16, 16, v17
	v_and_b32_e32 v17, 0xffff0000, v17
	v_lshlrev_b32_e32 v46, 16, v18
	v_and_b32_e32 v47, 0xffff0000, v18
	v_lshlrev_b32_e32 v18, 16, v19
	v_and_b32_e32 v19, 0xffff0000, v19
	v_pk_fma_f32 v[14:15], v[14:15], v[20:21], v[26:27]
	v_pk_fma_f32 v[12:13], v[12:13], v[40:41], v[24:25]
	v_pk_fma_f32 v[10:11], v[10:11], v[22:23], v[30:31]
	v_pk_fma_f32 v[8:9], v[8:9], v[42:43], v[28:29]
	v_pk_fma_f32 v[6:7], v[6:7], v[16:17], v[34:35]
	v_pk_fma_f32 v[4:5], v[4:5], v[44:45], v[32:33]
	v_pk_fma_f32 v[16:17], v[2:3], v[18:19], v[38:39]
	v_pk_fma_f32 v[18:19], v[0:1], v[46:47], v[36:37]
	v_cvt_pk_bf16_f32 v0, v12, v13
	v_cvt_pk_bf16_f32 v1, v14, v15
	v_cvt_pk_bf16_f32 v2, v8, v9
	v_cvt_pk_bf16_f32 v3, v10, v11
	v_cvt_pk_bf16_f32 v4, v4, v5
	v_cvt_pk_bf16_f32 v5, v6, v7
	v_cvt_pk_bf16_f32 v6, v18, v19
	v_cvt_pk_bf16_f32 v7, v16, v17
	global_store_dwordx4 v[52:53], v[0:3], off
	global_store_dwordx4 v[52:53], v[4:7], off offset:256
	s_cbranch_vccz .LBB0_600
	s_waitcnt vmcnt(0)
	s_cmpk_gt_u32 s0, 0xff
	s_cbranch_scc1 .LBB0_607
	s_barrier

.LBB0_628:
	ds_read_b128 v[146:149], v159
	ds_read_b128 v[150:153], v159 offset:1024
	ds_read_b128 v[164:167], v159 offset:2048
	ds_read_b128 v[168:171], v159 offset:3072
	s_add_u32 s52, s50, 0xfffc0080
	s_addc_u32 s53, s51, -1
	s_cmp_eq_u32 s71, 12
	s_cselect_b32 s55, s25, s53
	s_cselect_b32 s54, s47, s52
	s_cselect_b32 s53, s23, s70
	s_cselect_b32 s52, s49, s69
	v_lshl_add_u64 v[204:205], s[50:51], 0, v[138:139]
	s_add_i32 m0, s33, 0xc000
	ds_read_b128 v[172:175], v160
	ds_read_b128 v[176:179], v160 offset:1024
	ds_read_b128 v[180:183], v160 offset:2048
	ds_read_b128 v[184:187], v160 offset:3072
	ds_read_b128 v[188:191], v160 offset:4096
	ds_read_b128 v[192:195], v160 offset:5120
	ds_read_b128 v[196:199], v160 offset:6144
	ds_read_b128 v[200:203], v160 offset:7168
	global_load_lds_dwordx4 v[204:205], off
	s_add_i32 m0, s33, 0xe000
	v_lshl_add_u64 v[204:205], s[50:51], 0, v[140:141]
	global_load_lds_dwordx4 v[204:205], off
	s_waitcnt lgkmcnt(8)
	s_barrier
	s_waitcnt lgkmcnt(0)
	v_mfma_f32_16x16x32_bf16 v[124:127], v[146:149], v[172:175], v[124:127]
	v_mfma_f32_16x16x32_bf16 v[120:123], v[164:167], v[172:175], v[120:123]
	v_mfma_f32_16x16x32_bf16 v[108:111], v[146:149], v[180:183], v[108:111]
	v_mfma_f32_16x16x32_bf16 v[104:107], v[164:167], v[180:183], v[104:107]
	v_mfma_f32_16x16x32_bf16 v[92:95], v[146:149], v[188:191], v[92:95]
	v_mfma_f32_16x16x32_bf16 v[88:91], v[164:167], v[188:191], v[88:91]
	v_mfma_f32_16x16x32_bf16 v[76:79], v[146:149], v[196:199], v[76:79]
	v_mfma_f32_16x16x32_bf16 v[72:75], v[164:167], v[196:199], v[72:75]
	v_mfma_f32_16x16x32_bf16 v[124:127], v[150:153], v[176:179], v[124:127]
	v_mfma_f32_16x16x32_bf16 v[120:123], v[168:171], v[176:179], v[120:123]
	v_mfma_f32_16x16x32_bf16 v[108:111], v[150:153], v[184:187], v[108:111]
	v_mfma_f32_16x16x32_bf16 v[104:107], v[168:171], v[184:187], v[104:107]
	v_mfma_f32_16x16x32_bf16 v[92:95], v[150:153], v[192:195], v[92:95]
	v_mfma_f32_16x16x32_bf16 v[88:91], v[168:171], v[192:195], v[88:91]
	v_mfma_f32_16x16x32_bf16 v[76:79], v[150:153], v[200:203], v[76:79]
	v_mfma_f32_16x16x32_bf16 v[72:75], v[168:171], v[200:203], v[72:75]
	s_barrier
	s_add_i32 s73, s63, s1
	v_lshl_add_u64 v[220:221], s[52:53], 0, v[130:131]
	s_mov_b32 m0, s73
	ds_read_b128 v[204:207], v161
	ds_read_b128 v[208:211], v161 offset:1024
	ds_read_b128 v[212:215], v161 offset:2048
	ds_read_b128 v[216:219], v161 offset:3072
	global_load_lds_dwordx4 v[220:221], off
	s_add_i32 m0, s73, 0x2000
	v_lshl_add_u64 v[222:223], s[52:53], 0, v[134:135]
	global_load_lds_dwordx4 v[222:223], off
	s_barrier
	s_waitcnt lgkmcnt(0)
	v_mfma_f32_16x16x32_bf16 v[116:119], v[204:207], v[172:175], v[116:119]
	v_mfma_f32_16x16x32_bf16 v[112:115], v[212:215], v[172:175], v[112:115]
	v_mfma_f32_16x16x32_bf16 v[100:103], v[204:207], v[180:183], v[100:103]
	v_mfma_f32_16x16x32_bf16 v[96:99], v[212:215], v[180:183], v[96:99]
	v_mfma_f32_16x16x32_bf16 v[84:87], v[204:207], v[188:191], v[84:87]
	v_mfma_f32_16x16x32_bf16 v[80:83], v[212:215], v[188:191], v[80:83]
	v_mfma_f32_16x16x32_bf16 v[68:71], v[204:207], v[196:199], v[68:71]
	v_mfma_f32_16x16x32_bf16 v[64:67], v[212:215], v[196:199], v[64:67]
	v_mfma_f32_16x16x32_bf16 v[116:119], v[208:211], v[176:179], v[116:119]
	v_mfma_f32_16x16x32_bf16 v[112:115], v[216:219], v[176:179], v[112:115]
	v_mfma_f32_16x16x32_bf16 v[100:103], v[208:211], v[184:187], v[100:103]
	v_mfma_f32_16x16x32_bf16 v[96:99], v[216:219], v[184:187], v[96:99]
	v_mfma_f32_16x16x32_bf16 v[84:87], v[208:211], v[192:195], v[84:87]
	v_mfma_f32_16x16x32_bf16 v[80:83], v[216:219], v[192:195], v[80:83]
	v_mfma_f32_16x16x32_bf16 v[68:71], v[208:211], v[200:203], v[68:71]
	v_mfma_f32_16x16x32_bf16 v[64:67], v[216:219], v[200:203], v[64:67]
	s_mov_b32 m0, s33
	v_lshl_add_u64 v[224:225], s[54:55], 0, v[128:129]
	s_barrier
	ds_read_b128 v[172:175], v160 offset:16384
	ds_read_b128 v[176:179], v160 offset:17408
	ds_read_b128 v[180:183], v160 offset:18432
	ds_read_b128 v[184:187], v160 offset:19456
	ds_read_b128 v[188:191], v160 offset:20480
	ds_read_b128 v[192:195], v160 offset:21504
	ds_read_b128 v[196:199], v160 offset:22528
	ds_read_b128 v[200:203], v160 offset:23552
	global_load_lds_dwordx4 v[224:225], off
	s_mov_b32 m0, s34
	v_lshl_add_u64 v[226:227], s[54:55], 0, v[132:133]
	global_load_lds_dwordx4 v[226:227], off
	s_barrier
	s_waitcnt lgkmcnt(0)
	v_mfma_f32_16x16x32_bf16 v[60:63], v[146:149], v[172:175], v[60:63]
	v_mfma_f32_16x16x32_bf16 v[56:59], v[164:167], v[172:175], v[56:59]
	v_mfma_f32_16x16x32_bf16 v[44:47], v[146:149], v[180:183], v[44:47]
	v_mfma_f32_16x16x32_bf16 v[40:43], v[164:167], v[180:183], v[40:43]
	v_mfma_f32_16x16x32_bf16 v[28:31], v[146:149], v[188:191], v[28:31]
	v_mfma_f32_16x16x32_bf16 v[24:27], v[164:167], v[188:191], v[24:27]
	v_mfma_f32_16x16x32_bf16 v[12:15], v[146:149], v[196:199], v[12:15]
	v_mfma_f32_16x16x32_bf16 v[8:11], v[164:167], v[196:199], v[8:11]
	v_mfma_f32_16x16x32_bf16 v[60:63], v[150:153], v[176:179], v[60:63]
	v_mfma_f32_16x16x32_bf16 v[56:59], v[168:171], v[176:179], v[56:59]
	v_mfma_f32_16x16x32_bf16 v[44:47], v[150:153], v[184:187], v[44:47]
	v_mfma_f32_16x16x32_bf16 v[40:43], v[168:171], v[184:187], v[40:43]
	v_mfma_f32_16x16x32_bf16 v[28:31], v[150:153], v[192:195], v[28:31]
	v_mfma_f32_16x16x32_bf16 v[24:27], v[168:171], v[192:195], v[24:27]
	v_mfma_f32_16x16x32_bf16 v[12:15], v[150:153], v[200:203], v[12:15]
	v_mfma_f32_16x16x32_bf16 v[8:11], v[168:171], v[200:203], v[8:11]
	s_barrier
	s_add_u32 s74, s52, 0x40000
	s_addc_u32 s75, s53, 0
	s_add_i32 s73, s72, s1
	s_mov_b32 m0, s73
	v_lshl_add_u64 v[146:147], s[74:75], 0, v[130:131]
	global_load_lds_dwordx4 v[146:147], off
	s_add_i32 m0, s73, 0x2000
	v_lshl_add_u64 v[146:147], s[74:75], 0, v[134:135]
	global_load_lds_dwordx4 v[146:147], off
	s_waitcnt vmcnt(6)
	s_barrier
	v_mfma_f32_16x16x32_bf16 v[52:55], v[204:207], v[172:175], v[52:55]
	v_mfma_f32_16x16x32_bf16 v[48:51], v[212:215], v[172:175], v[48:51]
	v_mfma_f32_16x16x32_bf16 v[36:39], v[204:207], v[180:183], v[36:39]
	v_mfma_f32_16x16x32_bf16 v[32:35], v[212:215], v[180:183], v[32:35]
	v_mfma_f32_16x16x32_bf16 v[20:23], v[204:207], v[188:191], v[20:23]
	v_mfma_f32_16x16x32_bf16 v[16:19], v[212:215], v[188:191], v[16:19]
	v_mfma_f32_16x16x32_bf16 v[4:7], v[204:207], v[196:199], v[4:7]
	v_mfma_f32_16x16x32_bf16 v[0:3], v[212:215], v[196:199], v[0:3]
	v_mfma_f32_16x16x32_bf16 v[52:55], v[208:211], v[176:179], v[52:55]
	v_mfma_f32_16x16x32_bf16 v[48:51], v[216:219], v[176:179], v[48:51]
	v_mfma_f32_16x16x32_bf16 v[36:39], v[208:211], v[184:187], v[36:39]
	v_mfma_f32_16x16x32_bf16 v[32:35], v[216:219], v[184:187], v[32:35]
	v_mfma_f32_16x16x32_bf16 v[20:23], v[208:211], v[192:195], v[20:23]
	v_mfma_f32_16x16x32_bf16 v[16:19], v[216:219], v[192:195], v[16:19]
	v_mfma_f32_16x16x32_bf16 v[4:7], v[208:211], v[200:203], v[4:7]
	v_mfma_f32_16x16x32_bf16 v[0:3], v[216:219], v[200:203], v[0:3]
	s_add_i32 s73, 0, 0x18000
	v_add_u32_e32 v136, s73, v157
	s_barrier
	ds_read_b128 v[146:149], v136
	ds_read_b128 v[150:153], v136 offset:1024
	ds_read_b128 v[164:167], v136 offset:2048
	ds_read_b128 v[168:171], v136 offset:3072
	s_add_u32 s54, s54, 0x40000
	s_addc_u32 s55, s55, 0
	s_mov_b32 m0, s35
	v_lshl_add_u64 v[204:205], s[54:55], 0, v[128:129]
	ds_read_b128 v[172:175], v160 offset:32768
	ds_read_b128 v[176:179], v160 offset:33792
	ds_read_b128 v[180:183], v160 offset:34816
	ds_read_b128 v[184:187], v160 offset:35840
	ds_read_b128 v[188:191], v160 offset:36864
	ds_read_b128 v[192:195], v160 offset:37888
	ds_read_b128 v[196:199], v160 offset:38912
	ds_read_b128 v[200:203], v160 offset:39936
	global_load_lds_dwordx4 v[204:205], off
	s_mov_b32 m0, s56
	v_lshl_add_u64 v[204:205], s[54:55], 0, v[132:133]
	global_load_lds_dwordx4 v[204:205], off
	s_waitcnt lgkmcnt(8)
	s_barrier
	s_waitcnt lgkmcnt(0)
	v_mfma_f32_16x16x32_bf16 v[124:127], v[146:149], v[172:175], v[124:127]
	v_mfma_f32_16x16x32_bf16 v[120:123], v[164:167], v[172:175], v[120:123]
	v_mfma_f32_16x16x32_bf16 v[108:111], v[146:149], v[180:183], v[108:111]
	v_mfma_f32_16x16x32_bf16 v[104:107], v[164:167], v[180:183], v[104:107]
	v_mfma_f32_16x16x32_bf16 v[92:95], v[146:149], v[188:191], v[92:95]
	v_mfma_f32_16x16x32_bf16 v[88:91], v[164:167], v[188:191], v[88:91]
	v_mfma_f32_16x16x32_bf16 v[76:79], v[146:149], v[196:199], v[76:79]
	v_mfma_f32_16x16x32_bf16 v[72:75], v[164:167], v[196:199], v[72:75]
	v_mfma_f32_16x16x32_bf16 v[124:127], v[150:153], v[176:179], v[124:127]
	v_mfma_f32_16x16x32_bf16 v[120:123], v[168:171], v[176:179], v[120:123]
	v_mfma_f32_16x16x32_bf16 v[108:111], v[150:153], v[184:187], v[108:111]
	v_mfma_f32_16x16x32_bf16 v[104:107], v[168:171], v[184:187], v[104:107]
	v_mfma_f32_16x16x32_bf16 v[92:95], v[150:153], v[192:195], v[92:95]
	v_mfma_f32_16x16x32_bf16 v[88:91], v[168:171], v[192:195], v[88:91]
	v_mfma_f32_16x16x32_bf16 v[76:79], v[150:153], v[200:203], v[76:79]
	v_mfma_f32_16x16x32_bf16 v[72:75], v[168:171], v[200:203], v[72:75]
	s_barrier
	s_add_i32 s54, s73, s1
	v_add_u32_e32 v136, s97, v157
	v_lshl_add_u64 v[220:221], v[220:221], 0, s[20:21]
	s_mov_b32 m0, s54
	ds_read_b128 v[204:207], v136
	ds_read_b128 v[208:211], v136 offset:1024
	ds_read_b128 v[212:215], v136 offset:2048
	ds_read_b128 v[216:219], v136 offset:3072
	global_load_lds_dwordx4 v[220:221], off
	s_add_i32 m0, s54, 0x2000
	v_lshl_add_u64 v[220:221], v[222:223], 0, s[20:21]
	global_load_lds_dwordx4 v[220:221], off
	s_barrier
	s_waitcnt lgkmcnt(0)
	v_mfma_f32_16x16x32_bf16 v[116:119], v[204:207], v[172:175], v[116:119]
	v_mfma_f32_16x16x32_bf16 v[112:115], v[212:215], v[172:175], v[112:115]
	v_mfma_f32_16x16x32_bf16 v[100:103], v[204:207], v[180:183], v[100:103]
	v_mfma_f32_16x16x32_bf16 v[96:99], v[212:215], v[180:183], v[96:99]
	v_mfma_f32_16x16x32_bf16 v[84:87], v[204:207], v[188:191], v[84:87]
	v_mfma_f32_16x16x32_bf16 v[80:83], v[212:215], v[188:191], v[80:83]
	v_mfma_f32_16x16x32_bf16 v[68:71], v[204:207], v[196:199], v[68:71]
	v_mfma_f32_16x16x32_bf16 v[64:67], v[212:215], v[196:199], v[64:67]
	v_mfma_f32_16x16x32_bf16 v[116:119], v[208:211], v[176:179], v[116:119]
	v_mfma_f32_16x16x32_bf16 v[112:115], v[216:219], v[176:179], v[112:115]
	v_mfma_f32_16x16x32_bf16 v[100:103], v[208:211], v[184:187], v[100:103]
	v_mfma_f32_16x16x32_bf16 v[96:99], v[216:219], v[184:187], v[96:99]
	v_mfma_f32_16x16x32_bf16 v[84:87], v[208:211], v[192:195], v[84:87]
	v_mfma_f32_16x16x32_bf16 v[80:83], v[216:219], v[192:195], v[80:83]
	v_mfma_f32_16x16x32_bf16 v[68:71], v[208:211], v[200:203], v[68:71]
	v_mfma_f32_16x16x32_bf16 v[64:67], v[216:219], v[200:203], v[64:67]
	s_mov_b32 m0, s58
	v_lshl_add_u64 v[220:221], v[224:225], 0, s[20:21]
	s_barrier
	ds_read_b128 v[172:175], v160 offset:49152
	ds_read_b128 v[176:179], v160 offset:50176
	ds_read_b128 v[180:183], v160 offset:51200
	ds_read_b128 v[184:187], v160 offset:52224
	ds_read_b128 v[188:191], v160 offset:53248
	ds_read_b128 v[192:195], v160 offset:54272
	ds_read_b128 v[196:199], v160 offset:55296
	ds_read_b128 v[200:203], v160 offset:56320
	global_load_lds_dwordx4 v[220:221], off
	s_mov_b32 m0, s59
	v_lshl_add_u64 v[220:221], v[226:227], 0, s[20:21]
	global_load_lds_dwordx4 v[220:221], off
	s_barrier
	s_waitcnt lgkmcnt(0)
	v_mfma_f32_16x16x32_bf16 v[60:63], v[146:149], v[172:175], v[60:63]
	v_mfma_f32_16x16x32_bf16 v[56:59], v[164:167], v[172:175], v[56:59]
	v_mfma_f32_16x16x32_bf16 v[44:47], v[146:149], v[180:183], v[44:47]
	v_mfma_f32_16x16x32_bf16 v[40:43], v[164:167], v[180:183], v[40:43]
	v_mfma_f32_16x16x32_bf16 v[28:31], v[146:149], v[188:191], v[28:31]
	v_mfma_f32_16x16x32_bf16 v[24:27], v[164:167], v[188:191], v[24:27]
	v_mfma_f32_16x16x32_bf16 v[12:15], v[146:149], v[196:199], v[12:15]
	v_mfma_f32_16x16x32_bf16 v[8:11], v[164:167], v[196:199], v[8:11]
	v_mfma_f32_16x16x32_bf16 v[60:63], v[150:153], v[176:179], v[60:63]
	v_mfma_f32_16x16x32_bf16 v[56:59], v[168:171], v[176:179], v[56:59]
	v_mfma_f32_16x16x32_bf16 v[44:47], v[150:153], v[184:187], v[44:47]
	v_mfma_f32_16x16x32_bf16 v[40:43], v[168:171], v[184:187], v[40:43]
	v_mfma_f32_16x16x32_bf16 v[28:31], v[150:153], v[192:195], v[28:31]
	v_mfma_f32_16x16x32_bf16 v[24:27], v[168:171], v[192:195], v[24:27]
	v_mfma_f32_16x16x32_bf16 v[12:15], v[150:153], v[200:203], v[12:15]
	v_mfma_f32_16x16x32_bf16 v[8:11], v[168:171], v[200:203], v[8:11]
	s_barrier
	s_add_u32 s52, s52, 0x40080
	s_addc_u32 s53, s53, 0
	s_add_i32 s54, s97, s1
	s_mov_b32 m0, s54
	v_lshl_add_u64 v[146:147], s[52:53], 0, v[130:131]
	global_load_lds_dwordx4 v[146:147], off
	s_add_i32 m0, s54, 0x2000
	v_lshl_add_u64 v[146:147], s[52:53], 0, v[134:135]
	global_load_lds_dwordx4 v[146:147], off
	s_waitcnt vmcnt(6)
	s_barrier
	v_mfma_f32_16x16x32_bf16 v[52:55], v[204:207], v[172:175], v[52:55]
	v_mfma_f32_16x16x32_bf16 v[48:51], v[212:215], v[172:175], v[48:51]
	v_mfma_f32_16x16x32_bf16 v[36:39], v[204:207], v[180:183], v[36:39]
	v_mfma_f32_16x16x32_bf16 v[32:35], v[212:215], v[180:183], v[32:35]
	v_mfma_f32_16x16x32_bf16 v[20:23], v[204:207], v[188:191], v[20:23]
	v_mfma_f32_16x16x32_bf16 v[16:19], v[212:215], v[188:191], v[16:19]
	v_mfma_f32_16x16x32_bf16 v[4:7], v[204:207], v[196:199], v[4:7]
	v_mfma_f32_16x16x32_bf16 v[0:3], v[212:215], v[196:199], v[0:3]
	v_mfma_f32_16x16x32_bf16 v[52:55], v[208:211], v[176:179], v[52:55]
	v_mfma_f32_16x16x32_bf16 v[48:51], v[216:219], v[176:179], v[48:51]
	v_mfma_f32_16x16x32_bf16 v[36:39], v[208:211], v[184:187], v[36:39]
	v_mfma_f32_16x16x32_bf16 v[32:35], v[216:219], v[184:187], v[32:35]
	v_mfma_f32_16x16x32_bf16 v[20:23], v[208:211], v[192:195], v[20:23]
	v_mfma_f32_16x16x32_bf16 v[16:19], v[216:219], v[192:195], v[16:19]
	v_mfma_f32_16x16x32_bf16 v[4:7], v[208:211], v[200:203], v[4:7]
	v_mfma_f32_16x16x32_bf16 v[0:3], v[216:219], v[200:203], v[0:3]
	s_add_i32 s71, s71, 2
	s_add_u32 s50, s50, 0x100
	s_addc_u32 s51, s51, 0
	s_add_u32 s69, s69, 0x100
	s_addc_u32 s70, s70, 0
	s_cmp_gt_u32 s71, 13
	s_barrier
	s_cbranch_scc0 .LBB0_628
	v_lshl_add_u32 v150, s48, 8, v156
	v_cmp_lt_i32_e32 vcc, s64, v150
	s_and_saveexec_b64 s[48:49], vcc
	s_xor_b64 s[48:49], exec, s[48:49]
	v_add_u32_e32 v136, 0xffff0000, v150
	v_lshlrev_b64 v[146:147], 12, v[136:137]
	v_lshl_add_u64 v[152:153], s[38:39], 0, v[146:147]
	v_mov_b32_e32 v151, v137
	s_andn2_saveexec_b64 s[48:49], s[48:49]
	v_ashrrev_i32_e32 v151, 31, v150
	v_lshlrev_b64 v[146:147], 12, v[150:151]
	v_lshl_add_u64 v[152:153], s[36:37], 0, v[146:147]
	s_or_b64 exec, exec, s[48:49]
	v_lshl_or_b32 v146, s46, 8, v158
	v_ashrrev_i32_e32 v147, 31, v146
	v_lshlrev_b64 v[148:149], 2, v[146:147]
	v_lshl_add_u64 v[152:153], v[152:153], 0, v[148:149]
	global_load_dwordx4 v[164:167], v[152:153], off
	global_load_dwordx4 v[168:171], v[152:153], off offset:16
	v_lshlrev_b64 v[172:173], 12, v[150:151]
	v_lshlrev_b64 v[174:175], 11, v[150:151]
	v_lshl_add_u64 v[172:173], s[42:43], 0, v[172:173]
	v_lshl_add_u64 v[174:175], s[84:85], 0, v[174:175]
	v_lshl_add_u64 v[176:177], v[146:147], 1, v[174:175]
	v_lshl_add_u64 v[178:179], v[172:173], 0, v[148:149]
	s_waitcnt vmcnt(0)
	v_pk_add_f32 v[126:127], v[126:127], v[166:167]
	v_pk_add_f32 v[124:125], v[124:125], v[164:165]
	v_pk_add_f32 v[166:167], v[122:123], v[170:171]
	v_pk_add_f32 v[164:165], v[120:121], v[168:169]
	v_cvt_pk_bf16_f32 v120, v124, v125
	v_cvt_pk_bf16_f32 v121, v126, v127
	v_cvt_pk_bf16_f32 v122, v164, v165
	v_cvt_pk_bf16_f32 v123, v166, v167
	global_store_dwordx4 v[178:179], v[124:127], off
	global_store_dwordx4 v[178:179], v[164:167], off offset:16
	global_store_dwordx4 v[176:177], v[120:123], off
	global_load_dwordx4 v[168:171], v[152:153], off offset:512
	global_load_dwordx4 v[172:175], v[152:153], off offset:528
	v_and_b32_e32 v121, 64, v162
	v_xor_b32_e32 v120, 16, v162
	v_add_u32_e32 v121, 64, v121
	v_xor_b32_e32 v122, 32, v162
	v_cmp_lt_i32_e32 vcc, v120, v121
	v_mul_f32_e32 v123, v165, v165
	v_mul_f32_e32 v136, v166, v166
	v_cndmask_b32_e32 v120, v162, v120, vcc
	v_cmp_lt_i32_e32 vcc, v122, v121
	v_fmac_f32_e32 v123, v125, v125
	v_mul_f32_e32 v152, v167, v167
	v_cndmask_b32_e32 v121, v162, v122, vcc
	v_mul_f32_e32 v122, v164, v164
	v_fmac_f32_e32 v122, v124, v124
	v_fmac_f32_e32 v136, v126, v126
	v_add_f32_e32 v122, v122, v123
	v_fmac_f32_e32 v152, v127, v127
	v_add_f32_e32 v122, v136, v122
	v_add_f32_e32 v126, v152, v122
	v_lshlrev_b32_e32 v120, 2, v120
	s_waitcnt vmcnt(0)
	v_pk_add_f32 v[122:123], v[116:117], v[168:169]
	v_pk_add_f32 v[164:165], v[112:113], v[172:173]
	v_pk_add_f32 v[166:167], v[114:115], v[174:175]
	v_mul_f32_e32 v112, v164, v164
	v_mul_f32_e32 v113, v165, v165
	v_fmac_f32_e32 v112, v122, v122
	v_pk_add_f32 v[124:125], v[118:119], v[170:171]
	v_mul_f32_e32 v114, v166, v166
	v_fmac_f32_e32 v113, v123, v123
	v_add_f32_e32 v112, v126, v112
	v_mul_f32_e32 v115, v167, v167
	v_fmac_f32_e32 v114, v124, v124
	v_add_f32_e32 v112, v113, v112
	v_add_f32_e32 v112, v114, v112
	v_fmac_f32_e32 v115, v125, v125
	v_add_f32_e32 v112, v115, v112
	ds_bpermute_b32 v113, v120, v112
	v_lshlrev_b32_e32 v116, 2, v121
	global_store_dwordx4 v[178:179], v[122:125], off offset:512
	global_store_dwordx4 v[178:179], v[164:167], off offset:528
	s_waitcnt lgkmcnt(0)
	v_add_f32_e32 v112, v112, v113
	ds_bpermute_b32 v113, v116, v112
	v_cvt_pk_bf16_f32 v122, v122, v123
	v_cvt_pk_bf16_f32 v123, v124, v125
	v_cvt_pk_bf16_f32 v124, v164, v165
	v_cvt_pk_bf16_f32 v125, v166, v167
	global_store_dwordx4 v[176:177], v[122:125], off offset:256
	s_and_saveexec_b64 s[46:47], s[4:5]
	s_cbranch_execz .LBB0_635
	v_lshl_add_u64 v[114:115], v[150:151], 2, s[18:19]
	s_waitcnt lgkmcnt(0)
	v_add_f32_e32 v112, v112, v113
	global_atomic_add_f32 v[114:115], v112, off

.LBB0_697:
	ds_read_b128 v[144:147], v157
	ds_read_b128 v[148:151], v157 offset:1024
	ds_read_b128 v[162:165], v157 offset:2048
	ds_read_b128 v[166:169], v157 offset:3072
	s_add_u32 s48, s6, 0xfffc0080
	s_addc_u32 s49, s7, -1
	s_cmp_eq_u32 s71, 12
	s_cselect_b32 s51, s39, s49
	s_cselect_b32 s50, s67, s48
	s_cselect_b32 s49, s37, s70
	s_cselect_b32 s48, s68, s69
	v_lshl_add_u64 v[202:203], s[6:7], 0, v[136:137]
	s_add_i32 m0, s47, 0xc000
	ds_read_b128 v[170:173], v158
	ds_read_b128 v[174:177], v158 offset:1024
	ds_read_b128 v[178:181], v158 offset:2048
	ds_read_b128 v[182:185], v158 offset:3072
	ds_read_b128 v[186:189], v158 offset:4096
	ds_read_b128 v[190:193], v158 offset:5120
	ds_read_b128 v[194:197], v158 offset:6144
	ds_read_b128 v[198:201], v158 offset:7168
	global_load_lds_dwordx4 v[202:203], off
	s_add_i32 m0, s47, 0xe000
	v_lshl_add_u64 v[202:203], s[6:7], 0, v[138:139]
	global_load_lds_dwordx4 v[202:203], off
	s_waitcnt lgkmcnt(8)
	s_barrier
	s_waitcnt lgkmcnt(0)
	v_mfma_f32_16x16x32_bf16 v[124:127], v[144:147], v[170:173], v[124:127]
	v_mfma_f32_16x16x32_bf16 v[120:123], v[162:165], v[170:173], v[120:123]
	v_mfma_f32_16x16x32_bf16 v[108:111], v[144:147], v[178:181], v[108:111]
	v_mfma_f32_16x16x32_bf16 v[104:107], v[162:165], v[178:181], v[104:107]
	v_mfma_f32_16x16x32_bf16 v[92:95], v[144:147], v[186:189], v[92:95]
	v_mfma_f32_16x16x32_bf16 v[88:91], v[162:165], v[186:189], v[88:91]
	v_mfma_f32_16x16x32_bf16 v[76:79], v[144:147], v[194:197], v[76:79]
	v_mfma_f32_16x16x32_bf16 v[72:75], v[162:165], v[194:197], v[72:75]
	v_mfma_f32_16x16x32_bf16 v[124:127], v[148:151], v[174:177], v[124:127]
	v_mfma_f32_16x16x32_bf16 v[120:123], v[166:169], v[174:177], v[120:123]
	v_mfma_f32_16x16x32_bf16 v[108:111], v[148:151], v[182:185], v[108:111]
	v_mfma_f32_16x16x32_bf16 v[104:107], v[166:169], v[182:185], v[104:107]
	v_mfma_f32_16x16x32_bf16 v[92:95], v[148:151], v[190:193], v[92:95]
	v_mfma_f32_16x16x32_bf16 v[88:91], v[166:169], v[190:193], v[88:91]
	v_mfma_f32_16x16x32_bf16 v[76:79], v[148:151], v[198:201], v[76:79]
	v_mfma_f32_16x16x32_bf16 v[72:75], v[166:169], v[198:201], v[72:75]
	s_barrier
	s_add_i32 s73, s60, s34
	v_lshl_add_u64 v[218:219], s[48:49], 0, v[132:133]
	s_mov_b32 m0, s73
	ds_read_b128 v[202:205], v159
	ds_read_b128 v[206:209], v159 offset:1024
	ds_read_b128 v[210:213], v159 offset:2048
	ds_read_b128 v[214:217], v159 offset:3072
	global_load_lds_dwordx4 v[218:219], off
	s_add_i32 m0, s73, 0x2000
	v_lshl_add_u64 v[220:221], s[48:49], 0, v[128:129]
	global_load_lds_dwordx4 v[220:221], off
	s_barrier
	s_waitcnt lgkmcnt(0)
	v_mfma_f32_16x16x32_bf16 v[116:119], v[202:205], v[170:173], v[116:119]
	v_mfma_f32_16x16x32_bf16 v[112:115], v[210:213], v[170:173], v[112:115]
	v_mfma_f32_16x16x32_bf16 v[100:103], v[202:205], v[178:181], v[100:103]
	v_mfma_f32_16x16x32_bf16 v[96:99], v[210:213], v[178:181], v[96:99]
	v_mfma_f32_16x16x32_bf16 v[84:87], v[202:205], v[186:189], v[84:87]
	v_mfma_f32_16x16x32_bf16 v[80:83], v[210:213], v[186:189], v[80:83]
	v_mfma_f32_16x16x32_bf16 v[68:71], v[202:205], v[194:197], v[68:71]
	v_mfma_f32_16x16x32_bf16 v[64:67], v[210:213], v[194:197], v[64:67]
	v_mfma_f32_16x16x32_bf16 v[116:119], v[206:209], v[174:177], v[116:119]
	v_mfma_f32_16x16x32_bf16 v[112:115], v[214:217], v[174:177], v[112:115]
	v_mfma_f32_16x16x32_bf16 v[100:103], v[206:209], v[182:185], v[100:103]
	v_mfma_f32_16x16x32_bf16 v[96:99], v[214:217], v[182:185], v[96:99]
	v_mfma_f32_16x16x32_bf16 v[84:87], v[206:209], v[190:193], v[84:87]
	v_mfma_f32_16x16x32_bf16 v[80:83], v[214:217], v[190:193], v[80:83]
	v_mfma_f32_16x16x32_bf16 v[68:71], v[206:209], v[198:201], v[68:71]
	v_mfma_f32_16x16x32_bf16 v[64:67], v[214:217], v[198:201], v[64:67]
	s_mov_b32 m0, s47
	v_lshl_add_u64 v[222:223], s[50:51], 0, v[134:135]
	s_barrier
	ds_read_b128 v[170:173], v158 offset:16384
	ds_read_b128 v[174:177], v158 offset:17408
	ds_read_b128 v[178:181], v158 offset:18432
	ds_read_b128 v[182:185], v158 offset:19456
	ds_read_b128 v[186:189], v158 offset:20480
	ds_read_b128 v[190:193], v158 offset:21504
	ds_read_b128 v[194:197], v158 offset:22528
	ds_read_b128 v[198:201], v158 offset:23552
	global_load_lds_dwordx4 v[222:223], off
	s_mov_b32 m0, s53
	v_lshl_add_u64 v[224:225], s[50:51], 0, v[130:131]
	global_load_lds_dwordx4 v[224:225], off
	s_barrier
	s_waitcnt lgkmcnt(0)
	v_mfma_f32_16x16x32_bf16 v[60:63], v[144:147], v[170:173], v[60:63]
	v_mfma_f32_16x16x32_bf16 v[56:59], v[162:165], v[170:173], v[56:59]
	v_mfma_f32_16x16x32_bf16 v[44:47], v[144:147], v[178:181], v[44:47]
	v_mfma_f32_16x16x32_bf16 v[40:43], v[162:165], v[178:181], v[40:43]
	v_mfma_f32_16x16x32_bf16 v[28:31], v[144:147], v[186:189], v[28:31]
	v_mfma_f32_16x16x32_bf16 v[24:27], v[162:165], v[186:189], v[24:27]
	v_mfma_f32_16x16x32_bf16 v[12:15], v[144:147], v[194:197], v[12:15]
	v_mfma_f32_16x16x32_bf16 v[8:11], v[162:165], v[194:197], v[8:11]
	v_mfma_f32_16x16x32_bf16 v[60:63], v[148:151], v[174:177], v[60:63]
	v_mfma_f32_16x16x32_bf16 v[56:59], v[166:169], v[174:177], v[56:59]
	v_mfma_f32_16x16x32_bf16 v[44:47], v[148:151], v[182:185], v[44:47]
	v_mfma_f32_16x16x32_bf16 v[40:43], v[166:169], v[182:185], v[40:43]
	v_mfma_f32_16x16x32_bf16 v[28:31], v[148:151], v[190:193], v[28:31]
	v_mfma_f32_16x16x32_bf16 v[24:27], v[166:169], v[190:193], v[24:27]
	v_mfma_f32_16x16x32_bf16 v[12:15], v[148:151], v[198:201], v[12:15]
	v_mfma_f32_16x16x32_bf16 v[8:11], v[166:169], v[198:201], v[8:11]
	s_barrier
	s_add_u32 s74, s48, 0x40000
	s_addc_u32 s75, s49, 0
	s_add_i32 s73, s72, s34
	s_mov_b32 m0, s73
	v_lshl_add_u64 v[144:145], s[74:75], 0, v[132:133]
	global_load_lds_dwordx4 v[144:145], off
	s_add_i32 m0, s73, 0x2000
	v_lshl_add_u64 v[144:145], s[74:75], 0, v[128:129]
	global_load_lds_dwordx4 v[144:145], off
	s_waitcnt vmcnt(6)
	s_barrier
	v_mfma_f32_16x16x32_bf16 v[52:55], v[202:205], v[170:173], v[52:55]
	v_mfma_f32_16x16x32_bf16 v[48:51], v[210:213], v[170:173], v[48:51]
	v_mfma_f32_16x16x32_bf16 v[36:39], v[202:205], v[178:181], v[36:39]
	v_mfma_f32_16x16x32_bf16 v[32:35], v[210:213], v[178:181], v[32:35]
	v_mfma_f32_16x16x32_bf16 v[20:23], v[202:205], v[186:189], v[20:23]
	v_mfma_f32_16x16x32_bf16 v[16:19], v[210:213], v[186:189], v[16:19]
	v_mfma_f32_16x16x32_bf16 v[4:7], v[202:205], v[194:197], v[4:7]
	v_mfma_f32_16x16x32_bf16 v[0:3], v[210:213], v[194:197], v[0:3]
	v_mfma_f32_16x16x32_bf16 v[52:55], v[206:209], v[174:177], v[52:55]
	v_mfma_f32_16x16x32_bf16 v[48:51], v[214:217], v[174:177], v[48:51]
	v_mfma_f32_16x16x32_bf16 v[36:39], v[206:209], v[182:185], v[36:39]
	v_mfma_f32_16x16x32_bf16 v[32:35], v[214:217], v[182:185], v[32:35]
	v_mfma_f32_16x16x32_bf16 v[20:23], v[206:209], v[190:193], v[20:23]
	v_mfma_f32_16x16x32_bf16 v[16:19], v[214:217], v[190:193], v[16:19]
	v_mfma_f32_16x16x32_bf16 v[4:7], v[206:209], v[198:201], v[4:7]
	v_mfma_f32_16x16x32_bf16 v[0:3], v[214:217], v[198:201], v[0:3]
	s_add_i32 s73, 0, 0x18000
	v_add_u32_e32 v161, s73, v153
	s_barrier
	ds_read_b128 v[144:147], v161
	ds_read_b128 v[148:151], v161 offset:1024
	ds_read_b128 v[162:165], v161 offset:2048
	ds_read_b128 v[166:169], v161 offset:3072
	s_add_u32 s50, s50, 0x40000
	s_addc_u32 s51, s51, 0
	s_mov_b32 m0, s54
	v_lshl_add_u64 v[202:203], s[50:51], 0, v[134:135]
	ds_read_b128 v[170:173], v158 offset:32768
	ds_read_b128 v[174:177], v158 offset:33792
	ds_read_b128 v[178:181], v158 offset:34816
	ds_read_b128 v[182:185], v158 offset:35840
	ds_read_b128 v[186:189], v158 offset:36864
	ds_read_b128 v[190:193], v158 offset:37888
	ds_read_b128 v[194:197], v158 offset:38912
	ds_read_b128 v[198:201], v158 offset:39936
	global_load_lds_dwordx4 v[202:203], off
	s_mov_b32 m0, s55
	v_lshl_add_u64 v[202:203], s[50:51], 0, v[130:131]
	global_load_lds_dwordx4 v[202:203], off
	s_waitcnt lgkmcnt(8)
	s_barrier
	s_waitcnt lgkmcnt(0)
	v_mfma_f32_16x16x32_bf16 v[124:127], v[144:147], v[170:173], v[124:127]
	v_mfma_f32_16x16x32_bf16 v[120:123], v[162:165], v[170:173], v[120:123]
	v_mfma_f32_16x16x32_bf16 v[108:111], v[144:147], v[178:181], v[108:111]
	v_mfma_f32_16x16x32_bf16 v[104:107], v[162:165], v[178:181], v[104:107]
	v_mfma_f32_16x16x32_bf16 v[92:95], v[144:147], v[186:189], v[92:95]
	v_mfma_f32_16x16x32_bf16 v[88:91], v[162:165], v[186:189], v[88:91]
	v_mfma_f32_16x16x32_bf16 v[76:79], v[144:147], v[194:197], v[76:79]
	v_mfma_f32_16x16x32_bf16 v[72:75], v[162:165], v[194:197], v[72:75]
	v_mfma_f32_16x16x32_bf16 v[124:127], v[148:151], v[174:177], v[124:127]
	v_mfma_f32_16x16x32_bf16 v[120:123], v[166:169], v[174:177], v[120:123]
	v_mfma_f32_16x16x32_bf16 v[108:111], v[148:151], v[182:185], v[108:111]
	v_mfma_f32_16x16x32_bf16 v[104:107], v[166:169], v[182:185], v[104:107]
	v_mfma_f32_16x16x32_bf16 v[92:95], v[148:151], v[190:193], v[92:95]
	v_mfma_f32_16x16x32_bf16 v[88:91], v[166:169], v[190:193], v[88:91]
	v_mfma_f32_16x16x32_bf16 v[76:79], v[148:151], v[198:201], v[76:79]
	v_mfma_f32_16x16x32_bf16 v[72:75], v[166:169], v[198:201], v[72:75]
	s_barrier
	s_add_i32 s50, s73, s34
	v_add_u32_e32 v161, s97, v153
	v_lshl_add_u64 v[218:219], v[218:219], 0, s[14:15]
	s_mov_b32 m0, s50
	ds_read_b128 v[202:205], v161
	ds_read_b128 v[206:209], v161 offset:1024
	ds_read_b128 v[210:213], v161 offset:2048
	ds_read_b128 v[214:217], v161 offset:3072
	global_load_lds_dwordx4 v[218:219], off
	s_add_i32 m0, s50, 0x2000
	v_lshl_add_u64 v[218:219], v[220:221], 0, s[14:15]
	global_load_lds_dwordx4 v[218:219], off
	s_barrier
	s_waitcnt lgkmcnt(0)
	v_mfma_f32_16x16x32_bf16 v[116:119], v[202:205], v[170:173], v[116:119]
	v_mfma_f32_16x16x32_bf16 v[112:115], v[210:213], v[170:173], v[112:115]
	v_mfma_f32_16x16x32_bf16 v[100:103], v[202:205], v[178:181], v[100:103]
	v_mfma_f32_16x16x32_bf16 v[96:99], v[210:213], v[178:181], v[96:99]
	v_mfma_f32_16x16x32_bf16 v[84:87], v[202:205], v[186:189], v[84:87]
	v_mfma_f32_16x16x32_bf16 v[80:83], v[210:213], v[186:189], v[80:83]
	v_mfma_f32_16x16x32_bf16 v[68:71], v[202:205], v[194:197], v[68:71]
	v_mfma_f32_16x16x32_bf16 v[64:67], v[210:213], v[194:197], v[64:67]
	v_mfma_f32_16x16x32_bf16 v[116:119], v[206:209], v[174:177], v[116:119]
	v_mfma_f32_16x16x32_bf16 v[112:115], v[214:217], v[174:177], v[112:115]
	v_mfma_f32_16x16x32_bf16 v[100:103], v[206:209], v[182:185], v[100:103]
	v_mfma_f32_16x16x32_bf16 v[96:99], v[214:217], v[182:185], v[96:99]
	v_mfma_f32_16x16x32_bf16 v[84:87], v[206:209], v[190:193], v[84:87]
	v_mfma_f32_16x16x32_bf16 v[80:83], v[214:217], v[190:193], v[80:83]
	v_mfma_f32_16x16x32_bf16 v[68:71], v[206:209], v[198:201], v[68:71]
	v_mfma_f32_16x16x32_bf16 v[64:67], v[214:217], v[198:201], v[64:67]
	s_mov_b32 m0, s57
	v_lshl_add_u64 v[218:219], v[222:223], 0, s[14:15]
	s_barrier
	ds_read_b128 v[170:173], v158 offset:49152
	ds_read_b128 v[174:177], v158 offset:50176
	ds_read_b128 v[178:181], v158 offset:51200
	ds_read_b128 v[182:185], v158 offset:52224
	ds_read_b128 v[186:189], v158 offset:53248
	ds_read_b128 v[190:193], v158 offset:54272
	ds_read_b128 v[194:197], v158 offset:55296
	ds_read_b128 v[198:201], v158 offset:56320
	global_load_lds_dwordx4 v[218:219], off
	s_mov_b32 m0, s58
	v_lshl_add_u64 v[218:219], v[224:225], 0, s[14:15]
	global_load_lds_dwordx4 v[218:219], off
	s_barrier
	s_waitcnt lgkmcnt(0)
	v_mfma_f32_16x16x32_bf16 v[60:63], v[144:147], v[170:173], v[60:63]
	v_mfma_f32_16x16x32_bf16 v[56:59], v[162:165], v[170:173], v[56:59]
	v_mfma_f32_16x16x32_bf16 v[44:47], v[144:147], v[178:181], v[44:47]
	v_mfma_f32_16x16x32_bf16 v[40:43], v[162:165], v[178:181], v[40:43]
	v_mfma_f32_16x16x32_bf16 v[28:31], v[144:147], v[186:189], v[28:31]
	v_mfma_f32_16x16x32_bf16 v[24:27], v[162:165], v[186:189], v[24:27]
	v_mfma_f32_16x16x32_bf16 v[12:15], v[144:147], v[194:197], v[12:15]
	v_mfma_f32_16x16x32_bf16 v[8:11], v[162:165], v[194:197], v[8:11]
	v_mfma_f32_16x16x32_bf16 v[60:63], v[148:151], v[174:177], v[60:63]
	v_mfma_f32_16x16x32_bf16 v[56:59], v[166:169], v[174:177], v[56:59]
	v_mfma_f32_16x16x32_bf16 v[44:47], v[148:151], v[182:185], v[44:47]
	v_mfma_f32_16x16x32_bf16 v[40:43], v[166:169], v[182:185], v[40:43]
	v_mfma_f32_16x16x32_bf16 v[28:31], v[148:151], v[190:193], v[28:31]
	v_mfma_f32_16x16x32_bf16 v[24:27], v[166:169], v[190:193], v[24:27]
	v_mfma_f32_16x16x32_bf16 v[12:15], v[148:151], v[198:201], v[12:15]
	v_mfma_f32_16x16x32_bf16 v[8:11], v[166:169], v[198:201], v[8:11]
	s_barrier
	s_add_u32 s48, s48, 0x40080
	s_addc_u32 s49, s49, 0
	s_add_i32 s50, s97, s34
	s_mov_b32 m0, s50
	v_lshl_add_u64 v[144:145], s[48:49], 0, v[132:133]
	global_load_lds_dwordx4 v[144:145], off
	s_add_i32 m0, s50, 0x2000
	v_lshl_add_u64 v[144:145], s[48:49], 0, v[128:129]
	global_load_lds_dwordx4 v[144:145], off
	s_waitcnt vmcnt(6)
	s_barrier
	v_mfma_f32_16x16x32_bf16 v[52:55], v[202:205], v[170:173], v[52:55]
	v_mfma_f32_16x16x32_bf16 v[48:51], v[210:213], v[170:173], v[48:51]
	v_mfma_f32_16x16x32_bf16 v[36:39], v[202:205], v[178:181], v[36:39]
	v_mfma_f32_16x16x32_bf16 v[32:35], v[210:213], v[178:181], v[32:35]
	v_mfma_f32_16x16x32_bf16 v[20:23], v[202:205], v[186:189], v[20:23]
	v_mfma_f32_16x16x32_bf16 v[16:19], v[210:213], v[186:189], v[16:19]
	v_mfma_f32_16x16x32_bf16 v[4:7], v[202:205], v[194:197], v[4:7]
	v_mfma_f32_16x16x32_bf16 v[0:3], v[210:213], v[194:197], v[0:3]
	v_mfma_f32_16x16x32_bf16 v[52:55], v[206:209], v[174:177], v[52:55]
	v_mfma_f32_16x16x32_bf16 v[48:51], v[214:217], v[174:177], v[48:51]
	v_mfma_f32_16x16x32_bf16 v[36:39], v[206:209], v[182:185], v[36:39]
	v_mfma_f32_16x16x32_bf16 v[32:35], v[214:217], v[182:185], v[32:35]
	v_mfma_f32_16x16x32_bf16 v[20:23], v[206:209], v[190:193], v[20:23]
	v_mfma_f32_16x16x32_bf16 v[16:19], v[214:217], v[190:193], v[16:19]
	v_mfma_f32_16x16x32_bf16 v[4:7], v[206:209], v[198:201], v[4:7]
	v_mfma_f32_16x16x32_bf16 v[0:3], v[214:217], v[198:201], v[0:3]
	s_add_i32 s71, s71, 2
	s_add_u32 s6, s6, 0x100
	s_addc_u32 s7, s7, 0
	s_add_u32 s69, s69, 0x100
	s_addc_u32 s70, s70, 0
	s_cmp_gt_u32 s71, 13
	s_barrier
	s_cbranch_scc0 .LBB0_697
	v_lshl_add_u32 v148, s46, 8, v152
	v_ashrrev_i32_e32 v149, 31, v148
	v_lshl_add_u64 v[144:145], v[148:149], 2, s[18:19]
	global_load_dword v151, v[144:145], off
	v_lshlrev_b64 v[146:147], 12, v[148:149]
	s_cmp_lt_i32 s66, 8
	s_cselect_b32 s7, s1, s29
	s_cselect_b32 s6, s0, s28
	s_cselect_b32 s37, 0, 0xfffff800
	s_lshl_b32 s39, s66, 8
	s_add_i32 s37, s37, s39
	v_or_b32_e32 v150, s37, v156
	v_or_b32_e32 v162, 16, v148
	v_lshl_add_u64 v[146:147], s[6:7], 0, v[146:147]
	v_ashrrev_i32_e32 v163, 31, v162
	v_lshl_add_u64 v[164:165], v[162:163], 2, s[18:19]
	s_mov_b32 s46, s38
	s_mov_b64 s[48:49], s[44:45]
	s_mov_b64 s[50:51], s[40:41]
	s_mov_b32 s66, s36
	s_waitcnt vmcnt(0)
	v_fmamk_f32 v149, v151, 0x3a800000, v160
	v_mul_f32_e32 v151, 0x4b800000, v149
	v_cmp_gt_f32_e32 vcc, s61, v149
	s_nop 1
	v_cndmask_b32_e32 v149, v149, v151, vcc
	v_rsq_f32_e32 v149, v149
	v_ashrrev_i32_e32 v151, 31, v150
	v_lshlrev_b64 v[150:151], 1, v[150:151]
	v_lshl_add_u64 v[146:147], v[146:147], 0, v[150:151]
	v_mul_f32_e32 v161, 0x45800000, v149
	v_cndmask_b32_e32 v149, v149, v161, vcc
	v_mul_f32_e32 v124, v124, v149
	v_mul_f32_e32 v120, v120, v149
	v_mul_f32_e32 v125, v125, v149
	v_mul_f32_e32 v121, v121, v149
	v_mul_f32_e32 v126, v126, v149
	v_mul_f32_e32 v122, v122, v149
	v_mul_f32_e32 v127, v127, v149
	v_mul_f32_e32 v123, v123, v149
	v_mul_f32_e32 v161, v116, v149
	v_mul_f32_e32 v166, v112, v149
	v_mul_f32_e32 v167, v117, v149
	v_mul_f32_e32 v168, v113, v149
	v_mul_f32_e32 v169, v118, v149
	v_mul_f32_e32 v170, v114, v149
	v_mul_f32_e32 v171, v119, v149
	v_mul_f32_e32 v149, v115, v149
	v_max_f32_e32 v112, 0, v124
	v_max_f32_e32 v114, 0, v120
	v_max_f32_e32 v113, 0, v125
	v_max_f32_e32 v115, 0, v121
	v_max_f32_e32 v116, 0, v126
	v_max_f32_e32 v118, 0, v122
	v_max_f32_e32 v117, 0, v127
	v_max_f32_e32 v119, 0, v123
	v_max_f32_e32 v120, 0, v161
	v_max_f32_e32 v122, 0, v166
	v_max_f32_e32 v121, 0, v167
	v_max_f32_e32 v123, 0, v168
	v_max_f32_e32 v124, 0, v169
	v_max_f32_e32 v126, 0, v170
	v_max_f32_e32 v125, 0, v171
	v_max_f32_e32 v127, 0, v149
	v_pk_mul_f32 v[112:113], v[112:113], v[112:113]
	v_pk_mul_f32 v[114:115], v[114:115], v[114:115]
	v_pk_mul_f32 v[116:117], v[116:117], v[116:117]
	v_pk_mul_f32 v[118:119], v[118:119], v[118:119]
	v_pk_mul_f32 v[120:121], v[120:121], v[120:121]
	v_pk_mul_f32 v[122:123], v[122:123], v[122:123]
	v_pk_mul_f32 v[124:125], v[124:125], v[124:125]
	v_pk_mul_f32 v[126:127], v[126:127], v[126:127]
	v_cvt_pk_bf16_f32 v112, v112, v113
	v_cvt_pk_bf16_f32 v113, v116, v117
	v_cvt_pk_bf16_f32 v114, v114, v115
	v_cvt_pk_bf16_f32 v115, v118, v119
	v_cvt_pk_bf16_f32 v116, v120, v121
	v_cvt_pk_bf16_f32 v117, v124, v125
	v_cvt_pk_bf16_f32 v118, v122, v123
	v_cvt_pk_bf16_f32 v119, v126, v127
	global_store_dwordx4 v[146:147], v[112:115], off
	global_store_dwordx4 v[146:147], v[116:119], off offset:256
	global_load_dword v116, v[164:165], off
	v_lshlrev_b64 v[114:115], 12, v[162:163]
	v_or_b32_e32 v112, 32, v148
	v_lshl_add_u64 v[114:115], s[6:7], 0, v[114:115]
	v_ashrrev_i32_e32 v113, 31, v112
	v_lshl_add_u64 v[114:115], v[114:115], 0, v[150:151]
	s_waitcnt vmcnt(0)
	v_fmamk_f32 v116, v116, 0x3a800000, v160
	v_mul_f32_e32 v117, 0x4b800000, v116
	v_cmp_gt_f32_e32 vcc, s61, v116
	s_nop 1
	v_cndmask_b32_e32 v116, v116, v117, vcc
	v_rsq_f32_e32 v118, v116
	v_lshl_add_u64 v[116:117], v[112:113], 2, s[18:19]
	v_mul_f32_e32 v119, 0x45800000, v118
	v_cndmask_b32_e32 v118, v118, v119, vcc
	v_mul_f32_e32 v108, v108, v118
	v_mul_f32_e32 v104, v104, v118
	v_mul_f32_e32 v109, v109, v118
	v_mul_f32_e32 v105, v105, v118
	v_mul_f32_e32 v110, v110, v118
	v_mul_f32_e32 v106, v106, v118
	v_mul_f32_e32 v111, v111, v118
	v_mul_f32_e32 v107, v107, v118
	v_mul_f32_e32 v119, v100, v118
	v_mul_f32_e32 v120, v96, v118
	v_mul_f32_e32 v121, v101, v118
	v_mul_f32_e32 v122, v97, v118
	v_mul_f32_e32 v123, v102, v118
	v_mul_f32_e32 v124, v98, v118
	v_mul_f32_e32 v125, v103, v118
	v_mul_f32_e32 v118, v99, v118
	v_max_f32_e32 v96, 0, v108
	v_max_f32_e32 v98, 0, v104
	v_max_f32_e32 v97, 0, v109
	v_max_f32_e32 v99, 0, v105
	v_max_f32_e32 v100, 0, v110
	v_max_f32_e32 v102, 0, v106
	v_max_f32_e32 v101, 0, v111
	v_max_f32_e32 v103, 0, v107
	v_max_f32_e32 v104, 0, v119
	v_max_f32_e32 v106, 0, v120
	v_max_f32_e32 v105, 0, v121
	v_max_f32_e32 v107, 0, v122
	v_max_f32_e32 v108, 0, v123
	v_max_f32_e32 v110, 0, v124
	v_max_f32_e32 v109, 0, v125
	v_max_f32_e32 v111, 0, v118
	v_pk_mul_f32 v[96:97], v[96:97], v[96:97]
	v_pk_mul_f32 v[98:99], v[98:99], v[98:99]
	v_pk_mul_f32 v[100:101], v[100:101], v[100:101]
	v_pk_mul_f32 v[102:103], v[102:103], v[102:103]
	v_pk_mul_f32 v[104:105], v[104:105], v[104:105]
	v_pk_mul_f32 v[106:107], v[106:107], v[106:107]
	v_pk_mul_f32 v[108:109], v[108:109], v[108:109]
	v_pk_mul_f32 v[110:111], v[110:111], v[110:111]
	v_cvt_pk_bf16_f32 v96, v96, v97
	v_cvt_pk_bf16_f32 v97, v100, v101
	v_cvt_pk_bf16_f32 v98, v98, v99
	v_cvt_pk_bf16_f32 v99, v102, v103
	v_cvt_pk_bf16_f32 v100, v104, v105
	v_cvt_pk_bf16_f32 v101, v108, v109
	v_cvt_pk_bf16_f32 v102, v106, v107
	v_cvt_pk_bf16_f32 v103, v110, v111
	global_store_dwordx4 v[114:115], v[96:99], off
	global_store_dwordx4 v[114:115], v[100:103], off offset:256
	global_load_dword v100, v[116:117], off
	v_lshlrev_b64 v[98:99], 12, v[112:113]
	v_or_b32_e32 v96, 48, v148
	v_lshl_add_u64 v[98:99], s[6:7], 0, v[98:99]
	v_ashrrev_i32_e32 v97, 31, v96
	v_lshl_add_u64 v[98:99], v[98:99], 0, v[150:151]
	s_waitcnt vmcnt(0)
	v_fmamk_f32 v100, v100, 0x3a800000, v160
	v_mul_f32_e32 v101, 0x4b800000, v100
	v_cmp_gt_f32_e32 vcc, s61, v100
	s_nop 1
	v_cndmask_b32_e32 v100, v100, v101, vcc
	v_rsq_f32_e32 v102, v100
	v_lshl_add_u64 v[100:101], v[96:97], 2, s[18:19]
	v_mul_f32_e32 v103, 0x45800000, v102
	v_cndmask_b32_e32 v102, v102, v103, vcc
	v_mul_f32_e32 v92, v92, v102
	v_mul_f32_e32 v88, v88, v102
	v_mul_f32_e32 v93, v93, v102
	v_mul_f32_e32 v89, v89, v102
	v_mul_f32_e32 v94, v94, v102
	v_mul_f32_e32 v90, v90, v102
	v_mul_f32_e32 v95, v95, v102
	v_mul_f32_e32 v91, v91, v102
	v_mul_f32_e32 v103, v84, v102
	v_mul_f32_e32 v104, v80, v102
	v_mul_f32_e32 v105, v85, v102
	v_mul_f32_e32 v106, v81, v102
	v_mul_f32_e32 v107, v86, v102
	v_mul_f32_e32 v108, v82, v102
	v_mul_f32_e32 v109, v87, v102
	v_mul_f32_e32 v102, v83, v102
	v_max_f32_e32 v80, 0, v92
	v_max_f32_e32 v82, 0, v88
	v_max_f32_e32 v81, 0, v93
	v_max_f32_e32 v83, 0, v89
	v_max_f32_e32 v84, 0, v94
	v_max_f32_e32 v86, 0, v90
	v_max_f32_e32 v85, 0, v95
	v_max_f32_e32 v87, 0, v91
	v_max_f32_e32 v88, 0, v103
	v_max_f32_e32 v90, 0, v104
	v_max_f32_e32 v89, 0, v105
	v_max_f32_e32 v91, 0, v106
	v_max_f32_e32 v92, 0, v107
	v_max_f32_e32 v94, 0, v108
	v_max_f32_e32 v93, 0, v109
	v_max_f32_e32 v95, 0, v102
	v_pk_mul_f32 v[80:81], v[80:81], v[80:81]
	v_pk_mul_f32 v[82:83], v[82:83], v[82:83]
	v_pk_mul_f32 v[84:85], v[84:85], v[84:85]
	v_pk_mul_f32 v[86:87], v[86:87], v[86:87]
	v_pk_mul_f32 v[88:89], v[88:89], v[88:89]
	v_pk_mul_f32 v[90:91], v[90:91], v[90:91]
	v_pk_mul_f32 v[92:93], v[92:93], v[92:93]
	v_pk_mul_f32 v[94:95], v[94:95], v[94:95]
	v_cvt_pk_bf16_f32 v80, v80, v81
	v_cvt_pk_bf16_f32 v81, v84, v85
	v_cvt_pk_bf16_f32 v82, v82, v83
	v_cvt_pk_bf16_f32 v83, v86, v87
	v_cvt_pk_bf16_f32 v84, v88, v89
	v_cvt_pk_bf16_f32 v85, v92, v93
	v_cvt_pk_bf16_f32 v86, v90, v91
	v_cvt_pk_bf16_f32 v87, v94, v95
	global_store_dwordx4 v[98:99], v[80:83], off
	global_store_dwordx4 v[98:99], v[84:87], off offset:256
	global_load_dword v80, v[100:101], off
	s_waitcnt vmcnt(0)
	v_fmamk_f32 v80, v80, 0x3a800000, v160
	v_mul_f32_e32 v81, 0x4b800000, v80
	v_cmp_gt_f32_e32 vcc, s61, v80
	s_nop 1
	v_cndmask_b32_e32 v80, v80, v81, vcc
	v_rsq_f32_e32 v82, v80
	v_lshlrev_b64 v[80:81], 12, v[96:97]
	v_lshl_add_u64 v[80:81], s[6:7], 0, v[80:81]
	v_lshl_add_u64 v[80:81], v[80:81], 0, v[150:151]
	v_mul_f32_e32 v83, 0x45800000, v82
	v_cndmask_b32_e32 v82, v82, v83, vcc
	v_mul_f32_e32 v76, v76, v82
	v_mul_f32_e32 v72, v72, v82
	v_mul_f32_e32 v77, v77, v82
	v_mul_f32_e32 v73, v73, v82
	v_mul_f32_e32 v78, v78, v82
	v_mul_f32_e32 v74, v74, v82
	v_mul_f32_e32 v79, v79, v82
	v_mul_f32_e32 v75, v75, v82
	v_mul_f32_e32 v83, v68, v82
	v_mul_f32_e32 v84, v64, v82
	v_mul_f32_e32 v85, v69, v82
	v_mul_f32_e32 v86, v65, v82
	v_mul_f32_e32 v87, v70, v82
	v_mul_f32_e32 v88, v66, v82
	v_mul_f32_e32 v89, v71, v82
	v_mul_f32_e32 v82, v67, v82
	v_max_f32_e32 v64, 0, v76
	v_max_f32_e32 v66, 0, v72
	v_max_f32_e32 v65, 0, v77
	v_max_f32_e32 v67, 0, v73
	v_max_f32_e32 v68, 0, v78
	v_max_f32_e32 v70, 0, v74
	v_max_f32_e32 v69, 0, v79
	v_max_f32_e32 v71, 0, v75
	v_max_f32_e32 v72, 0, v83
	v_max_f32_e32 v74, 0, v84
	v_max_f32_e32 v73, 0, v85
	v_max_f32_e32 v75, 0, v86
	v_max_f32_e32 v76, 0, v87
	v_max_f32_e32 v78, 0, v88
	v_max_f32_e32 v77, 0, v89
	v_max_f32_e32 v79, 0, v82
	v_pk_mul_f32 v[64:65], v[64:65], v[64:65]
	v_pk_mul_f32 v[66:67], v[66:67], v[66:67]
	v_pk_mul_f32 v[68:69], v[68:69], v[68:69]
	v_pk_mul_f32 v[70:71], v[70:71], v[70:71]
	v_pk_mul_f32 v[72:73], v[72:73], v[72:73]
	v_pk_mul_f32 v[74:75], v[74:75], v[74:75]
	v_pk_mul_f32 v[76:77], v[76:77], v[76:77]
	v_pk_mul_f32 v[78:79], v[78:79], v[78:79]
	v_cvt_pk_bf16_f32 v64, v64, v65
	v_cvt_pk_bf16_f32 v65, v68, v69
	v_cvt_pk_bf16_f32 v66, v66, v67
	v_cvt_pk_bf16_f32 v67, v70, v71
	v_cvt_pk_bf16_f32 v68, v72, v73
	v_cvt_pk_bf16_f32 v69, v76, v77
	v_cvt_pk_bf16_f32 v70, v74, v75
	v_cvt_pk_bf16_f32 v71, v78, v79
	global_store_dwordx4 v[80:81], v[64:67], off
	global_store_dwordx4 v[80:81], v[68:71], off offset:256
	global_load_dword v66, v[144:145], off offset:512
	v_lshl_add_u64 v[64:65], v[146:147], 0, s[16:17]
	s_waitcnt vmcnt(0)
	v_fmamk_f32 v66, v66, 0x3a800000, v160
	v_mul_f32_e32 v67, 0x4b800000, v66
	v_cmp_gt_f32_e32 vcc, s61, v66
	s_nop 1
	v_cndmask_b32_e32 v66, v66, v67, vcc
	v_rsq_f32_e32 v68, v66
	v_add_co_u32_e64 v66, s[6:7], s62, v146
	v_mul_f32_e32 v69, 0x45800000, v68
	v_cndmask_b32_e32 v68, v68, v69, vcc
	v_mul_f32_e32 v60, v60, v68
	v_mul_f32_e32 v56, v56, v68
	v_mul_f32_e32 v61, v61, v68
	v_mul_f32_e32 v57, v57, v68
	v_mul_f32_e32 v62, v62, v68
	v_mul_f32_e32 v58, v58, v68
	v_mul_f32_e32 v63, v63, v68
	v_mul_f32_e32 v59, v59, v68
	v_mul_f32_e32 v69, v52, v68
	v_mul_f32_e32 v70, v48, v68
	v_mul_f32_e32 v71, v53, v68
	v_mul_f32_e32 v72, v49, v68
	v_mul_f32_e32 v73, v54, v68
	v_mul_f32_e32 v74, v50, v68
	v_mul_f32_e32 v75, v55, v68
	v_mul_f32_e32 v68, v51, v68
	v_max_f32_e32 v48, 0, v60
	v_max_f32_e32 v50, 0, v56
	v_max_f32_e32 v49, 0, v61
	v_max_f32_e32 v51, 0, v57
	v_max_f32_e32 v52, 0, v62
	v_max_f32_e32 v54, 0, v58
	v_max_f32_e32 v53, 0, v63
	v_max_f32_e32 v55, 0, v59
	v_max_f32_e32 v56, 0, v69
	v_max_f32_e32 v58, 0, v70
	v_max_f32_e32 v57, 0, v71
	v_max_f32_e32 v59, 0, v72
	v_max_f32_e32 v60, 0, v73
	v_max_f32_e32 v62, 0, v74
	v_max_f32_e32 v61, 0, v75
	v_max_f32_e32 v63, 0, v68
	v_pk_mul_f32 v[48:49], v[48:49], v[48:49]
	v_pk_mul_f32 v[50:51], v[50:51], v[50:51]
	v_pk_mul_f32 v[52:53], v[52:53], v[52:53]
	v_pk_mul_f32 v[54:55], v[54:55], v[54:55]
	v_addc_co_u32_e64 v67, s[6:7], 0, v147, s[6:7]
	v_pk_mul_f32 v[56:57], v[56:57], v[56:57]
	v_pk_mul_f32 v[58:59], v[58:59], v[58:59]
	v_pk_mul_f32 v[60:61], v[60:61], v[60:61]
	v_pk_mul_f32 v[62:63], v[62:63], v[62:63]
	v_cvt_pk_bf16_f32 v48, v48, v49
	v_cvt_pk_bf16_f32 v49, v52, v53
	v_cvt_pk_bf16_f32 v50, v50, v51
	v_cvt_pk_bf16_f32 v51, v54, v55
	v_cvt_pk_bf16_f32 v52, v56, v57
	v_cvt_pk_bf16_f32 v53, v60, v61
	v_cvt_pk_bf16_f32 v54, v58, v59
	v_cvt_pk_bf16_f32 v55, v62, v63
	global_store_dwordx4 v[66:67], v[48:51], off
	global_store_dwordx4 v[64:65], v[52:55], off offset:256
	global_load_dword v50, v[144:145], off offset:576
	v_lshl_add_u64 v[48:49], v[146:147], 0, s[20:21]
	s_waitcnt vmcnt(0)
	v_fmamk_f32 v50, v50, 0x3a800000, v160
	v_mul_f32_e32 v51, 0x4b800000, v50
	v_cmp_gt_f32_e32 vcc, s61, v50
	s_nop 1
	v_cndmask_b32_e32 v50, v50, v51, vcc
	v_rsq_f32_e32 v52, v50
	v_add_co_u32_e64 v50, s[6:7], s63, v146
	v_mul_f32_e32 v53, 0x45800000, v52
	v_cndmask_b32_e32 v52, v52, v53, vcc
	v_mul_f32_e32 v44, v44, v52
	v_mul_f32_e32 v40, v40, v52
	v_mul_f32_e32 v45, v45, v52
	v_mul_f32_e32 v41, v41, v52
	v_mul_f32_e32 v46, v46, v52
	v_mul_f32_e32 v42, v42, v52
	v_mul_f32_e32 v47, v47, v52
	v_mul_f32_e32 v43, v43, v52
	v_mul_f32_e32 v53, v36, v52
	v_mul_f32_e32 v54, v32, v52
	v_mul_f32_e32 v55, v37, v52
	v_mul_f32_e32 v56, v33, v52
	v_mul_f32_e32 v57, v38, v52
	v_mul_f32_e32 v58, v34, v52
	v_mul_f32_e32 v59, v39, v52
	v_mul_f32_e32 v52, v35, v52
	v_max_f32_e32 v32, 0, v44
	v_max_f32_e32 v34, 0, v40
	v_max_f32_e32 v33, 0, v45
	v_max_f32_e32 v35, 0, v41
	v_max_f32_e32 v36, 0, v46
	v_max_f32_e32 v38, 0, v42
	v_max_f32_e32 v37, 0, v47
	v_max_f32_e32 v39, 0, v43
	v_max_f32_e32 v40, 0, v53
	v_max_f32_e32 v42, 0, v54
	v_max_f32_e32 v41, 0, v55
	v_max_f32_e32 v43, 0, v56
	v_max_f32_e32 v44, 0, v57
	v_max_f32_e32 v46, 0, v58
	v_max_f32_e32 v45, 0, v59
	v_max_f32_e32 v47, 0, v52
	v_pk_mul_f32 v[32:33], v[32:33], v[32:33]
	v_pk_mul_f32 v[34:35], v[34:35], v[34:35]
	v_pk_mul_f32 v[36:37], v[36:37], v[36:37]
	v_pk_mul_f32 v[38:39], v[38:39], v[38:39]
	v_addc_co_u32_e64 v51, s[6:7], 0, v147, s[6:7]
	v_pk_mul_f32 v[40:41], v[40:41], v[40:41]
	v_pk_mul_f32 v[42:43], v[42:43], v[42:43]
	v_pk_mul_f32 v[44:45], v[44:45], v[44:45]
	v_pk_mul_f32 v[46:47], v[46:47], v[46:47]
	v_cvt_pk_bf16_f32 v32, v32, v33
	v_cvt_pk_bf16_f32 v33, v36, v37
	v_cvt_pk_bf16_f32 v34, v34, v35
	v_cvt_pk_bf16_f32 v35, v38, v39
	v_cvt_pk_bf16_f32 v36, v40, v41
	v_cvt_pk_bf16_f32 v37, v44, v45
	v_cvt_pk_bf16_f32 v38, v42, v43
	v_cvt_pk_bf16_f32 v39, v46, v47
	global_store_dwordx4 v[50:51], v[32:35], off
	global_store_dwordx4 v[48:49], v[36:39], off offset:256
	global_load_dword v34, v[144:145], off offset:640
	v_lshl_add_u64 v[32:33], v[146:147], 0, s[22:23]
	s_waitcnt vmcnt(0)
	v_fmamk_f32 v34, v34, 0x3a800000, v160
	v_mul_f32_e32 v35, 0x4b800000, v34
	v_cmp_gt_f32_e32 vcc, s61, v34
	s_nop 1
	v_cndmask_b32_e32 v34, v34, v35, vcc
	v_rsq_f32_e32 v36, v34
	v_add_co_u32_e64 v34, s[6:7], s64, v146
	v_mul_f32_e32 v37, 0x45800000, v36
	v_cndmask_b32_e32 v36, v36, v37, vcc
	v_mul_f32_e32 v28, v28, v36
	v_mul_f32_e32 v24, v24, v36
	v_mul_f32_e32 v29, v29, v36
	v_mul_f32_e32 v25, v25, v36
	v_mul_f32_e32 v30, v30, v36
	v_mul_f32_e32 v26, v26, v36
	v_mul_f32_e32 v31, v31, v36
	v_mul_f32_e32 v27, v27, v36
	v_mul_f32_e32 v37, v20, v36
	v_mul_f32_e32 v38, v16, v36
	v_mul_f32_e32 v39, v21, v36
	v_mul_f32_e32 v40, v17, v36
	v_mul_f32_e32 v41, v22, v36
	v_mul_f32_e32 v42, v18, v36
	v_mul_f32_e32 v43, v23, v36
	v_mul_f32_e32 v36, v19, v36
	v_max_f32_e32 v16, 0, v28
	v_max_f32_e32 v18, 0, v24
	v_max_f32_e32 v17, 0, v29
	v_max_f32_e32 v19, 0, v25
	v_max_f32_e32 v20, 0, v30
	v_max_f32_e32 v22, 0, v26
	v_max_f32_e32 v21, 0, v31
	v_max_f32_e32 v23, 0, v27
	v_max_f32_e32 v24, 0, v37
	v_max_f32_e32 v26, 0, v38
	v_max_f32_e32 v25, 0, v39
	v_max_f32_e32 v27, 0, v40
	v_max_f32_e32 v28, 0, v41
	v_max_f32_e32 v30, 0, v42
	v_max_f32_e32 v29, 0, v43
	v_max_f32_e32 v31, 0, v36
	v_pk_mul_f32 v[16:17], v[16:17], v[16:17]
	v_pk_mul_f32 v[18:19], v[18:19], v[18:19]
	v_pk_mul_f32 v[20:21], v[20:21], v[20:21]
	v_pk_mul_f32 v[22:23], v[22:23], v[22:23]
	v_addc_co_u32_e64 v35, s[6:7], 0, v147, s[6:7]
	v_pk_mul_f32 v[24:25], v[24:25], v[24:25]
	v_pk_mul_f32 v[26:27], v[26:27], v[26:27]
	v_pk_mul_f32 v[28:29], v[28:29], v[28:29]
	v_pk_mul_f32 v[30:31], v[30:31], v[30:31]
	v_cvt_pk_bf16_f32 v16, v16, v17
	v_cvt_pk_bf16_f32 v17, v20, v21
	v_cvt_pk_bf16_f32 v18, v18, v19
	v_cvt_pk_bf16_f32 v19, v22, v23
	v_cvt_pk_bf16_f32 v20, v24, v25
	v_cvt_pk_bf16_f32 v21, v28, v29
	v_cvt_pk_bf16_f32 v22, v26, v27
	v_cvt_pk_bf16_f32 v23, v30, v31
	global_store_dwordx4 v[34:35], v[16:19], off
	global_store_dwordx4 v[32:33], v[20:23], off offset:256
	global_load_dword v18, v[144:145], off offset:704
	s_and_b64 vcc, exec, s[4:5]
	v_lshl_add_u64 v[16:17], v[146:147], 0, s[24:25]
	s_waitcnt vmcnt(0)
	v_fmamk_f32 v18, v18, 0x3a800000, v160
	v_mul_f32_e32 v19, 0x4b800000, v18
	v_cmp_gt_f32_e64 s[4:5], s61, v18
	s_nop 1
	v_cndmask_b32_e64 v18, v18, v19, s[4:5]
	v_rsq_f32_e32 v20, v18
	v_add_co_u32_e64 v18, s[6:7], s65, v146
	v_mul_f32_e32 v21, 0x45800000, v20
	v_cndmask_b32_e64 v20, v20, v21, s[4:5]
	v_mul_f32_e32 v12, v12, v20
	v_mul_f32_e32 v8, v8, v20
	v_mul_f32_e32 v13, v13, v20
	v_mul_f32_e32 v9, v9, v20
	v_mul_f32_e32 v14, v14, v20
	v_mul_f32_e32 v10, v10, v20
	v_mul_f32_e32 v15, v15, v20
	v_mul_f32_e32 v11, v11, v20
	v_mul_f32_e32 v21, v4, v20
	v_mul_f32_e32 v22, v0, v20
	v_mul_f32_e32 v23, v5, v20
	v_mul_f32_e32 v24, v1, v20
	v_mul_f32_e32 v25, v6, v20
	v_mul_f32_e32 v26, v2, v20
	v_mul_f32_e32 v27, v7, v20
	v_mul_f32_e32 v20, v3, v20
	v_max_f32_e32 v0, 0, v12
	v_max_f32_e32 v2, 0, v8
	v_max_f32_e32 v1, 0, v13
	v_max_f32_e32 v3, 0, v9
	v_max_f32_e32 v4, 0, v14
	v_max_f32_e32 v6, 0, v10
	v_max_f32_e32 v5, 0, v15
	v_max_f32_e32 v7, 0, v11
	v_max_f32_e32 v8, 0, v21
	v_max_f32_e32 v10, 0, v22
	v_max_f32_e32 v9, 0, v23
	v_max_f32_e32 v11, 0, v24
	v_max_f32_e32 v12, 0, v25
	v_max_f32_e32 v14, 0, v26
	v_max_f32_e32 v13, 0, v27
	v_max_f32_e32 v15, 0, v20
	v_pk_mul_f32 v[0:1], v[0:1], v[0:1]
	v_pk_mul_f32 v[2:3], v[2:3], v[2:3]
	v_pk_mul_f32 v[4:5], v[4:5], v[4:5]
	v_pk_mul_f32 v[6:7], v[6:7], v[6:7]
	v_addc_co_u32_e64 v19, s[6:7], 0, v147, s[6:7]
	v_pk_mul_f32 v[8:9], v[8:9], v[8:9]
	v_pk_mul_f32 v[10:11], v[10:11], v[10:11]
	v_pk_mul_f32 v[12:13], v[12:13], v[12:13]
	v_pk_mul_f32 v[14:15], v[14:15], v[14:15]
	v_cvt_pk_bf16_f32 v0, v0, v1
	v_cvt_pk_bf16_f32 v1, v4, v5
	v_cvt_pk_bf16_f32 v2, v2, v3
	v_cvt_pk_bf16_f32 v3, v6, v7
	v_cvt_pk_bf16_f32 v4, v8, v9
	v_cvt_pk_bf16_f32 v5, v12, v13
	v_cvt_pk_bf16_f32 v6, v10, v11
	v_cvt_pk_bf16_f32 v7, v14, v15
	global_store_dwordx4 v[18:19], v[0:3], off
	global_store_dwordx4 v[16:17], v[4:7], off offset:256
	s_cbranch_vccz .LBB0_694
	s_waitcnt vmcnt(0)
	s_cmpk_gt_u32 s33, 0xff
	s_cbranch_scc1 .LBB0_701
	s_barrier

.LBB0_722:
	s_or_b32 s52, s37, 1
	s_sub_i32 s53, s52, s57
	s_min_u32 s53, s52, s53
	s_cmp_lt_u32 s52, s57
	s_cselect_b32 s52, s45, s58
	s_cselect_b32 s67, s44, s59
	s_lshl_b32 s53, s53, 7
	v_add_u32_e32 v149, s65, v145
	s_add_u32 s53, s67, s53
	ds_read_b128 v[140:143], v149
	ds_read_b128 v[150:153], v149 offset:1024
	ds_read_b128 v[156:159], v149 offset:2048
	ds_read_b128 v[160:163], v149 offset:3072
	s_addc_u32 s67, s52, 0
	s_lshl_b32 s52, s37, 7
	s_add_u32 s52, s40, s52
	s_addc_u32 s68, s41, 0
	s_add_u32 s52, s52, 0x100
	s_addc_u32 s68, s68, 0
	s_and_b64 s[50:51], exec, s[50:51]
	s_cselect_b32 s51, s19, s68
	s_cselect_b32 s50, s21, s52
	s_add_u32 s52, s53, 0x80000
	s_addc_u32 s53, s67, 0
	v_lshl_add_u64 v[196:197], s[52:53], 0, v[128:129]
	s_add_i32 m0, s35, 0xc000
	ds_read_b128 v[164:167], v147
	ds_read_b128 v[168:171], v147 offset:1024
	ds_read_b128 v[172:175], v147 offset:2048
	ds_read_b128 v[176:179], v147 offset:3072
	ds_read_b128 v[180:183], v147 offset:4096
	ds_read_b128 v[184:187], v147 offset:5120
	ds_read_b128 v[188:191], v147 offset:6144
	ds_read_b128 v[192:195], v147 offset:7168
	global_load_lds_dwordx4 v[196:197], off
	s_add_i32 m0, s35, 0xe000
	v_lshl_add_u64 v[196:197], s[52:53], 0, v[132:133]
	global_load_lds_dwordx4 v[196:197], off
	s_waitcnt lgkmcnt(8)
	s_barrier
	s_waitcnt lgkmcnt(0)
	v_mfma_f32_16x16x32_bf16 v[124:127], v[140:143], v[164:167], v[124:127]
	v_mfma_f32_16x16x32_bf16 v[120:123], v[156:159], v[164:167], v[120:123]
	v_mfma_f32_16x16x32_bf16 v[108:111], v[140:143], v[172:175], v[108:111]
	v_mfma_f32_16x16x32_bf16 v[104:107], v[156:159], v[172:175], v[104:107]
	v_mfma_f32_16x16x32_bf16 v[92:95], v[140:143], v[180:183], v[92:95]
	v_mfma_f32_16x16x32_bf16 v[88:91], v[156:159], v[180:183], v[88:91]
	v_mfma_f32_16x16x32_bf16 v[76:79], v[140:143], v[188:191], v[76:79]
	v_mfma_f32_16x16x32_bf16 v[72:75], v[156:159], v[188:191], v[72:75]
	v_mfma_f32_16x16x32_bf16 v[124:127], v[150:153], v[168:171], v[124:127]
	v_mfma_f32_16x16x32_bf16 v[120:123], v[160:163], v[168:171], v[120:123]
	v_mfma_f32_16x16x32_bf16 v[108:111], v[150:153], v[176:179], v[108:111]
	v_mfma_f32_16x16x32_bf16 v[104:107], v[160:163], v[176:179], v[104:107]
	v_mfma_f32_16x16x32_bf16 v[92:95], v[150:153], v[184:187], v[92:95]
	v_mfma_f32_16x16x32_bf16 v[88:91], v[160:163], v[184:187], v[88:91]
	v_mfma_f32_16x16x32_bf16 v[76:79], v[150:153], v[192:195], v[76:79]
	v_mfma_f32_16x16x32_bf16 v[72:75], v[160:163], v[192:195], v[72:75]
	s_barrier
	s_add_i32 s52, s65, s34
	v_add_u32_e32 v149, s72, v145
	v_lshl_add_u64 v[212:213], s[50:51], 0, v[130:131]
	s_mov_b32 m0, s52
	ds_read_b128 v[196:199], v149
	ds_read_b128 v[200:203], v149 offset:1024
	ds_read_b128 v[204:207], v149 offset:2048
	ds_read_b128 v[208:211], v149 offset:3072
	global_load_lds_dwordx4 v[212:213], off
	s_add_i32 m0, s52, 0x2000
	v_lshl_add_u64 v[214:215], s[50:51], 0, v[134:135]
	global_load_lds_dwordx4 v[214:215], off
	s_barrier
	s_waitcnt lgkmcnt(0)
	v_mfma_f32_16x16x32_bf16 v[116:119], v[196:199], v[164:167], v[116:119]
	v_mfma_f32_16x16x32_bf16 v[112:115], v[204:207], v[164:167], v[112:115]
	v_mfma_f32_16x16x32_bf16 v[100:103], v[196:199], v[172:175], v[100:103]
	v_mfma_f32_16x16x32_bf16 v[96:99], v[204:207], v[172:175], v[96:99]
	v_mfma_f32_16x16x32_bf16 v[84:87], v[196:199], v[180:183], v[84:87]
	v_mfma_f32_16x16x32_bf16 v[80:83], v[204:207], v[180:183], v[80:83]
	v_mfma_f32_16x16x32_bf16 v[68:71], v[196:199], v[188:191], v[68:71]
	v_mfma_f32_16x16x32_bf16 v[64:67], v[204:207], v[188:191], v[64:67]
	v_mfma_f32_16x16x32_bf16 v[116:119], v[200:203], v[168:171], v[116:119]
	v_mfma_f32_16x16x32_bf16 v[112:115], v[208:211], v[168:171], v[112:115]
	v_mfma_f32_16x16x32_bf16 v[100:103], v[200:203], v[176:179], v[100:103]
	v_mfma_f32_16x16x32_bf16 v[96:99], v[208:211], v[176:179], v[96:99]
	v_mfma_f32_16x16x32_bf16 v[84:87], v[200:203], v[184:187], v[84:87]
	v_mfma_f32_16x16x32_bf16 v[80:83], v[208:211], v[184:187], v[80:83]
	v_mfma_f32_16x16x32_bf16 v[68:71], v[200:203], v[192:195], v[68:71]
	v_mfma_f32_16x16x32_bf16 v[64:67], v[208:211], v[192:195], v[64:67]
	s_mov_b32 m0, s35
	v_lshl_add_u64 v[216:217], s[48:49], 0, v[128:129]
	s_barrier
	ds_read_b128 v[164:167], v147 offset:16384
	ds_read_b128 v[168:171], v147 offset:17408
	ds_read_b128 v[172:175], v147 offset:18432
	ds_read_b128 v[176:179], v147 offset:19456
	ds_read_b128 v[180:183], v147 offset:20480
	ds_read_b128 v[184:187], v147 offset:21504
	ds_read_b128 v[188:191], v147 offset:22528
	ds_read_b128 v[192:195], v147 offset:23552
	global_load_lds_dwordx4 v[216:217], off
	s_mov_b32 m0, s39
	v_lshl_add_u64 v[218:219], s[48:49], 0, v[132:133]
	global_load_lds_dwordx4 v[218:219], off
	s_barrier
	s_waitcnt lgkmcnt(0)
	v_mfma_f32_16x16x32_bf16 v[60:63], v[140:143], v[164:167], v[60:63]
	v_mfma_f32_16x16x32_bf16 v[56:59], v[156:159], v[164:167], v[56:59]
	v_mfma_f32_16x16x32_bf16 v[44:47], v[140:143], v[172:175], v[44:47]
	v_mfma_f32_16x16x32_bf16 v[40:43], v[156:159], v[172:175], v[40:43]
	v_mfma_f32_16x16x32_bf16 v[28:31], v[140:143], v[180:183], v[28:31]
	v_mfma_f32_16x16x32_bf16 v[24:27], v[156:159], v[180:183], v[24:27]
	v_mfma_f32_16x16x32_bf16 v[12:15], v[140:143], v[188:191], v[12:15]
	v_mfma_f32_16x16x32_bf16 v[8:11], v[156:159], v[188:191], v[8:11]
	v_mfma_f32_16x16x32_bf16 v[60:63], v[150:153], v[168:171], v[60:63]
	v_mfma_f32_16x16x32_bf16 v[56:59], v[160:163], v[168:171], v[56:59]
	v_mfma_f32_16x16x32_bf16 v[44:47], v[150:153], v[176:179], v[44:47]
	v_mfma_f32_16x16x32_bf16 v[40:43], v[160:163], v[176:179], v[40:43]
	v_mfma_f32_16x16x32_bf16 v[28:31], v[150:153], v[184:187], v[28:31]
	v_mfma_f32_16x16x32_bf16 v[24:27], v[160:163], v[184:187], v[24:27]
	v_mfma_f32_16x16x32_bf16 v[12:15], v[150:153], v[192:195], v[12:15]
	v_mfma_f32_16x16x32_bf16 v[8:11], v[160:163], v[192:195], v[8:11]
	s_barrier
	s_add_u32 s52, s50, 0x100000
	s_addc_u32 s53, s51, 0
	s_add_i32 s67, s72, s34
	s_mov_b32 m0, s67
	v_lshl_add_u64 v[140:141], s[52:53], 0, v[130:131]
	global_load_lds_dwordx4 v[140:141], off
	s_add_i32 m0, s67, 0x2000
	v_lshl_add_u64 v[140:141], s[52:53], 0, v[134:135]
	global_load_lds_dwordx4 v[140:141], off
	s_waitcnt vmcnt(6)
	s_barrier
	v_mfma_f32_16x16x32_bf16 v[52:55], v[196:199], v[164:167], v[52:55]
	v_mfma_f32_16x16x32_bf16 v[48:51], v[204:207], v[164:167], v[48:51]
	v_mfma_f32_16x16x32_bf16 v[36:39], v[196:199], v[172:175], v[36:39]
	v_mfma_f32_16x16x32_bf16 v[32:35], v[204:207], v[172:175], v[32:35]
	v_mfma_f32_16x16x32_bf16 v[20:23], v[196:199], v[180:183], v[20:23]
	v_mfma_f32_16x16x32_bf16 v[16:19], v[204:207], v[180:183], v[16:19]
	v_mfma_f32_16x16x32_bf16 v[4:7], v[196:199], v[188:191], v[4:7]
	v_mfma_f32_16x16x32_bf16 v[0:3], v[204:207], v[188:191], v[0:3]
	v_mfma_f32_16x16x32_bf16 v[52:55], v[200:203], v[168:171], v[52:55]
	v_mfma_f32_16x16x32_bf16 v[48:51], v[208:211], v[168:171], v[48:51]
	v_mfma_f32_16x16x32_bf16 v[36:39], v[200:203], v[176:179], v[36:39]
	v_mfma_f32_16x16x32_bf16 v[32:35], v[208:211], v[176:179], v[32:35]
	v_mfma_f32_16x16x32_bf16 v[20:23], v[200:203], v[184:187], v[20:23]
	v_mfma_f32_16x16x32_bf16 v[16:19], v[208:211], v[184:187], v[16:19]
	v_mfma_f32_16x16x32_bf16 v[4:7], v[200:203], v[192:195], v[4:7]
	v_mfma_f32_16x16x32_bf16 v[0:3], v[208:211], v[192:195], v[0:3]
	s_add_i32 s52, 0, 0x18000
	v_add_u32_e32 v149, s52, v145
	s_barrier
	ds_read_b128 v[140:143], v149
	ds_read_b128 v[150:153], v149 offset:1024
	ds_read_b128 v[156:159], v149 offset:2048
	ds_read_b128 v[160:163], v149 offset:3072
	s_add_u32 s48, s48, 0x80000
	s_addc_u32 s49, s49, 0
	s_mov_b32 m0, s54
	v_lshl_add_u64 v[196:197], s[48:49], 0, v[128:129]
	ds_read_b128 v[164:167], v147 offset:32768
	ds_read_b128 v[168:171], v147 offset:33792
	ds_read_b128 v[172:175], v147 offset:34816
	ds_read_b128 v[176:179], v147 offset:35840
	ds_read_b128 v[180:183], v147 offset:36864
	ds_read_b128 v[184:187], v147 offset:37888
	ds_read_b128 v[188:191], v147 offset:38912
	ds_read_b128 v[192:195], v147 offset:39936
	global_load_lds_dwordx4 v[196:197], off
	s_mov_b32 m0, s55
	v_lshl_add_u64 v[196:197], s[48:49], 0, v[132:133]
	global_load_lds_dwordx4 v[196:197], off
	s_waitcnt lgkmcnt(8)
	s_barrier
	s_waitcnt lgkmcnt(0)
	v_mfma_f32_16x16x32_bf16 v[124:127], v[140:143], v[164:167], v[124:127]
	v_mfma_f32_16x16x32_bf16 v[120:123], v[156:159], v[164:167], v[120:123]
	v_mfma_f32_16x16x32_bf16 v[108:111], v[140:143], v[172:175], v[108:111]
	v_mfma_f32_16x16x32_bf16 v[104:107], v[156:159], v[172:175], v[104:107]
	v_mfma_f32_16x16x32_bf16 v[92:95], v[140:143], v[180:183], v[92:95]
	v_mfma_f32_16x16x32_bf16 v[88:91], v[156:159], v[180:183], v[88:91]
	v_mfma_f32_16x16x32_bf16 v[76:79], v[140:143], v[188:191], v[76:79]
	v_mfma_f32_16x16x32_bf16 v[72:75], v[156:159], v[188:191], v[72:75]
	v_mfma_f32_16x16x32_bf16 v[124:127], v[150:153], v[168:171], v[124:127]
	v_mfma_f32_16x16x32_bf16 v[120:123], v[160:163], v[168:171], v[120:123]
	v_mfma_f32_16x16x32_bf16 v[108:111], v[150:153], v[176:179], v[108:111]
	v_mfma_f32_16x16x32_bf16 v[104:107], v[160:163], v[176:179], v[104:107]
	v_mfma_f32_16x16x32_bf16 v[92:95], v[150:153], v[184:187], v[92:95]
	v_mfma_f32_16x16x32_bf16 v[88:91], v[160:163], v[184:187], v[88:91]
	v_mfma_f32_16x16x32_bf16 v[76:79], v[150:153], v[192:195], v[76:79]
	v_mfma_f32_16x16x32_bf16 v[72:75], v[160:163], v[192:195], v[72:75]
	s_barrier
	s_add_i32 s48, s52, s34
	v_add_u32_e32 v149, s97, v145
	v_lshl_add_u64 v[212:213], v[212:213], 0, s[16:17]
	s_mov_b32 m0, s48
	ds_read_b128 v[196:199], v149
	ds_read_b128 v[200:203], v149 offset:1024
	ds_read_b128 v[204:207], v149 offset:2048
	ds_read_b128 v[208:211], v149 offset:3072
	global_load_lds_dwordx4 v[212:213], off
	s_add_i32 m0, s48, 0x2000
	v_lshl_add_u64 v[212:213], v[214:215], 0, s[16:17]
	global_load_lds_dwordx4 v[212:213], off
	s_barrier
	s_waitcnt lgkmcnt(0)
	v_mfma_f32_16x16x32_bf16 v[116:119], v[196:199], v[164:167], v[116:119]
	v_mfma_f32_16x16x32_bf16 v[112:115], v[204:207], v[164:167], v[112:115]
	v_mfma_f32_16x16x32_bf16 v[100:103], v[196:199], v[172:175], v[100:103]
	v_mfma_f32_16x16x32_bf16 v[96:99], v[204:207], v[172:175], v[96:99]
	v_mfma_f32_16x16x32_bf16 v[84:87], v[196:199], v[180:183], v[84:87]
	v_mfma_f32_16x16x32_bf16 v[80:83], v[204:207], v[180:183], v[80:83]
	v_mfma_f32_16x16x32_bf16 v[68:71], v[196:199], v[188:191], v[68:71]
	v_mfma_f32_16x16x32_bf16 v[64:67], v[204:207], v[188:191], v[64:67]
	v_mfma_f32_16x16x32_bf16 v[116:119], v[200:203], v[168:171], v[116:119]
	v_mfma_f32_16x16x32_bf16 v[112:115], v[208:211], v[168:171], v[112:115]
	v_mfma_f32_16x16x32_bf16 v[100:103], v[200:203], v[176:179], v[100:103]
	v_mfma_f32_16x16x32_bf16 v[96:99], v[208:211], v[176:179], v[96:99]
	v_mfma_f32_16x16x32_bf16 v[84:87], v[200:203], v[184:187], v[84:87]
	v_mfma_f32_16x16x32_bf16 v[80:83], v[208:211], v[184:187], v[80:83]
	v_mfma_f32_16x16x32_bf16 v[68:71], v[200:203], v[192:195], v[68:71]
	v_mfma_f32_16x16x32_bf16 v[64:67], v[208:211], v[192:195], v[64:67]
	s_mov_b32 m0, s60
	v_lshl_add_u64 v[212:213], v[216:217], 0, s[16:17]
	s_barrier
	ds_read_b128 v[164:167], v147 offset:49152
	ds_read_b128 v[168:171], v147 offset:50176
	ds_read_b128 v[172:175], v147 offset:51200
	ds_read_b128 v[176:179], v147 offset:52224
	ds_read_b128 v[180:183], v147 offset:53248
	ds_read_b128 v[184:187], v147 offset:54272
	ds_read_b128 v[188:191], v147 offset:55296
	ds_read_b128 v[192:195], v147 offset:56320
	global_load_lds_dwordx4 v[212:213], off
	s_mov_b32 m0, s61
	v_lshl_add_u64 v[212:213], v[218:219], 0, s[16:17]
	global_load_lds_dwordx4 v[212:213], off
	s_barrier
	s_waitcnt lgkmcnt(0)
	v_mfma_f32_16x16x32_bf16 v[60:63], v[140:143], v[164:167], v[60:63]
	v_mfma_f32_16x16x32_bf16 v[56:59], v[156:159], v[164:167], v[56:59]
	v_mfma_f32_16x16x32_bf16 v[44:47], v[140:143], v[172:175], v[44:47]
	v_mfma_f32_16x16x32_bf16 v[40:43], v[156:159], v[172:175], v[40:43]
	v_mfma_f32_16x16x32_bf16 v[28:31], v[140:143], v[180:183], v[28:31]
	v_mfma_f32_16x16x32_bf16 v[24:27], v[156:159], v[180:183], v[24:27]
	v_mfma_f32_16x16x32_bf16 v[12:15], v[140:143], v[188:191], v[12:15]
	v_mfma_f32_16x16x32_bf16 v[8:11], v[156:159], v[188:191], v[8:11]
	v_mfma_f32_16x16x32_bf16 v[60:63], v[150:153], v[168:171], v[60:63]
	v_mfma_f32_16x16x32_bf16 v[56:59], v[160:163], v[168:171], v[56:59]
	v_mfma_f32_16x16x32_bf16 v[44:47], v[150:153], v[176:179], v[44:47]
	v_mfma_f32_16x16x32_bf16 v[40:43], v[160:163], v[176:179], v[40:43]
	v_mfma_f32_16x16x32_bf16 v[28:31], v[150:153], v[184:187], v[28:31]
	v_mfma_f32_16x16x32_bf16 v[24:27], v[160:163], v[184:187], v[24:27]
	v_mfma_f32_16x16x32_bf16 v[12:15], v[150:153], v[192:195], v[12:15]
	v_mfma_f32_16x16x32_bf16 v[8:11], v[160:163], v[192:195], v[8:11]
	s_barrier
	s_add_u32 s48, s50, 0x100080
	s_addc_u32 s49, s51, 0
	s_add_i32 s50, s97, s34
	s_mov_b32 m0, s50
	v_lshl_add_u64 v[140:141], s[48:49], 0, v[130:131]
	global_load_lds_dwordx4 v[140:141], off
	s_add_i32 m0, s50, 0x2000
	v_lshl_add_u64 v[140:141], s[48:49], 0, v[134:135]
	global_load_lds_dwordx4 v[140:141], off
	s_waitcnt vmcnt(6)
	s_barrier
	v_mfma_f32_16x16x32_bf16 v[52:55], v[196:199], v[164:167], v[52:55]
	v_mfma_f32_16x16x32_bf16 v[48:51], v[204:207], v[164:167], v[48:51]
	v_mfma_f32_16x16x32_bf16 v[36:39], v[196:199], v[172:175], v[36:39]
	v_mfma_f32_16x16x32_bf16 v[32:35], v[204:207], v[172:175], v[32:35]
	v_mfma_f32_16x16x32_bf16 v[20:23], v[196:199], v[180:183], v[20:23]
	v_mfma_f32_16x16x32_bf16 v[16:19], v[204:207], v[180:183], v[16:19]
	v_mfma_f32_16x16x32_bf16 v[4:7], v[196:199], v[188:191], v[4:7]
	v_mfma_f32_16x16x32_bf16 v[0:3], v[204:207], v[188:191], v[0:3]
	v_mfma_f32_16x16x32_bf16 v[52:55], v[200:203], v[168:171], v[52:55]
	v_mfma_f32_16x16x32_bf16 v[48:51], v[208:211], v[168:171], v[48:51]
	v_mfma_f32_16x16x32_bf16 v[36:39], v[200:203], v[176:179], v[36:39]
	v_mfma_f32_16x16x32_bf16 v[32:35], v[208:211], v[176:179], v[32:35]
	v_mfma_f32_16x16x32_bf16 v[20:23], v[200:203], v[184:187], v[20:23]
	v_mfma_f32_16x16x32_bf16 v[16:19], v[208:211], v[184:187], v[16:19]
	v_mfma_f32_16x16x32_bf16 v[4:7], v[200:203], v[192:195], v[4:7]
	v_mfma_f32_16x16x32_bf16 v[0:3], v[208:211], v[192:195], v[0:3]
	s_cmp_gt_u32 s37, 61
	s_mov_b32 s37, s66
	s_barrier
	s_cbranch_scc1 .LBB0_728
